# rebalanced LDS-DMA issue in all GEMM K-loops: moved the two As[b][0] pieces from SP2(t) (6 loads) to SP1(t+1) (now 4+4), SP2(t) wait vmcnt(6)
# baseline (speedup 1.0000x reference)
; #define PG8_STAGE(bufoff, gbase, voff) do { _Pragma("unroll") for (int _i = 0; _i < 2; ++_i) \
;         __builtin_amdgcn_global_load_lds((const unsigned*)((const char*)(gbase) + (voff)[_i]), (PG8_LAS unsigned*)(lds + (bufoff) + ldsw + _i * 8192), 16, 0, 0); } while (0)
; #define PG8_LDA(dst, b, h) do { _Pragma("unroll") for (int m = 0; m < 4; ++m) _Pragma("unroll") for (int k = 0; k < 2; ++k) dst[m][k] = *(const PG8_LAS bf16x8*)(lds + PG8_SA(b, h) + aoff + m * 2048 + k * 1024); } while (0)
; #define PG8_LDB(dst, b, h) do { _Pragma("unroll") for (int n = 0; n < 2; ++n) _Pragma("unroll") for (int k = 0; k < 2; ++k) dst[n][k] = *(const PG8_LAS bf16x8*)(lds + PG8_SB(b, h) + boff + n * 2048 + k * 1024); } while (0)
; #define PG8_MMA(ai, bj, At, Bt) do { __builtin_amdgcn_s_setprio(1); _Pragma("unroll") for (int m = 0; m < 4; ++m) _Pragma("unroll") for (int n = 0; n < 2; ++n) _Pragma("unroll") for (int k = 0; k < 2; ++k) \
;         acc[ai][bj][m][n] = __builtin_amdgcn_mfma_f32_16x16x32_bf16(Bt[n][k], At[m][k], acc[ai][bj][m][n], 0, 0, 0); __builtin_amdgcn_s_setprio(0); } while (0)
; #define PG8_WAIT_V(n) asm volatile("s_waitcnt vmcnt(" #n ")" ::: "memory")
; #define PG8_WAIT_L(n) asm volatile("s_waitcnt lgkmcnt(" #n ")" ::: "memory")
; template <class Epi, class Sched, bool ALIGN_EPI = false, bool SP2 = false>
; __device__ __forceinline__ void gemm_phase(PG8_LAS unsigned char* lds, const Gemm g, const Sched& S, const Epi& E) {
;     ...
;             const bool last = (t == nt - 2);
;             const char* a1 = cA + (size_t)(t + 1) * kstep;
;             const char* a2 = last ? nA : cA + (size_t)(t + 2) * kstep; const char* b2 = last ? nB : cB + (size_t)(t + 2) * kstep;
;             const char* a3 = a2 + kstep; const char* b3 = b2 + kstep;
;             if (last && has_next) S.a_ready(nxt);
;             if constexpr (SP2) {
;             PG8_LDB(B0, 0, 0); PG8_LDB(B1, 0, 1); PG8_SCHED; PG8_LDA(At, 0, 0); PG8_STAGE(PG8_SA(1, 1), a1 + hstep, voffA);
;             PG8_WAIT_V(8); PG8_WAIT_L(0); PG8_BAR; PG8_MMA(0, 0, At, B0); PG8_MMA(0, 1, At, B1); PG8_BAR; PG8_SCHED;
;             PG8_LDA(At, 0, 1); PG8_STAGE(PG8_SB(0, 0), b2, voffB); PG8_STAGE(PG8_SB(0, 1), b2 + hstep, voffB); PG8_STAGE(PG8_SA(0, 0), a2, voffA);
;             PG8_WAIT_V(8); PG8_WAIT_L(0); PG8_BAR; PG8_MMA(1, 0, At, B0); PG8_MMA(1, 1, At, B1); PG8_BAR; PG8_SCHED;
.LBB0_58:
	s_add_i32 s42, s8, 2
	s_add_u32 s43, s0, 0x80
	s_addc_u32 s9, s1, 0
	s_add_i32 s45, 0, 0x10000
	s_cmp_eq_u32 s28, s8
	s_cselect_b32 s9, s51, s9
	s_cselect_b32 s8, s50, s43
	v_add_u32_e32 v160, s45, v156
	s_cselect_b32 s49, s81, s11
	s_cselect_b32 s48, s80, s10
	s_add_i32 s43, 0, 0x14000
	ds_read_b128 v[152:155], v160
	ds_read_b128 v[176:179], v160 offset:1024
	ds_read_b128 v[180:183], v160 offset:2048
	ds_read_b128 v[192:195], v160 offset:3072
	v_add_u32_e32 v160, s43, v156
	ds_read_b128 v[196:199], v160
	ds_read_b128 v[200:203], v160 offset:1024
	ds_read_b128 v[204:207], v160 offset:2048
	ds_read_b128 v[208:211], v160 offset:3072
	v_lshl_add_u64 v[166:167], s[0:1], 0, v[148:149]
	s_add_i32 m0, s85, 0xc000
	ds_read_b128 v[212:215], v175
	ds_read_b128 v[216:219], v175 offset:1024
	ds_read_b128 v[220:223], v175 offset:2048
	ds_read_b128 v[224:227], v175 offset:3072
	ds_read_b128 v[228:231], v175 offset:4096
	ds_read_b128 v[232:235], v175 offset:5120
	ds_read_b128 v[236:239], v175 offset:6144
	ds_read_b128 v[240:243], v175 offset:7168
	global_load_lds_dwordx4 v[166:167], off
	v_lshl_add_u64 v[166:167], s[0:1], 0, v[150:151]
	s_add_i32 m0, s85, 0xe000
	s_nop 0
	global_load_lds_dwordx4 v[166:167], off
	s_waitcnt vmcnt(8)
	s_waitcnt lgkmcnt(0)
	s_barrier
	s_setprio 1
	s_waitcnt lgkmcnt(0)
	v_mfma_f32_16x16x32_bf16 v[126:129], v[152:155], v[212:215], v[126:129]
	v_mfma_f32_16x16x32_bf16 v[122:125], v[180:183], v[212:215], v[122:125]
	v_mfma_f32_16x16x32_bf16 v[110:113], v[152:155], v[220:223], v[110:113]
	v_mfma_f32_16x16x32_bf16 v[106:109], v[180:183], v[220:223], v[106:109]
	v_mfma_f32_16x16x32_bf16 v[94:97], v[152:155], v[228:231], v[94:97]
	v_mfma_f32_16x16x32_bf16 v[90:93], v[180:183], v[228:231], v[90:93]
	v_mfma_f32_16x16x32_bf16 v[78:81], v[152:155], v[236:239], v[78:81]
	v_mfma_f32_16x16x32_bf16 v[74:77], v[180:183], v[236:239], v[74:77]
	v_mfma_f32_16x16x32_bf16 v[126:129], v[176:179], v[216:219], v[126:129]
	v_mfma_f32_16x16x32_bf16 v[122:125], v[192:195], v[216:219], v[122:125]
	v_mfma_f32_16x16x32_bf16 v[110:113], v[176:179], v[224:227], v[110:113]
	v_mfma_f32_16x16x32_bf16 v[106:109], v[192:195], v[224:227], v[106:109]
	v_mfma_f32_16x16x32_bf16 v[94:97], v[176:179], v[232:235], v[94:97]
	v_mfma_f32_16x16x32_bf16 v[90:93], v[192:195], v[232:235], v[90:93]
	v_mfma_f32_16x16x32_bf16 v[78:81], v[176:179], v[240:243], v[78:81]
	v_mfma_f32_16x16x32_bf16 v[74:77], v[192:195], v[240:243], v[74:77]
	s_setprio 0
	s_setprio 1
	v_mfma_f32_16x16x32_bf16 v[118:121], v[196:199], v[212:215], v[118:121]
	v_mfma_f32_16x16x32_bf16 v[114:117], v[204:207], v[212:215], v[114:117]
	v_mfma_f32_16x16x32_bf16 v[102:105], v[196:199], v[220:223], v[102:105]
	v_mfma_f32_16x16x32_bf16 v[98:101], v[204:207], v[220:223], v[98:101]
	v_mfma_f32_16x16x32_bf16 v[86:89], v[196:199], v[228:231], v[86:89]
	v_mfma_f32_16x16x32_bf16 v[82:85], v[204:207], v[228:231], v[82:85]
	v_mfma_f32_16x16x32_bf16 v[70:73], v[196:199], v[236:239], v[70:73]
	v_mfma_f32_16x16x32_bf16 v[66:69], v[204:207], v[236:239], v[66:69]
	v_mfma_f32_16x16x32_bf16 v[118:121], v[200:203], v[216:219], v[118:121]
	v_mfma_f32_16x16x32_bf16 v[114:117], v[208:211], v[216:219], v[114:117]
	v_mfma_f32_16x16x32_bf16 v[102:105], v[200:203], v[224:227], v[102:105]
	v_mfma_f32_16x16x32_bf16 v[98:101], v[208:211], v[224:227], v[98:101]
	v_mfma_f32_16x16x32_bf16 v[86:89], v[200:203], v[232:235], v[86:89]
	v_mfma_f32_16x16x32_bf16 v[82:85], v[208:211], v[232:235], v[82:85]
	v_mfma_f32_16x16x32_bf16 v[70:73], v[200:203], v[240:243], v[70:73]
	v_mfma_f32_16x16x32_bf16 v[66:69], v[208:211], v[240:243], v[66:69]
	s_setprio 0
	s_barrier
	s_add_i32 s45, s45, s5
	v_lshl_add_u64 v[166:167], s[48:49], 0, v[132:133]
	s_mov_b32 m0, s45
	ds_read_b128 v[212:215], v175 offset:16384
	ds_read_b128 v[216:219], v175 offset:17408
	ds_read_b128 v[220:223], v175 offset:18432
	ds_read_b128 v[224:227], v175 offset:19456
	ds_read_b128 v[228:231], v175 offset:20480
	ds_read_b128 v[232:235], v175 offset:21504
	ds_read_b128 v[236:239], v175 offset:22528
	ds_read_b128 v[240:243], v175 offset:23552
	global_load_lds_dwordx4 v[166:167], off
	s_add_i32 m0, s45, 0x2000
	v_lshl_add_u64 v[184:185], s[48:49], 0, v[136:137]
	s_add_u32 s48, s48, s24
	s_addc_u32 s49, s49, s25
	s_add_i32 s43, s43, s5
	global_load_lds_dwordx4 v[184:185], off
	v_lshl_add_u64 v[244:245], s[48:49], 0, v[132:133]
	s_mov_b32 m0, s43
	v_lshl_add_u64 v[246:247], s[48:49], 0, v[136:137]
	global_load_lds_dwordx4 v[244:245], off
	s_add_i32 m0, s43, 0x2000
	v_lshl_add_u64 v[248:249], s[8:9], 0, v[130:131]
	global_load_lds_dwordx4 v[246:247], off
	v_lshl_add_u64 v[250:251], s[8:9], 0, v[134:135]
	s_nop 0
	s_waitcnt vmcnt(6)
	s_waitcnt lgkmcnt(0)
	s_barrier
; #define PG8_STAGE(bufoff, gbase, voff) do { _Pragma("unroll") for (int _i = 0; _i < 2; ++_i) \
;         __builtin_amdgcn_global_load_lds((const unsigned*)((const char*)(gbase) + (voff)[_i]), (PG8_LAS unsigned*)(lds + (bufoff) + ldsw + _i * 8192), 16, 0, 0); } while (0)
; #define PG8_LDA(dst, b, h) do { _Pragma("unroll") for (int m = 0; m < 4; ++m) _Pragma("unroll") for (int k = 0; k < 2; ++k) dst[m][k] = *(const PG8_LAS bf16x8*)(lds + PG8_SA(b, h) + aoff + m * 2048 + k * 1024); } while (0)
; #define PG8_LDB(dst, b, h) do { _Pragma("unroll") for (int n = 0; n < 2; ++n) _Pragma("unroll") for (int k = 0; k < 2; ++k) dst[n][k] = *(const PG8_LAS bf16x8*)(lds + PG8_SB(b, h) + boff + n * 2048 + k * 1024); } while (0)
; #define PG8_MMA(ai, bj, At, Bt) do { __builtin_amdgcn_s_setprio(1); _Pragma("unroll") for (int m = 0; m < 4; ++m) _Pragma("unroll") for (int n = 0; n < 2; ++n) _Pragma("unroll") for (int k = 0; k < 2; ++k) \
;         acc[ai][bj][m][n] = __builtin_amdgcn_mfma_f32_16x16x32_bf16(Bt[n][k], At[m][k], acc[ai][bj][m][n], 0, 0, 0); __builtin_amdgcn_s_setprio(0); } while (0)
; #define PG8_WAIT_V(n) asm volatile("s_waitcnt vmcnt(" #n ")" ::: "memory")
; #define PG8_WAIT_L(n) asm volatile("s_waitcnt lgkmcnt(" #n ")" ::: "memory")
; #define PG8_BAR __builtin_amdgcn_s_barrier()
; #define PG8_SCHED __builtin_amdgcn_sched_barrier(0)
; template <class Epi, class Sched, bool ALIGN_EPI = false, bool SP2 = false>
; __device__ __forceinline__ void gemm_phase(PG8_LAS unsigned char* lds, const Gemm g, const Sched& S, const Epi& E) {
;     ...
;             PG8_WAIT_V(8); PG8_WAIT_L(0); PG8_BAR; PG8_MMA(1, 0, At, B0); PG8_MMA(1, 1, At, B1); PG8_BAR; PG8_SCHED;
;             PG8_LDB(B0, 1, 0); PG8_LDB(B1, 1, 1); PG8_SCHED; PG8_LDA(At, 1, 0); PG8_STAGE(PG8_SA(0, 1), a2 + hstep, voffA);
;             PG8_WAIT_V(8); PG8_WAIT_L(0); PG8_BAR; PG8_MMA(0, 0, At, B0); PG8_MMA(0, 1, At, B1); PG8_BAR; PG8_SCHED;
	s_setprio 1
	s_waitcnt lgkmcnt(0)
	v_mfma_f32_16x16x32_bf16 v[62:65], v[152:155], v[212:215], v[62:65]
	v_mfma_f32_16x16x32_bf16 v[58:61], v[180:183], v[212:215], v[58:61]
	v_mfma_f32_16x16x32_bf16 v[46:49], v[152:155], v[220:223], v[46:49]
	v_mfma_f32_16x16x32_bf16 v[42:45], v[180:183], v[220:223], v[42:45]
	v_mfma_f32_16x16x32_bf16 v[30:33], v[152:155], v[228:231], v[30:33]
	v_mfma_f32_16x16x32_bf16 v[26:29], v[180:183], v[228:231], v[26:29]
	v_mfma_f32_16x16x32_bf16 v[14:17], v[152:155], v[236:239], v[14:17]
	v_mfma_f32_16x16x32_bf16 v[10:13], v[180:183], v[236:239], v[10:13]
	v_mfma_f32_16x16x32_bf16 v[62:65], v[176:179], v[216:219], v[62:65]
	v_mfma_f32_16x16x32_bf16 v[58:61], v[192:195], v[216:219], v[58:61]
	v_mfma_f32_16x16x32_bf16 v[46:49], v[176:179], v[224:227], v[46:49]
	v_mfma_f32_16x16x32_bf16 v[42:45], v[192:195], v[224:227], v[42:45]
	v_mfma_f32_16x16x32_bf16 v[30:33], v[176:179], v[232:235], v[30:33]
	v_mfma_f32_16x16x32_bf16 v[26:29], v[192:195], v[232:235], v[26:29]
	v_mfma_f32_16x16x32_bf16 v[14:17], v[176:179], v[240:243], v[14:17]
	v_mfma_f32_16x16x32_bf16 v[10:13], v[192:195], v[240:243], v[10:13]
	s_setprio 0
	s_setprio 1
	v_mfma_f32_16x16x32_bf16 v[54:57], v[196:199], v[212:215], v[54:57]
	v_mfma_f32_16x16x32_bf16 v[50:53], v[204:207], v[212:215], v[50:53]
	v_mfma_f32_16x16x32_bf16 v[38:41], v[196:199], v[220:223], v[38:41]
	v_mfma_f32_16x16x32_bf16 v[34:37], v[204:207], v[220:223], v[34:37]
	v_mfma_f32_16x16x32_bf16 v[22:25], v[196:199], v[228:231], v[22:25]
	v_mfma_f32_16x16x32_bf16 v[18:21], v[204:207], v[228:231], v[18:21]
	v_mfma_f32_16x16x32_bf16 v[6:9], v[196:199], v[236:239], v[6:9]
	v_mfma_f32_16x16x32_bf16 v[2:5], v[204:207], v[236:239], v[2:5]
	v_mfma_f32_16x16x32_bf16 v[54:57], v[200:203], v[216:219], v[54:57]
	v_mfma_f32_16x16x32_bf16 v[50:53], v[208:211], v[216:219], v[50:53]
	v_mfma_f32_16x16x32_bf16 v[38:41], v[200:203], v[224:227], v[38:41]
	v_mfma_f32_16x16x32_bf16 v[34:37], v[208:211], v[224:227], v[34:37]
	v_mfma_f32_16x16x32_bf16 v[22:25], v[200:203], v[232:235], v[22:25]
	v_mfma_f32_16x16x32_bf16 v[18:21], v[208:211], v[232:235], v[18:21]
	v_mfma_f32_16x16x32_bf16 v[6:9], v[200:203], v[240:243], v[6:9]
	v_mfma_f32_16x16x32_bf16 v[2:5], v[208:211], v[240:243], v[2:5]
	s_setprio 0
	s_barrier
	s_add_i32 s43, 0, 0x18000
	v_add_u32_e32 v160, s43, v156
	s_add_i32 s45, 0, 0x1c000
	ds_read_b128 v[152:155], v160
	ds_read_b128 v[176:179], v160 offset:1024
	ds_read_b128 v[180:183], v160 offset:2048
	ds_read_b128 v[192:195], v160 offset:3072
	v_add_u32_e32 v160, s45, v156
	ds_read_b128 v[196:199], v160
	ds_read_b128 v[200:203], v160 offset:1024
	ds_read_b128 v[204:207], v160 offset:2048
	ds_read_b128 v[208:211], v160 offset:3072
	s_add_u32 s8, s8, s24
	s_addc_u32 s9, s9, s25
	s_mov_b32 m0, s85
	s_nop 0
	global_load_lds_dwordx4 v[248:249], off
	s_mov_b32 m0, s94
	s_nop 0
	global_load_lds_dwordx4 v[250:251], off
	s_mov_b32 m0, s95
	v_lshl_add_u64 v[252:253], s[8:9], 0, v[130:131]
	ds_read_b128 v[212:215], v175 offset:32768
	ds_read_b128 v[216:219], v175 offset:33792
	ds_read_b128 v[220:223], v175 offset:34816
	ds_read_b128 v[224:227], v175 offset:35840
	ds_read_b128 v[228:231], v175 offset:36864
	ds_read_b128 v[232:235], v175 offset:37888
	ds_read_b128 v[236:239], v175 offset:38912
	ds_read_b128 v[240:243], v175 offset:39936
	global_load_lds_dwordx4 v[252:253], off
	v_lshl_add_u64 v[252:253], s[8:9], 0, v[134:135]
	s_mov_b32 m0, s96
	s_nop 0
	global_load_lds_dwordx4 v[252:253], off
	s_waitcnt vmcnt(8)
	s_waitcnt lgkmcnt(0)
	s_barrier
	s_setprio 1
	s_waitcnt lgkmcnt(0)
	v_mfma_f32_16x16x32_bf16 v[126:129], v[152:155], v[212:215], v[126:129]
	v_mfma_f32_16x16x32_bf16 v[122:125], v[180:183], v[212:215], v[122:125]
	v_mfma_f32_16x16x32_bf16 v[110:113], v[152:155], v[220:223], v[110:113]
	v_mfma_f32_16x16x32_bf16 v[106:109], v[180:183], v[220:223], v[106:109]
	v_mfma_f32_16x16x32_bf16 v[94:97], v[152:155], v[228:231], v[94:97]
	v_mfma_f32_16x16x32_bf16 v[90:93], v[180:183], v[228:231], v[90:93]
	v_mfma_f32_16x16x32_bf16 v[78:81], v[152:155], v[236:239], v[78:81]
	v_mfma_f32_16x16x32_bf16 v[74:77], v[180:183], v[236:239], v[74:77]
	v_mfma_f32_16x16x32_bf16 v[126:129], v[176:179], v[216:219], v[126:129]
	v_mfma_f32_16x16x32_bf16 v[122:125], v[192:195], v[216:219], v[122:125]
	v_mfma_f32_16x16x32_bf16 v[110:113], v[176:179], v[224:227], v[110:113]
	v_mfma_f32_16x16x32_bf16 v[106:109], v[192:195], v[224:227], v[106:109]
	v_mfma_f32_16x16x32_bf16 v[94:97], v[176:179], v[232:235], v[94:97]
	v_mfma_f32_16x16x32_bf16 v[90:93], v[192:195], v[232:235], v[90:93]
	v_mfma_f32_16x16x32_bf16 v[78:81], v[176:179], v[240:243], v[78:81]
	v_mfma_f32_16x16x32_bf16 v[74:77], v[192:195], v[240:243], v[74:77]
	s_setprio 0
	s_setprio 1
	v_mfma_f32_16x16x32_bf16 v[118:121], v[196:199], v[212:215], v[118:121]
	v_mfma_f32_16x16x32_bf16 v[114:117], v[204:207], v[212:215], v[114:117]
	v_mfma_f32_16x16x32_bf16 v[102:105], v[196:199], v[220:223], v[102:105]
	v_mfma_f32_16x16x32_bf16 v[98:101], v[204:207], v[220:223], v[98:101]
	v_mfma_f32_16x16x32_bf16 v[86:89], v[196:199], v[228:231], v[86:89]
	v_mfma_f32_16x16x32_bf16 v[82:85], v[204:207], v[228:231], v[82:85]
	v_mfma_f32_16x16x32_bf16 v[70:73], v[196:199], v[236:239], v[70:73]
	v_mfma_f32_16x16x32_bf16 v[66:69], v[204:207], v[236:239], v[66:69]
	v_mfma_f32_16x16x32_bf16 v[118:121], v[200:203], v[216:219], v[118:121]
	v_mfma_f32_16x16x32_bf16 v[114:117], v[208:211], v[216:219], v[114:117]
	v_mfma_f32_16x16x32_bf16 v[102:105], v[200:203], v[224:227], v[102:105]
	v_mfma_f32_16x16x32_bf16 v[98:101], v[208:211], v[224:227], v[98:101]
	v_mfma_f32_16x16x32_bf16 v[86:89], v[200:203], v[232:235], v[86:89]
	v_mfma_f32_16x16x32_bf16 v[82:85], v[208:211], v[232:235], v[82:85]
	v_mfma_f32_16x16x32_bf16 v[70:73], v[200:203], v[240:243], v[70:73]
	v_mfma_f32_16x16x32_bf16 v[66:69], v[208:211], v[240:243], v[66:69]
	s_setprio 0
	s_barrier
; #define PG8_STAGE(bufoff, gbase, voff) do { _Pragma("unroll") for (int _i = 0; _i < 2; ++_i) \
;         __builtin_amdgcn_global_load_lds((const unsigned*)((const char*)(gbase) + (voff)[_i]), (PG8_LAS unsigned*)(lds + (bufoff) + ldsw + _i * 8192), 16, 0, 0); } while (0)
; #define PG8_LDA(dst, b, h) do { _Pragma("unroll") for (int m = 0; m < 4; ++m) _Pragma("unroll") for (int k = 0; k < 2; ++k) dst[m][k] = *(const PG8_LAS bf16x8*)(lds + PG8_SA(b, h) + aoff + m * 2048 + k * 1024); } while (0)
; #define PG8_MMA(ai, bj, At, Bt) do { __builtin_amdgcn_s_setprio(1); _Pragma("unroll") for (int m = 0; m < 4; ++m) _Pragma("unroll") for (int n = 0; n < 2; ++n) _Pragma("unroll") for (int k = 0; k < 2; ++k) \
;         acc[ai][bj][m][n] = __builtin_amdgcn_mfma_f32_16x16x32_bf16(Bt[n][k], At[m][k], acc[ai][bj][m][n], 0, 0, 0); __builtin_amdgcn_s_setprio(0); } while (0)
; #define PG8_WAIT_V(n) asm volatile("s_waitcnt vmcnt(" #n ")" ::: "memory")
; #define PG8_WAIT_L(n) asm volatile("s_waitcnt lgkmcnt(" #n ")" ::: "memory")
; #define PG8_BAR __builtin_amdgcn_s_barrier()
; #define PG8_SCHED __builtin_amdgcn_sched_barrier(0)
; template <class Epi, class Sched, bool ALIGN_EPI = false, bool SP2 = false>
; __device__ __forceinline__ void gemm_phase(PG8_LAS unsigned char* lds, const Gemm g, const Sched& S, const Epi& E) {
;     ...
;         for (int t = 0; t < nt; t += 2) {
;     ...
;             PG8_LDA(At, 1, 1); PG8_STAGE(PG8_SB(1, 0), b3, voffB); PG8_STAGE(PG8_SB(1, 1), b3 + hstep, voffB); PG8_STAGE(PG8_SA(1, 0), a3, voffA);
;             PG8_WAIT_V(8); PG8_WAIT_L(0); PG8_BAR; PG8_MMA(1, 0, At, B0); PG8_MMA(1, 1, At, B1); PG8_BAR; PG8_SCHED;
	s_add_i32 s8, s43, s5
	v_lshl_add_u64 v[166:167], v[166:167], 0, s[88:89]
	s_mov_b32 m0, s8
	ds_read_b128 v[212:215], v175 offset:49152
	ds_read_b128 v[216:219], v175 offset:50176
	ds_read_b128 v[220:223], v175 offset:51200
	ds_read_b128 v[224:227], v175 offset:52224
	ds_read_b128 v[228:231], v175 offset:53248
	ds_read_b128 v[232:235], v175 offset:54272
	ds_read_b128 v[236:239], v175 offset:55296
	ds_read_b128 v[240:243], v175 offset:56320
	global_load_lds_dwordx4 v[166:167], off
	v_lshl_add_u64 v[166:167], v[184:185], 0, s[88:89]
	s_add_i32 m0, s8, 0x2000
	s_add_i32 s8, s45, s5
	global_load_lds_dwordx4 v[166:167], off
	v_lshl_add_u64 v[166:167], v[244:245], 0, s[88:89]
	s_mov_b32 m0, s8
	s_nop 0
	global_load_lds_dwordx4 v[166:167], off
	v_lshl_add_u64 v[166:167], v[246:247], 0, s[88:89]
	s_add_i32 m0, s8, 0x2000
	s_nop 0
	global_load_lds_dwordx4 v[166:167], off
	v_lshl_add_u64 v[166:167], v[248:249], 0, s[88:89]
	s_mov_b32 m0, s97
	s_nop 0
	global_load_lds_dwordx4 v[166:167], off
	v_lshl_add_u64 v[166:167], v[250:251], 0, s[88:89]
	s_mov_b32 m0, s22
	s_nop 0
	global_load_lds_dwordx4 v[166:167], off
	s_waitcnt vmcnt(8)
	s_waitcnt lgkmcnt(0)
	s_barrier
	s_setprio 1
	s_waitcnt lgkmcnt(0)
	v_mfma_f32_16x16x32_bf16 v[62:65], v[152:155], v[212:215], v[62:65]
	v_mfma_f32_16x16x32_bf16 v[58:61], v[180:183], v[212:215], v[58:61]
	v_mfma_f32_16x16x32_bf16 v[46:49], v[152:155], v[220:223], v[46:49]
	v_mfma_f32_16x16x32_bf16 v[42:45], v[180:183], v[220:223], v[42:45]
	v_mfma_f32_16x16x32_bf16 v[30:33], v[152:155], v[228:231], v[30:33]
	v_mfma_f32_16x16x32_bf16 v[26:29], v[180:183], v[228:231], v[26:29]
	v_mfma_f32_16x16x32_bf16 v[14:17], v[152:155], v[236:239], v[14:17]
	v_mfma_f32_16x16x32_bf16 v[10:13], v[180:183], v[236:239], v[10:13]
	v_mfma_f32_16x16x32_bf16 v[62:65], v[176:179], v[216:219], v[62:65]
	v_mfma_f32_16x16x32_bf16 v[58:61], v[192:195], v[216:219], v[58:61]
	v_mfma_f32_16x16x32_bf16 v[46:49], v[176:179], v[224:227], v[46:49]
	v_mfma_f32_16x16x32_bf16 v[42:45], v[192:195], v[224:227], v[42:45]
	v_mfma_f32_16x16x32_bf16 v[30:33], v[176:179], v[232:235], v[30:33]
	v_mfma_f32_16x16x32_bf16 v[26:29], v[192:195], v[232:235], v[26:29]
	v_mfma_f32_16x16x32_bf16 v[14:17], v[176:179], v[240:243], v[14:17]
	v_mfma_f32_16x16x32_bf16 v[10:13], v[192:195], v[240:243], v[10:13]
	s_setprio 0
	s_setprio 1
	v_mfma_f32_16x16x32_bf16 v[54:57], v[196:199], v[212:215], v[54:57]
	v_mfma_f32_16x16x32_bf16 v[50:53], v[204:207], v[212:215], v[50:53]
	v_mfma_f32_16x16x32_bf16 v[38:41], v[196:199], v[220:223], v[38:41]
	v_mfma_f32_16x16x32_bf16 v[34:37], v[204:207], v[220:223], v[34:37]
	v_mfma_f32_16x16x32_bf16 v[22:25], v[196:199], v[228:231], v[22:25]
	v_mfma_f32_16x16x32_bf16 v[18:21], v[204:207], v[228:231], v[18:21]
	v_mfma_f32_16x16x32_bf16 v[6:9], v[196:199], v[236:239], v[6:9]
	v_mfma_f32_16x16x32_bf16 v[2:5], v[204:207], v[236:239], v[2:5]
	v_mfma_f32_16x16x32_bf16 v[54:57], v[200:203], v[216:219], v[54:57]
	v_mfma_f32_16x16x32_bf16 v[50:53], v[208:211], v[216:219], v[50:53]
	v_mfma_f32_16x16x32_bf16 v[38:41], v[200:203], v[224:227], v[38:41]
	v_mfma_f32_16x16x32_bf16 v[34:37], v[208:211], v[224:227], v[34:37]
	v_mfma_f32_16x16x32_bf16 v[22:25], v[200:203], v[232:235], v[22:25]
	v_mfma_f32_16x16x32_bf16 v[18:21], v[208:211], v[232:235], v[18:21]
	v_mfma_f32_16x16x32_bf16 v[6:9], v[200:203], v[240:243], v[6:9]
	v_mfma_f32_16x16x32_bf16 v[2:5], v[208:211], v[240:243], v[2:5]
	s_setprio 0
	s_barrier
	s_add_u32 s0, s0, 0x100
	s_addc_u32 s1, s1, 0
	s_add_u32 s10, s10, 0x100
	s_addc_u32 s11, s11, 0
	s_cmp_ge_i32 s42, s13
	s_mov_b32 s8, s42
	s_cbranch_scc0 .LBB0_58

; #define PG8_STAGE(bufoff, gbase, voff) do { _Pragma("unroll") for (int _i = 0; _i < 2; ++_i) \
;         __builtin_amdgcn_global_load_lds((const unsigned*)((const char*)(gbase) + (voff)[_i]), (PG8_LAS unsigned*)(lds + (bufoff) + ldsw + _i * 8192), 16, 0, 0); } while (0)
; #define PG8_LDA(dst, b, h) do { _Pragma("unroll") for (int m = 0; m < 4; ++m) _Pragma("unroll") for (int k = 0; k < 2; ++k) dst[m][k] = *(const PG8_LAS bf16x8*)(lds + PG8_SA(b, h) + aoff + m * 2048 + k * 1024); } while (0)
; #define PG8_LDB(dst, b, h) do { _Pragma("unroll") for (int n = 0; n < 2; ++n) _Pragma("unroll") for (int k = 0; k < 2; ++k) dst[n][k] = *(const PG8_LAS bf16x8*)(lds + PG8_SB(b, h) + boff + n * 2048 + k * 1024); } while (0)
; #define PG8_MMA(ai, bj, At, Bt) do { __builtin_amdgcn_s_setprio(1); _Pragma("unroll") for (int m = 0; m < 4; ++m) _Pragma("unroll") for (int n = 0; n < 2; ++n) _Pragma("unroll") for (int k = 0; k < 2; ++k) \
;         acc[ai][bj][m][n] = __builtin_amdgcn_mfma_f32_16x16x32_bf16(Bt[n][k], At[m][k], acc[ai][bj][m][n], 0, 0, 0); __builtin_amdgcn_s_setprio(0); } while (0)
; #define PG8_WAIT_V(n) asm volatile("s_waitcnt vmcnt(" #n ")" ::: "memory")
; #define PG8_WAIT_L(n) asm volatile("s_waitcnt lgkmcnt(" #n ")" ::: "memory")
; template <class Epi, class Sched, bool ALIGN_EPI = false, bool SP2 = false>
; __device__ __forceinline__ void gemm_phase(PG8_LAS unsigned char* lds, const Gemm g, const Sched& S, const Epi& E) {
;     ...
;             const bool last = (t == nt - 2);
;             const char* a1 = cA + (size_t)(t + 1) * kstep;
;             const char* a2 = last ? nA : cA + (size_t)(t + 2) * kstep; const char* b2 = last ? nB : cB + (size_t)(t + 2) * kstep;
;             const char* a3 = a2 + kstep; const char* b3 = b2 + kstep;
;             if (last && has_next) S.a_ready(nxt);
;             if constexpr (SP2) {
;             PG8_LDB(B0, 0, 0); PG8_LDB(B1, 0, 1); PG8_SCHED; PG8_LDA(At, 0, 0); PG8_STAGE(PG8_SA(1, 1), a1 + hstep, voffA);
;             PG8_WAIT_V(8); PG8_WAIT_L(0); PG8_BAR; PG8_MMA(0, 0, At, B0); PG8_MMA(0, 1, At, B1); PG8_BAR; PG8_SCHED;
;             PG8_LDA(At, 0, 1); PG8_STAGE(PG8_SB(0, 0), b2, voffB); PG8_STAGE(PG8_SB(0, 1), b2 + hstep, voffB); PG8_STAGE(PG8_SA(0, 0), a2, voffA);
;             PG8_WAIT_V(8); PG8_WAIT_L(0); PG8_BAR; PG8_MMA(1, 0, At, B0); PG8_MMA(1, 1, At, B1); PG8_BAR; PG8_SCHED;
.LBB0_251:
	s_add_i32 s84, s10, 2
	s_add_u32 s85, s8, 0x80
	s_addc_u32 s11, s9, 0
	s_add_i32 s92, 0, 0x10000
	s_cmp_eq_u32 s53, s10
	s_cselect_b32 s11, s1, s11
	s_cselect_b32 s10, s0, s85
	v_add_u32_e32 v144, s92, v147
	s_cselect_b32 s87, s37, s83
	s_cselect_b32 s86, s36, s81
	s_add_i32 s85, 0, 0x14000
	ds_read_b128 v[140:143], v144
	s_waitcnt vmcnt(0)
	ds_read_b128 v[150:153], v144 offset:1024
	ds_read_b128 v[154:157], v144 offset:2048
	ds_read_b128 v[168:171], v144 offset:3072
	v_add_u32_e32 v144, s85, v147
	ds_read_b128 v[172:175], v144
	ds_read_b128 v[176:179], v144 offset:1024
	ds_read_b128 v[180:183], v144 offset:2048
	ds_read_b128 v[192:195], v144 offset:3072
	v_lshl_add_u64 v[144:145], s[8:9], 0, v[136:137]
	s_add_i32 m0, s44, 0xc000
	ds_read_b128 v[196:199], v149
	ds_read_b128 v[200:203], v149 offset:1024
	ds_read_b128 v[204:207], v149 offset:2048
	ds_read_b128 v[208:211], v149 offset:3072
	ds_read_b128 v[212:215], v149 offset:4096
	ds_read_b128 v[216:219], v149 offset:5120
	ds_read_b128 v[220:223], v149 offset:6144
	ds_read_b128 v[224:227], v149 offset:7168
	global_load_lds_dwordx4 v[144:145], off
	v_lshl_add_u64 v[144:145], s[8:9], 0, v[138:139]
	s_add_i32 m0, s44, 0xe000
	s_nop 0
	global_load_lds_dwordx4 v[144:145], off
	s_waitcnt vmcnt(8)
	s_waitcnt lgkmcnt(0)
	s_barrier
	s_setprio 1
	s_waitcnt lgkmcnt(0)
	v_mfma_f32_16x16x32_bf16 v[122:125], v[140:143], v[196:199], v[122:125]
	v_mfma_f32_16x16x32_bf16 v[126:129], v[154:157], v[196:199], v[126:129]
	v_mfma_f32_16x16x32_bf16 v[110:113], v[140:143], v[204:207], v[110:113]
	v_mfma_f32_16x16x32_bf16 v[106:109], v[154:157], v[204:207], v[106:109]
	v_mfma_f32_16x16x32_bf16 v[94:97], v[140:143], v[212:215], v[94:97]
	v_mfma_f32_16x16x32_bf16 v[90:93], v[154:157], v[212:215], v[90:93]
	v_mfma_f32_16x16x32_bf16 v[78:81], v[140:143], v[220:223], v[78:81]
	v_mfma_f32_16x16x32_bf16 v[74:77], v[154:157], v[220:223], v[74:77]
	v_mfma_f32_16x16x32_bf16 v[122:125], v[150:153], v[200:203], v[122:125]
	v_mfma_f32_16x16x32_bf16 v[126:129], v[168:171], v[200:203], v[126:129]
	v_mfma_f32_16x16x32_bf16 v[110:113], v[150:153], v[208:211], v[110:113]
	v_mfma_f32_16x16x32_bf16 v[106:109], v[168:171], v[208:211], v[106:109]
	v_mfma_f32_16x16x32_bf16 v[94:97], v[150:153], v[216:219], v[94:97]
	v_mfma_f32_16x16x32_bf16 v[90:93], v[168:171], v[216:219], v[90:93]
	v_mfma_f32_16x16x32_bf16 v[78:81], v[150:153], v[224:227], v[78:81]
	v_mfma_f32_16x16x32_bf16 v[74:77], v[168:171], v[224:227], v[74:77]
	s_setprio 0
	s_setprio 1
	v_mfma_f32_16x16x32_bf16 v[118:121], v[172:175], v[196:199], v[118:121]
	v_mfma_f32_16x16x32_bf16 v[114:117], v[180:183], v[196:199], v[114:117]
	v_mfma_f32_16x16x32_bf16 v[102:105], v[172:175], v[204:207], v[102:105]
	v_mfma_f32_16x16x32_bf16 v[98:101], v[180:183], v[204:207], v[98:101]
	v_mfma_f32_16x16x32_bf16 v[86:89], v[172:175], v[212:215], v[86:89]
	v_mfma_f32_16x16x32_bf16 v[82:85], v[180:183], v[212:215], v[82:85]
	v_mfma_f32_16x16x32_bf16 v[70:73], v[172:175], v[220:223], v[70:73]
	v_mfma_f32_16x16x32_bf16 v[66:69], v[180:183], v[220:223], v[66:69]
	v_mfma_f32_16x16x32_bf16 v[118:121], v[176:179], v[200:203], v[118:121]
	v_mfma_f32_16x16x32_bf16 v[114:117], v[192:195], v[200:203], v[114:117]
	v_mfma_f32_16x16x32_bf16 v[102:105], v[176:179], v[208:211], v[102:105]
	v_mfma_f32_16x16x32_bf16 v[98:101], v[192:195], v[208:211], v[98:101]
	v_mfma_f32_16x16x32_bf16 v[86:89], v[176:179], v[216:219], v[86:89]
	v_mfma_f32_16x16x32_bf16 v[82:85], v[192:195], v[216:219], v[82:85]
	v_mfma_f32_16x16x32_bf16 v[70:73], v[176:179], v[224:227], v[70:73]
	v_mfma_f32_16x16x32_bf16 v[66:69], v[192:195], v[224:227], v[66:69]
	s_setprio 0
	s_barrier
	s_add_i32 s92, s92, s43
	v_lshl_add_u64 v[144:145], s[86:87], 0, v[160:161]
	s_mov_b32 m0, s92
	ds_read_b128 v[196:199], v149 offset:16384
	ds_read_b128 v[200:203], v149 offset:17408
	ds_read_b128 v[204:207], v149 offset:18432
	ds_read_b128 v[208:211], v149 offset:19456
	ds_read_b128 v[212:215], v149 offset:20480
	ds_read_b128 v[216:219], v149 offset:21504
	ds_read_b128 v[220:223], v149 offset:22528
	ds_read_b128 v[224:227], v149 offset:23552
	global_load_lds_dwordx4 v[144:145], off
	s_add_i32 m0, s92, 0x2000
	v_lshl_add_u64 v[158:159], s[86:87], 0, v[134:135]
	s_add_u32 s86, s86, s14
	s_addc_u32 s87, s87, s15
	s_add_i32 s85, s85, s43
	global_load_lds_dwordx4 v[158:159], off
	v_lshl_add_u64 v[166:167], s[86:87], 0, v[160:161]
	s_mov_b32 m0, s85
	v_lshl_add_u64 v[184:185], s[86:87], 0, v[134:135]
	global_load_lds_dwordx4 v[166:167], off
	s_add_i32 m0, s85, 0x2000
	v_lshl_add_u64 v[228:229], s[10:11], 0, v[130:131]
	global_load_lds_dwordx4 v[184:185], off
	v_lshl_add_u64 v[230:231], s[10:11], 0, v[132:133]
	s_nop 0
	s_waitcnt vmcnt(6)
	s_waitcnt lgkmcnt(0)
	s_barrier
; #define PG8_STAGE(bufoff, gbase, voff) do { _Pragma("unroll") for (int _i = 0; _i < 2; ++_i) \
;         __builtin_amdgcn_global_load_lds((const unsigned*)((const char*)(gbase) + (voff)[_i]), (PG8_LAS unsigned*)(lds + (bufoff) + ldsw + _i * 8192), 16, 0, 0); } while (0)
; #define PG8_LDA(dst, b, h) do { _Pragma("unroll") for (int m = 0; m < 4; ++m) _Pragma("unroll") for (int k = 0; k < 2; ++k) dst[m][k] = *(const PG8_LAS bf16x8*)(lds + PG8_SA(b, h) + aoff + m * 2048 + k * 1024); } while (0)
; #define PG8_LDB(dst, b, h) do { _Pragma("unroll") for (int n = 0; n < 2; ++n) _Pragma("unroll") for (int k = 0; k < 2; ++k) dst[n][k] = *(const PG8_LAS bf16x8*)(lds + PG8_SB(b, h) + boff + n * 2048 + k * 1024); } while (0)
; #define PG8_MMA(ai, bj, At, Bt) do { __builtin_amdgcn_s_setprio(1); _Pragma("unroll") for (int m = 0; m < 4; ++m) _Pragma("unroll") for (int n = 0; n < 2; ++n) _Pragma("unroll") for (int k = 0; k < 2; ++k) \
;         acc[ai][bj][m][n] = __builtin_amdgcn_mfma_f32_16x16x32_bf16(Bt[n][k], At[m][k], acc[ai][bj][m][n], 0, 0, 0); __builtin_amdgcn_s_setprio(0); } while (0)
; #define PG8_WAIT_V(n) asm volatile("s_waitcnt vmcnt(" #n ")" ::: "memory")
; #define PG8_WAIT_L(n) asm volatile("s_waitcnt lgkmcnt(" #n ")" ::: "memory")
; #define PG8_BAR __builtin_amdgcn_s_barrier()
; #define PG8_SCHED __builtin_amdgcn_sched_barrier(0)
; template <class Epi, class Sched, bool ALIGN_EPI = false, bool SP2 = false>
; __device__ __forceinline__ void gemm_phase(PG8_LAS unsigned char* lds, const Gemm g, const Sched& S, const Epi& E) {
;     ...
;             PG8_WAIT_V(8); PG8_WAIT_L(0); PG8_BAR; PG8_MMA(1, 0, At, B0); PG8_MMA(1, 1, At, B1); PG8_BAR; PG8_SCHED;
;             PG8_LDB(B0, 1, 0); PG8_LDB(B1, 1, 1); PG8_SCHED; PG8_LDA(At, 1, 0); PG8_STAGE(PG8_SA(0, 1), a2 + hstep, voffA);
;             PG8_WAIT_V(8); PG8_WAIT_L(0); PG8_BAR; PG8_MMA(0, 0, At, B0); PG8_MMA(0, 1, At, B1); PG8_BAR; PG8_SCHED;
	s_setprio 1
	s_waitcnt lgkmcnt(0)
	v_mfma_f32_16x16x32_bf16 v[62:65], v[140:143], v[196:199], v[62:65]
	v_mfma_f32_16x16x32_bf16 v[58:61], v[154:157], v[196:199], v[58:61]
	v_mfma_f32_16x16x32_bf16 v[46:49], v[140:143], v[204:207], v[46:49]
	v_mfma_f32_16x16x32_bf16 v[42:45], v[154:157], v[204:207], v[42:45]
	v_mfma_f32_16x16x32_bf16 v[30:33], v[140:143], v[212:215], v[30:33]
	v_mfma_f32_16x16x32_bf16 v[26:29], v[154:157], v[212:215], v[26:29]
	v_mfma_f32_16x16x32_bf16 v[14:17], v[140:143], v[220:223], v[14:17]
	v_mfma_f32_16x16x32_bf16 v[10:13], v[154:157], v[220:223], v[10:13]
	v_mfma_f32_16x16x32_bf16 v[62:65], v[150:153], v[200:203], v[62:65]
	v_mfma_f32_16x16x32_bf16 v[58:61], v[168:171], v[200:203], v[58:61]
	v_mfma_f32_16x16x32_bf16 v[46:49], v[150:153], v[208:211], v[46:49]
	v_mfma_f32_16x16x32_bf16 v[42:45], v[168:171], v[208:211], v[42:45]
	v_mfma_f32_16x16x32_bf16 v[30:33], v[150:153], v[216:219], v[30:33]
	v_mfma_f32_16x16x32_bf16 v[26:29], v[168:171], v[216:219], v[26:29]
	v_mfma_f32_16x16x32_bf16 v[14:17], v[150:153], v[224:227], v[14:17]
	v_mfma_f32_16x16x32_bf16 v[10:13], v[168:171], v[224:227], v[10:13]
	s_setprio 0
	s_setprio 1
	v_mfma_f32_16x16x32_bf16 v[54:57], v[172:175], v[196:199], v[54:57]
	v_mfma_f32_16x16x32_bf16 v[50:53], v[180:183], v[196:199], v[50:53]
	v_mfma_f32_16x16x32_bf16 v[38:41], v[172:175], v[204:207], v[38:41]
	v_mfma_f32_16x16x32_bf16 v[34:37], v[180:183], v[204:207], v[34:37]
	v_mfma_f32_16x16x32_bf16 v[22:25], v[172:175], v[212:215], v[22:25]
	v_mfma_f32_16x16x32_bf16 v[18:21], v[180:183], v[212:215], v[18:21]
	v_mfma_f32_16x16x32_bf16 v[6:9], v[172:175], v[220:223], v[6:9]
	v_mfma_f32_16x16x32_bf16 v[2:5], v[180:183], v[220:223], v[2:5]
	v_mfma_f32_16x16x32_bf16 v[54:57], v[176:179], v[200:203], v[54:57]
	v_mfma_f32_16x16x32_bf16 v[50:53], v[192:195], v[200:203], v[50:53]
	v_mfma_f32_16x16x32_bf16 v[38:41], v[176:179], v[208:211], v[38:41]
	v_mfma_f32_16x16x32_bf16 v[34:37], v[192:195], v[208:211], v[34:37]
	v_mfma_f32_16x16x32_bf16 v[22:25], v[176:179], v[216:219], v[22:25]
	v_mfma_f32_16x16x32_bf16 v[18:21], v[192:195], v[216:219], v[18:21]
	v_mfma_f32_16x16x32_bf16 v[6:9], v[176:179], v[224:227], v[6:9]
	v_mfma_f32_16x16x32_bf16 v[2:5], v[192:195], v[224:227], v[2:5]
	s_setprio 0
	s_barrier
	s_add_i32 s85, 0, 0x18000
	s_add_i32 s86, 0, 0x1c000
	v_add_u32_e32 v168, s85, v147
	v_add_u32_e32 v191, s86, v147
	ds_read_b128 v[140:143], v168
	ds_read_b128 v[150:153], v168 offset:1024
	ds_read_b128 v[154:157], v168 offset:2048
	ds_read_b128 v[168:171], v168 offset:3072
	ds_read_b128 v[172:175], v191
	ds_read_b128 v[176:179], v191 offset:1024
	ds_read_b128 v[180:183], v191 offset:2048
	ds_read_b128 v[192:195], v191 offset:3072
	s_add_u32 s10, s10, s14
	s_addc_u32 s11, s11, s15
	s_mov_b32 m0, s44
	s_nop 0
	global_load_lds_dwordx4 v[228:229], off
	s_mov_b32 m0, s45
	s_nop 0
	global_load_lds_dwordx4 v[230:231], off
	s_mov_b32 m0, s46
	v_lshl_add_u64 v[232:233], s[10:11], 0, v[130:131]
	ds_read_b128 v[196:199], v149 offset:32768
	ds_read_b128 v[200:203], v149 offset:33792
	ds_read_b128 v[204:207], v149 offset:34816
	ds_read_b128 v[208:211], v149 offset:35840
	ds_read_b128 v[212:215], v149 offset:36864
	ds_read_b128 v[216:219], v149 offset:37888
	ds_read_b128 v[220:223], v149 offset:38912
	ds_read_b128 v[224:227], v149 offset:39936
	global_load_lds_dwordx4 v[232:233], off
	v_lshl_add_u64 v[232:233], s[10:11], 0, v[132:133]
	s_mov_b32 m0, s47
	s_nop 0
	global_load_lds_dwordx4 v[232:233], off
	s_waitcnt vmcnt(8)
	s_waitcnt lgkmcnt(0)
	s_barrier
	s_setprio 1
	s_waitcnt lgkmcnt(0)
	v_mfma_f32_16x16x32_bf16 v[122:125], v[140:143], v[196:199], v[122:125]
	v_mfma_f32_16x16x32_bf16 v[126:129], v[154:157], v[196:199], v[126:129]
	v_mfma_f32_16x16x32_bf16 v[110:113], v[140:143], v[204:207], v[110:113]
	v_mfma_f32_16x16x32_bf16 v[106:109], v[154:157], v[204:207], v[106:109]
	v_mfma_f32_16x16x32_bf16 v[94:97], v[140:143], v[212:215], v[94:97]
	v_mfma_f32_16x16x32_bf16 v[90:93], v[154:157], v[212:215], v[90:93]
	v_mfma_f32_16x16x32_bf16 v[78:81], v[140:143], v[220:223], v[78:81]
	v_mfma_f32_16x16x32_bf16 v[74:77], v[154:157], v[220:223], v[74:77]
	v_mfma_f32_16x16x32_bf16 v[122:125], v[150:153], v[200:203], v[122:125]
	v_mfma_f32_16x16x32_bf16 v[126:129], v[168:171], v[200:203], v[126:129]
	v_mfma_f32_16x16x32_bf16 v[110:113], v[150:153], v[208:211], v[110:113]
	v_mfma_f32_16x16x32_bf16 v[106:109], v[168:171], v[208:211], v[106:109]
	v_mfma_f32_16x16x32_bf16 v[94:97], v[150:153], v[216:219], v[94:97]
	v_mfma_f32_16x16x32_bf16 v[90:93], v[168:171], v[216:219], v[90:93]
	v_mfma_f32_16x16x32_bf16 v[78:81], v[150:153], v[224:227], v[78:81]
	v_mfma_f32_16x16x32_bf16 v[74:77], v[168:171], v[224:227], v[74:77]
	s_setprio 0
	s_setprio 1
	v_mfma_f32_16x16x32_bf16 v[118:121], v[172:175], v[196:199], v[118:121]
	v_mfma_f32_16x16x32_bf16 v[114:117], v[180:183], v[196:199], v[114:117]
	v_mfma_f32_16x16x32_bf16 v[102:105], v[172:175], v[204:207], v[102:105]
	v_mfma_f32_16x16x32_bf16 v[98:101], v[180:183], v[204:207], v[98:101]
	v_mfma_f32_16x16x32_bf16 v[86:89], v[172:175], v[212:215], v[86:89]
	v_mfma_f32_16x16x32_bf16 v[82:85], v[180:183], v[212:215], v[82:85]
	v_mfma_f32_16x16x32_bf16 v[70:73], v[172:175], v[220:223], v[70:73]
	v_mfma_f32_16x16x32_bf16 v[66:69], v[180:183], v[220:223], v[66:69]
	v_mfma_f32_16x16x32_bf16 v[118:121], v[176:179], v[200:203], v[118:121]
	v_mfma_f32_16x16x32_bf16 v[114:117], v[192:195], v[200:203], v[114:117]
	v_mfma_f32_16x16x32_bf16 v[102:105], v[176:179], v[208:211], v[102:105]
	v_mfma_f32_16x16x32_bf16 v[98:101], v[192:195], v[208:211], v[98:101]
	v_mfma_f32_16x16x32_bf16 v[86:89], v[176:179], v[216:219], v[86:89]
	v_mfma_f32_16x16x32_bf16 v[82:85], v[192:195], v[216:219], v[82:85]
	v_mfma_f32_16x16x32_bf16 v[70:73], v[176:179], v[224:227], v[70:73]
	v_mfma_f32_16x16x32_bf16 v[66:69], v[192:195], v[224:227], v[66:69]
	s_setprio 0
	s_barrier
; #define PG8_STAGE(bufoff, gbase, voff) do { _Pragma("unroll") for (int _i = 0; _i < 2; ++_i) \
;         __builtin_amdgcn_global_load_lds((const unsigned*)((const char*)(gbase) + (voff)[_i]), (PG8_LAS unsigned*)(lds + (bufoff) + ldsw + _i * 8192), 16, 0, 0); } while (0)
; #define PG8_LDA(dst, b, h) do { _Pragma("unroll") for (int m = 0; m < 4; ++m) _Pragma("unroll") for (int k = 0; k < 2; ++k) dst[m][k] = *(const PG8_LAS bf16x8*)(lds + PG8_SA(b, h) + aoff + m * 2048 + k * 1024); } while (0)
; #define PG8_MMA(ai, bj, At, Bt) do { __builtin_amdgcn_s_setprio(1); _Pragma("unroll") for (int m = 0; m < 4; ++m) _Pragma("unroll") for (int n = 0; n < 2; ++n) _Pragma("unroll") for (int k = 0; k < 2; ++k) \
;         acc[ai][bj][m][n] = __builtin_amdgcn_mfma_f32_16x16x32_bf16(Bt[n][k], At[m][k], acc[ai][bj][m][n], 0, 0, 0); __builtin_amdgcn_s_setprio(0); } while (0)
; #define PG8_WAIT_V(n) asm volatile("s_waitcnt vmcnt(" #n ")" ::: "memory")
; #define PG8_WAIT_L(n) asm volatile("s_waitcnt lgkmcnt(" #n ")" ::: "memory")
; #define PG8_BAR __builtin_amdgcn_s_barrier()
; #define PG8_SCHED __builtin_amdgcn_sched_barrier(0)
; template <class Epi, class Sched, bool ALIGN_EPI = false, bool SP2 = false>
; __device__ __forceinline__ void gemm_phase(PG8_LAS unsigned char* lds, const Gemm g, const Sched& S, const Epi& E) {
;     ...
;         for (int t = 0; t < nt; t += 2) {
;     ...
;             PG8_LDA(At, 1, 1); PG8_STAGE(PG8_SB(1, 0), b3, voffB); PG8_STAGE(PG8_SB(1, 1), b3 + hstep, voffB); PG8_STAGE(PG8_SA(1, 0), a3, voffA);
;             PG8_WAIT_V(8); PG8_WAIT_L(0); PG8_BAR; PG8_MMA(1, 0, At, B0); PG8_MMA(1, 1, At, B1); PG8_BAR; PG8_SCHED;
	s_add_i32 s10, s85, s43
	v_lshl_add_u64 v[144:145], v[144:145], 0, s[88:89]
	s_mov_b32 m0, s10
	ds_read_b128 v[196:199], v149 offset:49152
	ds_read_b128 v[200:203], v149 offset:50176
	ds_read_b128 v[204:207], v149 offset:51200
	ds_read_b128 v[208:211], v149 offset:52224
	ds_read_b128 v[212:215], v149 offset:53248
	ds_read_b128 v[216:219], v149 offset:54272
	ds_read_b128 v[220:223], v149 offset:55296
	ds_read_b128 v[224:227], v149 offset:56320
	global_load_lds_dwordx4 v[144:145], off
	v_lshl_add_u64 v[144:145], v[158:159], 0, s[88:89]
	s_add_i32 m0, s10, 0x2000
	s_add_i32 s10, s86, s43
	global_load_lds_dwordx4 v[144:145], off
	v_lshl_add_u64 v[144:145], v[166:167], 0, s[88:89]
	s_mov_b32 m0, s10
	s_nop 0
	global_load_lds_dwordx4 v[144:145], off
	v_lshl_add_u64 v[144:145], v[184:185], 0, s[88:89]
	s_add_i32 m0, s10, 0x2000
	s_nop 0
	global_load_lds_dwordx4 v[144:145], off
	v_lshl_add_u64 v[144:145], v[228:229], 0, s[88:89]
	s_mov_b32 m0, s48
	s_nop 0
	global_load_lds_dwordx4 v[144:145], off
	v_lshl_add_u64 v[144:145], v[230:231], 0, s[88:89]
	s_mov_b32 m0, s49
	s_nop 0
	global_load_lds_dwordx4 v[144:145], off
	s_waitcnt vmcnt(8)
	s_waitcnt lgkmcnt(0)
	s_barrier
	s_setprio 1
	s_waitcnt lgkmcnt(0)
	v_mfma_f32_16x16x32_bf16 v[62:65], v[140:143], v[196:199], v[62:65]
	v_mfma_f32_16x16x32_bf16 v[58:61], v[154:157], v[196:199], v[58:61]
	v_mfma_f32_16x16x32_bf16 v[46:49], v[140:143], v[204:207], v[46:49]
	v_mfma_f32_16x16x32_bf16 v[42:45], v[154:157], v[204:207], v[42:45]
	v_mfma_f32_16x16x32_bf16 v[30:33], v[140:143], v[212:215], v[30:33]
	v_mfma_f32_16x16x32_bf16 v[26:29], v[154:157], v[212:215], v[26:29]
	v_mfma_f32_16x16x32_bf16 v[14:17], v[140:143], v[220:223], v[14:17]
	v_mfma_f32_16x16x32_bf16 v[10:13], v[154:157], v[220:223], v[10:13]
	v_mfma_f32_16x16x32_bf16 v[62:65], v[150:153], v[200:203], v[62:65]
	v_mfma_f32_16x16x32_bf16 v[58:61], v[168:171], v[200:203], v[58:61]
	v_mfma_f32_16x16x32_bf16 v[46:49], v[150:153], v[208:211], v[46:49]
	v_mfma_f32_16x16x32_bf16 v[42:45], v[168:171], v[208:211], v[42:45]
	v_mfma_f32_16x16x32_bf16 v[30:33], v[150:153], v[216:219], v[30:33]
	v_mfma_f32_16x16x32_bf16 v[26:29], v[168:171], v[216:219], v[26:29]
	v_mfma_f32_16x16x32_bf16 v[14:17], v[150:153], v[224:227], v[14:17]
	v_mfma_f32_16x16x32_bf16 v[10:13], v[168:171], v[224:227], v[10:13]
	s_setprio 0
	s_setprio 1
	v_mfma_f32_16x16x32_bf16 v[54:57], v[172:175], v[196:199], v[54:57]
	v_mfma_f32_16x16x32_bf16 v[50:53], v[180:183], v[196:199], v[50:53]
	v_mfma_f32_16x16x32_bf16 v[38:41], v[172:175], v[204:207], v[38:41]
	v_mfma_f32_16x16x32_bf16 v[34:37], v[180:183], v[204:207], v[34:37]
	v_mfma_f32_16x16x32_bf16 v[22:25], v[172:175], v[212:215], v[22:25]
	v_mfma_f32_16x16x32_bf16 v[18:21], v[180:183], v[212:215], v[18:21]
	v_mfma_f32_16x16x32_bf16 v[6:9], v[172:175], v[220:223], v[6:9]
	v_mfma_f32_16x16x32_bf16 v[2:5], v[180:183], v[220:223], v[2:5]
	v_mfma_f32_16x16x32_bf16 v[54:57], v[176:179], v[200:203], v[54:57]
	v_mfma_f32_16x16x32_bf16 v[50:53], v[192:195], v[200:203], v[50:53]
	v_mfma_f32_16x16x32_bf16 v[38:41], v[176:179], v[208:211], v[38:41]
	v_mfma_f32_16x16x32_bf16 v[34:37], v[192:195], v[208:211], v[34:37]
	v_mfma_f32_16x16x32_bf16 v[22:25], v[176:179], v[216:219], v[22:25]
	v_mfma_f32_16x16x32_bf16 v[18:21], v[192:195], v[216:219], v[18:21]
	v_mfma_f32_16x16x32_bf16 v[6:9], v[176:179], v[224:227], v[6:9]
	v_mfma_f32_16x16x32_bf16 v[2:5], v[192:195], v[224:227], v[2:5]
	s_setprio 0
	s_barrier
	s_add_u32 s8, s8, 0x100
	s_addc_u32 s9, s9, 0
	s_add_u32 s81, s81, 0x100
	s_addc_u32 s83, s83, 0
	s_cmp_ge_i32 s84, s52
	s_mov_b32 s10, s84
	s_cbranch_scc0 .LBB0_251
	s_movk_i32 s92, 0x2c00

; #define PG8_STAGE(bufoff, gbase, voff) do { _Pragma("unroll") for (int _i = 0; _i < 2; ++_i) \
;         __builtin_amdgcn_global_load_lds((const unsigned*)((const char*)(gbase) + (voff)[_i]), (PG8_LAS unsigned*)(lds + (bufoff) + ldsw + _i * 8192), 16, 0, 0); } while (0)
; #define PG8_LDA(dst, b, h) do { _Pragma("unroll") for (int m = 0; m < 4; ++m) _Pragma("unroll") for (int k = 0; k < 2; ++k) dst[m][k] = *(const PG8_LAS bf16x8*)(lds + PG8_SA(b, h) + aoff + m * 2048 + k * 1024); } while (0)
; #define PG8_LDB(dst, b, h) do { _Pragma("unroll") for (int n = 0; n < 2; ++n) _Pragma("unroll") for (int k = 0; k < 2; ++k) dst[n][k] = *(const PG8_LAS bf16x8*)(lds + PG8_SB(b, h) + boff + n * 2048 + k * 1024); } while (0)
; #define PG8_MMA(ai, bj, At, Bt) do { __builtin_amdgcn_s_setprio(1); _Pragma("unroll") for (int m = 0; m < 4; ++m) _Pragma("unroll") for (int n = 0; n < 2; ++n) _Pragma("unroll") for (int k = 0; k < 2; ++k) \
;         acc[ai][bj][m][n] = __builtin_amdgcn_mfma_f32_16x16x32_bf16(Bt[n][k], At[m][k], acc[ai][bj][m][n], 0, 0, 0); __builtin_amdgcn_s_setprio(0); } while (0)
; #define PG8_WAIT_V(n) asm volatile("s_waitcnt vmcnt(" #n ")" ::: "memory")
; #define PG8_WAIT_L(n) asm volatile("s_waitcnt lgkmcnt(" #n ")" ::: "memory")
; template <class Epi, class Sched, bool ALIGN_EPI = false, bool SP2 = false>
; __device__ __forceinline__ void gemm_phase(PG8_LAS unsigned char* lds, const Gemm g, const Sched& S, const Epi& E) {
;     ...
;             const bool last = (t == nt - 2);
;             const char* a1 = cA + (size_t)(t + 1) * kstep;
;             const char* a2 = last ? nA : cA + (size_t)(t + 2) * kstep; const char* b2 = last ? nB : cB + (size_t)(t + 2) * kstep;
;             const char* a3 = a2 + kstep; const char* b3 = b2 + kstep;
;             if (last && has_next) S.a_ready(nxt);
;             if constexpr (SP2) {
;             PG8_LDB(B0, 0, 0); PG8_LDB(B1, 0, 1); PG8_SCHED; PG8_LDA(At, 0, 0); PG8_STAGE(PG8_SA(1, 1), a1 + hstep, voffA);
;             PG8_WAIT_V(8); PG8_WAIT_L(0); PG8_BAR; PG8_MMA(0, 0, At, B0); PG8_MMA(0, 1, At, B1); PG8_BAR; PG8_SCHED;
;             PG8_LDA(At, 0, 1); PG8_STAGE(PG8_SB(0, 0), b2, voffB); PG8_STAGE(PG8_SB(0, 1), b2 + hstep, voffB); PG8_STAGE(PG8_SA(0, 0), a2, voffA);
;             PG8_WAIT_V(8); PG8_WAIT_L(0); PG8_BAR; PG8_MMA(1, 0, At, B0); PG8_MMA(1, 1, At, B1); PG8_BAR; PG8_SCHED;
.LBB0_308:
	s_add_i32 s40, s8, 2
	s_add_u32 s41, s0, 0x80
	s_addc_u32 s9, s1, 0
	s_add_i32 s85, 0, 0x10000
	s_cmp_eq_u32 s75, s8
	s_cselect_b32 s9, s35, s9
	s_cselect_b32 s8, s34, s41
	v_add_u32_e32 v146, s85, v148
	s_cselect_b32 s87, s37, s11
	s_cselect_b32 s86, s36, s10
	s_add_i32 s41, 0, 0x14000
	ds_read_b128 v[142:145], v146
	ds_read_b128 v[174:177], v146 offset:1024
	ds_read_b128 v[178:181], v146 offset:2048
	ds_read_b128 v[182:185], v146 offset:3072
	v_add_u32_e32 v146, s41, v148
	ds_read_b128 v[192:195], v146
	ds_read_b128 v[196:199], v146 offset:1024
	ds_read_b128 v[200:203], v146 offset:2048
	ds_read_b128 v[204:207], v146 offset:3072
	v_lshl_add_u64 v[166:167], s[0:1], 0, v[138:139]
	s_add_i32 m0, s44, 0xc000
	ds_read_b128 v[208:211], v173
	ds_read_b128 v[212:215], v173 offset:1024
	ds_read_b128 v[216:219], v173 offset:2048
	ds_read_b128 v[220:223], v173 offset:3072
	ds_read_b128 v[224:227], v173 offset:4096
	ds_read_b128 v[228:231], v173 offset:5120
	ds_read_b128 v[232:235], v173 offset:6144
	ds_read_b128 v[236:239], v173 offset:7168
	global_load_lds_dwordx4 v[166:167], off
	v_lshl_add_u64 v[166:167], s[0:1], 0, v[140:141]
	s_add_i32 m0, s44, 0xe000
	s_nop 0
	global_load_lds_dwordx4 v[166:167], off
	s_waitcnt vmcnt(8)
	s_waitcnt lgkmcnt(0)
	s_barrier
	s_setprio 1
	s_waitcnt lgkmcnt(0)
	v_mfma_f32_16x16x32_bf16 v[126:129], v[142:145], v[208:211], v[126:129]
	v_mfma_f32_16x16x32_bf16 v[122:125], v[178:181], v[208:211], v[122:125]
	v_mfma_f32_16x16x32_bf16 v[110:113], v[142:145], v[216:219], v[110:113]
	v_mfma_f32_16x16x32_bf16 v[106:109], v[178:181], v[216:219], v[106:109]
	v_mfma_f32_16x16x32_bf16 v[94:97], v[142:145], v[224:227], v[94:97]
	v_mfma_f32_16x16x32_bf16 v[90:93], v[178:181], v[224:227], v[90:93]
	v_mfma_f32_16x16x32_bf16 v[78:81], v[142:145], v[232:235], v[78:81]
	v_mfma_f32_16x16x32_bf16 v[74:77], v[178:181], v[232:235], v[74:77]
	v_mfma_f32_16x16x32_bf16 v[126:129], v[174:177], v[212:215], v[126:129]
	v_mfma_f32_16x16x32_bf16 v[122:125], v[182:185], v[212:215], v[122:125]
	v_mfma_f32_16x16x32_bf16 v[110:113], v[174:177], v[220:223], v[110:113]
	v_mfma_f32_16x16x32_bf16 v[106:109], v[182:185], v[220:223], v[106:109]
	v_mfma_f32_16x16x32_bf16 v[94:97], v[174:177], v[228:231], v[94:97]
	v_mfma_f32_16x16x32_bf16 v[90:93], v[182:185], v[228:231], v[90:93]
	v_mfma_f32_16x16x32_bf16 v[78:81], v[174:177], v[236:239], v[78:81]
	v_mfma_f32_16x16x32_bf16 v[74:77], v[182:185], v[236:239], v[74:77]
	s_setprio 0
	s_setprio 1
	v_mfma_f32_16x16x32_bf16 v[118:121], v[192:195], v[208:211], v[118:121]
	v_mfma_f32_16x16x32_bf16 v[114:117], v[200:203], v[208:211], v[114:117]
	v_mfma_f32_16x16x32_bf16 v[102:105], v[192:195], v[216:219], v[102:105]
	v_mfma_f32_16x16x32_bf16 v[98:101], v[200:203], v[216:219], v[98:101]
	v_mfma_f32_16x16x32_bf16 v[86:89], v[192:195], v[224:227], v[86:89]
	v_mfma_f32_16x16x32_bf16 v[82:85], v[200:203], v[224:227], v[82:85]
	v_mfma_f32_16x16x32_bf16 v[70:73], v[192:195], v[232:235], v[70:73]
	v_mfma_f32_16x16x32_bf16 v[66:69], v[200:203], v[232:235], v[66:69]
	v_mfma_f32_16x16x32_bf16 v[118:121], v[196:199], v[212:215], v[118:121]
	v_mfma_f32_16x16x32_bf16 v[114:117], v[204:207], v[212:215], v[114:117]
	v_mfma_f32_16x16x32_bf16 v[102:105], v[196:199], v[220:223], v[102:105]
	v_mfma_f32_16x16x32_bf16 v[98:101], v[204:207], v[220:223], v[98:101]
	v_mfma_f32_16x16x32_bf16 v[86:89], v[196:199], v[228:231], v[86:89]
	v_mfma_f32_16x16x32_bf16 v[82:85], v[204:207], v[228:231], v[82:85]
	v_mfma_f32_16x16x32_bf16 v[70:73], v[196:199], v[236:239], v[70:73]
	v_mfma_f32_16x16x32_bf16 v[66:69], v[204:207], v[236:239], v[66:69]
	s_setprio 0
	s_barrier
	s_add_i32 s85, s85, s4
	v_lshl_add_u64 v[166:167], s[86:87], 0, v[160:161]
	s_mov_b32 m0, s85
	ds_read_b128 v[208:211], v173 offset:16384
	ds_read_b128 v[212:215], v173 offset:17408
	ds_read_b128 v[216:219], v173 offset:18432
	ds_read_b128 v[220:223], v173 offset:19456
	ds_read_b128 v[224:227], v173 offset:20480
	ds_read_b128 v[228:231], v173 offset:21504
	ds_read_b128 v[232:235], v173 offset:22528
	ds_read_b128 v[236:239], v173 offset:23552
	global_load_lds_dwordx4 v[166:167], off
	s_add_i32 m0, s85, 0x2000
	v_lshl_add_u64 v[240:241], s[86:87], 0, v[134:135]
	s_add_u32 s86, s86, s14
	s_addc_u32 s87, s87, s15
	s_add_i32 s41, s41, s4
	global_load_lds_dwordx4 v[240:241], off
	v_lshl_add_u64 v[242:243], s[86:87], 0, v[160:161]
	s_mov_b32 m0, s41
	v_lshl_add_u64 v[244:245], s[86:87], 0, v[134:135]
	global_load_lds_dwordx4 v[242:243], off
	s_add_i32 m0, s41, 0x2000
	v_lshl_add_u64 v[246:247], s[8:9], 0, v[130:131]
	global_load_lds_dwordx4 v[244:245], off
	v_lshl_add_u64 v[248:249], s[8:9], 0, v[132:133]
	s_nop 0
	s_waitcnt vmcnt(6)
	s_waitcnt lgkmcnt(0)
	s_barrier
; #define PG8_STAGE(bufoff, gbase, voff) do { _Pragma("unroll") for (int _i = 0; _i < 2; ++_i) \
;         __builtin_amdgcn_global_load_lds((const unsigned*)((const char*)(gbase) + (voff)[_i]), (PG8_LAS unsigned*)(lds + (bufoff) + ldsw + _i * 8192), 16, 0, 0); } while (0)
; #define PG8_LDA(dst, b, h) do { _Pragma("unroll") for (int m = 0; m < 4; ++m) _Pragma("unroll") for (int k = 0; k < 2; ++k) dst[m][k] = *(const PG8_LAS bf16x8*)(lds + PG8_SA(b, h) + aoff + m * 2048 + k * 1024); } while (0)
; #define PG8_LDB(dst, b, h) do { _Pragma("unroll") for (int n = 0; n < 2; ++n) _Pragma("unroll") for (int k = 0; k < 2; ++k) dst[n][k] = *(const PG8_LAS bf16x8*)(lds + PG8_SB(b, h) + boff + n * 2048 + k * 1024); } while (0)
; #define PG8_MMA(ai, bj, At, Bt) do { __builtin_amdgcn_s_setprio(1); _Pragma("unroll") for (int m = 0; m < 4; ++m) _Pragma("unroll") for (int n = 0; n < 2; ++n) _Pragma("unroll") for (int k = 0; k < 2; ++k) \
;         acc[ai][bj][m][n] = __builtin_amdgcn_mfma_f32_16x16x32_bf16(Bt[n][k], At[m][k], acc[ai][bj][m][n], 0, 0, 0); __builtin_amdgcn_s_setprio(0); } while (0)
; #define PG8_WAIT_V(n) asm volatile("s_waitcnt vmcnt(" #n ")" ::: "memory")
; #define PG8_WAIT_L(n) asm volatile("s_waitcnt lgkmcnt(" #n ")" ::: "memory")
; #define PG8_BAR __builtin_amdgcn_s_barrier()
; #define PG8_SCHED __builtin_amdgcn_sched_barrier(0)
; template <class Epi, class Sched, bool ALIGN_EPI = false, bool SP2 = false>
; __device__ __forceinline__ void gemm_phase(PG8_LAS unsigned char* lds, const Gemm g, const Sched& S, const Epi& E) {
;     ...
;             PG8_WAIT_V(8); PG8_WAIT_L(0); PG8_BAR; PG8_MMA(1, 0, At, B0); PG8_MMA(1, 1, At, B1); PG8_BAR; PG8_SCHED;
;             PG8_LDB(B0, 1, 0); PG8_LDB(B1, 1, 1); PG8_SCHED; PG8_LDA(At, 1, 0); PG8_STAGE(PG8_SA(0, 1), a2 + hstep, voffA);
;             PG8_WAIT_V(8); PG8_WAIT_L(0); PG8_BAR; PG8_MMA(0, 0, At, B0); PG8_MMA(0, 1, At, B1); PG8_BAR; PG8_SCHED;
	s_setprio 1
	s_waitcnt lgkmcnt(0)
	v_mfma_f32_16x16x32_bf16 v[62:65], v[142:145], v[208:211], v[62:65]
	v_mfma_f32_16x16x32_bf16 v[58:61], v[178:181], v[208:211], v[58:61]
	v_mfma_f32_16x16x32_bf16 v[46:49], v[142:145], v[216:219], v[46:49]
	v_mfma_f32_16x16x32_bf16 v[42:45], v[178:181], v[216:219], v[42:45]
	v_mfma_f32_16x16x32_bf16 v[30:33], v[142:145], v[224:227], v[30:33]
	v_mfma_f32_16x16x32_bf16 v[26:29], v[178:181], v[224:227], v[26:29]
	v_mfma_f32_16x16x32_bf16 v[14:17], v[142:145], v[232:235], v[14:17]
	v_mfma_f32_16x16x32_bf16 v[10:13], v[178:181], v[232:235], v[10:13]
	v_mfma_f32_16x16x32_bf16 v[62:65], v[174:177], v[212:215], v[62:65]
	v_mfma_f32_16x16x32_bf16 v[58:61], v[182:185], v[212:215], v[58:61]
	v_mfma_f32_16x16x32_bf16 v[46:49], v[174:177], v[220:223], v[46:49]
	v_mfma_f32_16x16x32_bf16 v[42:45], v[182:185], v[220:223], v[42:45]
	v_mfma_f32_16x16x32_bf16 v[30:33], v[174:177], v[228:231], v[30:33]
	v_mfma_f32_16x16x32_bf16 v[26:29], v[182:185], v[228:231], v[26:29]
	v_mfma_f32_16x16x32_bf16 v[14:17], v[174:177], v[236:239], v[14:17]
	v_mfma_f32_16x16x32_bf16 v[10:13], v[182:185], v[236:239], v[10:13]
	s_setprio 0
	s_setprio 1
	v_mfma_f32_16x16x32_bf16 v[54:57], v[192:195], v[208:211], v[54:57]
	v_mfma_f32_16x16x32_bf16 v[50:53], v[200:203], v[208:211], v[50:53]
	v_mfma_f32_16x16x32_bf16 v[38:41], v[192:195], v[216:219], v[38:41]
	v_mfma_f32_16x16x32_bf16 v[34:37], v[200:203], v[216:219], v[34:37]
	v_mfma_f32_16x16x32_bf16 v[22:25], v[192:195], v[224:227], v[22:25]
	v_mfma_f32_16x16x32_bf16 v[18:21], v[200:203], v[224:227], v[18:21]
	v_mfma_f32_16x16x32_bf16 v[6:9], v[192:195], v[232:235], v[6:9]
	v_mfma_f32_16x16x32_bf16 v[2:5], v[200:203], v[232:235], v[2:5]
	v_mfma_f32_16x16x32_bf16 v[54:57], v[196:199], v[212:215], v[54:57]
	v_mfma_f32_16x16x32_bf16 v[50:53], v[204:207], v[212:215], v[50:53]
	v_mfma_f32_16x16x32_bf16 v[38:41], v[196:199], v[220:223], v[38:41]
	v_mfma_f32_16x16x32_bf16 v[34:37], v[204:207], v[220:223], v[34:37]
	v_mfma_f32_16x16x32_bf16 v[22:25], v[196:199], v[228:231], v[22:25]
	v_mfma_f32_16x16x32_bf16 v[18:21], v[204:207], v[228:231], v[18:21]
	v_mfma_f32_16x16x32_bf16 v[6:9], v[196:199], v[236:239], v[6:9]
	v_mfma_f32_16x16x32_bf16 v[2:5], v[204:207], v[236:239], v[2:5]
	s_setprio 0
	s_barrier
	s_add_i32 s41, 0, 0x18000
	v_add_u32_e32 v146, s41, v148
	s_add_i32 s85, 0, 0x1c000
	ds_read_b128 v[142:145], v146
	ds_read_b128 v[174:177], v146 offset:1024
	ds_read_b128 v[178:181], v146 offset:2048
	ds_read_b128 v[182:185], v146 offset:3072
	v_add_u32_e32 v146, s85, v148
	ds_read_b128 v[192:195], v146
	ds_read_b128 v[196:199], v146 offset:1024
	ds_read_b128 v[200:203], v146 offset:2048
	ds_read_b128 v[204:207], v146 offset:3072
	s_add_u32 s8, s8, s14
	s_addc_u32 s9, s9, s15
	s_mov_b32 m0, s44
	s_nop 0
	global_load_lds_dwordx4 v[246:247], off
	s_mov_b32 m0, s45
	s_nop 0
	global_load_lds_dwordx4 v[248:249], off
	s_mov_b32 m0, s51
	v_lshl_add_u64 v[250:251], s[8:9], 0, v[130:131]
	ds_read_b128 v[208:211], v173 offset:32768
	ds_read_b128 v[212:215], v173 offset:33792
	ds_read_b128 v[216:219], v173 offset:34816
	ds_read_b128 v[220:223], v173 offset:35840
	ds_read_b128 v[224:227], v173 offset:36864
	ds_read_b128 v[228:231], v173 offset:37888
	ds_read_b128 v[232:235], v173 offset:38912
	ds_read_b128 v[236:239], v173 offset:39936
	global_load_lds_dwordx4 v[250:251], off
	v_lshl_add_u64 v[250:251], s[8:9], 0, v[132:133]
	s_mov_b32 m0, s52
	s_nop 0
	global_load_lds_dwordx4 v[250:251], off
	s_waitcnt vmcnt(8)
	s_waitcnt lgkmcnt(0)
	s_barrier
	s_setprio 1
	s_waitcnt lgkmcnt(0)
	v_mfma_f32_16x16x32_bf16 v[126:129], v[142:145], v[208:211], v[126:129]
	v_mfma_f32_16x16x32_bf16 v[122:125], v[178:181], v[208:211], v[122:125]
	v_mfma_f32_16x16x32_bf16 v[110:113], v[142:145], v[216:219], v[110:113]
	v_mfma_f32_16x16x32_bf16 v[106:109], v[178:181], v[216:219], v[106:109]
	v_mfma_f32_16x16x32_bf16 v[94:97], v[142:145], v[224:227], v[94:97]
	v_mfma_f32_16x16x32_bf16 v[90:93], v[178:181], v[224:227], v[90:93]
	v_mfma_f32_16x16x32_bf16 v[78:81], v[142:145], v[232:235], v[78:81]
	v_mfma_f32_16x16x32_bf16 v[74:77], v[178:181], v[232:235], v[74:77]
	v_mfma_f32_16x16x32_bf16 v[126:129], v[174:177], v[212:215], v[126:129]
	v_mfma_f32_16x16x32_bf16 v[122:125], v[182:185], v[212:215], v[122:125]
	v_mfma_f32_16x16x32_bf16 v[110:113], v[174:177], v[220:223], v[110:113]
	v_mfma_f32_16x16x32_bf16 v[106:109], v[182:185], v[220:223], v[106:109]
	v_mfma_f32_16x16x32_bf16 v[94:97], v[174:177], v[228:231], v[94:97]
	v_mfma_f32_16x16x32_bf16 v[90:93], v[182:185], v[228:231], v[90:93]
	v_mfma_f32_16x16x32_bf16 v[78:81], v[174:177], v[236:239], v[78:81]
	v_mfma_f32_16x16x32_bf16 v[74:77], v[182:185], v[236:239], v[74:77]
	s_setprio 0
	s_setprio 1
	v_mfma_f32_16x16x32_bf16 v[118:121], v[192:195], v[208:211], v[118:121]
	v_mfma_f32_16x16x32_bf16 v[114:117], v[200:203], v[208:211], v[114:117]
	v_mfma_f32_16x16x32_bf16 v[102:105], v[192:195], v[216:219], v[102:105]
	v_mfma_f32_16x16x32_bf16 v[98:101], v[200:203], v[216:219], v[98:101]
	v_mfma_f32_16x16x32_bf16 v[86:89], v[192:195], v[224:227], v[86:89]
	v_mfma_f32_16x16x32_bf16 v[82:85], v[200:203], v[224:227], v[82:85]
	v_mfma_f32_16x16x32_bf16 v[70:73], v[192:195], v[232:235], v[70:73]
	v_mfma_f32_16x16x32_bf16 v[66:69], v[200:203], v[232:235], v[66:69]
	v_mfma_f32_16x16x32_bf16 v[118:121], v[196:199], v[212:215], v[118:121]
	v_mfma_f32_16x16x32_bf16 v[114:117], v[204:207], v[212:215], v[114:117]
	v_mfma_f32_16x16x32_bf16 v[102:105], v[196:199], v[220:223], v[102:105]
	v_mfma_f32_16x16x32_bf16 v[98:101], v[204:207], v[220:223], v[98:101]
	v_mfma_f32_16x16x32_bf16 v[86:89], v[196:199], v[228:231], v[86:89]
	v_mfma_f32_16x16x32_bf16 v[82:85], v[204:207], v[228:231], v[82:85]
	v_mfma_f32_16x16x32_bf16 v[70:73], v[196:199], v[236:239], v[70:73]
	v_mfma_f32_16x16x32_bf16 v[66:69], v[204:207], v[236:239], v[66:69]
	s_setprio 0
	s_barrier
; #define PG8_STAGE(bufoff, gbase, voff) do { _Pragma("unroll") for (int _i = 0; _i < 2; ++_i) \
;         __builtin_amdgcn_global_load_lds((const unsigned*)((const char*)(gbase) + (voff)[_i]), (PG8_LAS unsigned*)(lds + (bufoff) + ldsw + _i * 8192), 16, 0, 0); } while (0)
; #define PG8_LDA(dst, b, h) do { _Pragma("unroll") for (int m = 0; m < 4; ++m) _Pragma("unroll") for (int k = 0; k < 2; ++k) dst[m][k] = *(const PG8_LAS bf16x8*)(lds + PG8_SA(b, h) + aoff + m * 2048 + k * 1024); } while (0)
; #define PG8_MMA(ai, bj, At, Bt) do { __builtin_amdgcn_s_setprio(1); _Pragma("unroll") for (int m = 0; m < 4; ++m) _Pragma("unroll") for (int n = 0; n < 2; ++n) _Pragma("unroll") for (int k = 0; k < 2; ++k) \
;         acc[ai][bj][m][n] = __builtin_amdgcn_mfma_f32_16x16x32_bf16(Bt[n][k], At[m][k], acc[ai][bj][m][n], 0, 0, 0); __builtin_amdgcn_s_setprio(0); } while (0)
; #define PG8_WAIT_V(n) asm volatile("s_waitcnt vmcnt(" #n ")" ::: "memory")
; #define PG8_WAIT_L(n) asm volatile("s_waitcnt lgkmcnt(" #n ")" ::: "memory")
; #define PG8_BAR __builtin_amdgcn_s_barrier()
; #define PG8_SCHED __builtin_amdgcn_sched_barrier(0)
; template <class Epi, class Sched, bool ALIGN_EPI = false, bool SP2 = false>
; __device__ __forceinline__ void gemm_phase(PG8_LAS unsigned char* lds, const Gemm g, const Sched& S, const Epi& E) {
;     ...
;         for (int t = 0; t < nt; t += 2) {
;     ...
;             PG8_LDA(At, 1, 1); PG8_STAGE(PG8_SB(1, 0), b3, voffB); PG8_STAGE(PG8_SB(1, 1), b3 + hstep, voffB); PG8_STAGE(PG8_SA(1, 0), a3, voffA);
;             PG8_WAIT_V(8); PG8_WAIT_L(0); PG8_BAR; PG8_MMA(1, 0, At, B0); PG8_MMA(1, 1, At, B1); PG8_BAR; PG8_SCHED;
	s_add_i32 s8, s41, s4
	v_lshl_add_u64 v[166:167], v[166:167], 0, s[88:89]
	s_mov_b32 m0, s8
	ds_read_b128 v[208:211], v173 offset:49152
	ds_read_b128 v[212:215], v173 offset:50176
	ds_read_b128 v[216:219], v173 offset:51200
	ds_read_b128 v[220:223], v173 offset:52224
	ds_read_b128 v[224:227], v173 offset:53248
	ds_read_b128 v[228:231], v173 offset:54272
	ds_read_b128 v[232:235], v173 offset:55296
	ds_read_b128 v[236:239], v173 offset:56320
	global_load_lds_dwordx4 v[166:167], off
	v_lshl_add_u64 v[166:167], v[240:241], 0, s[88:89]
	s_add_i32 m0, s8, 0x2000
	s_add_i32 s8, s85, s4
	global_load_lds_dwordx4 v[166:167], off
	v_lshl_add_u64 v[166:167], v[242:243], 0, s[88:89]
	s_mov_b32 m0, s8
	s_nop 0
	global_load_lds_dwordx4 v[166:167], off
	v_lshl_add_u64 v[166:167], v[244:245], 0, s[88:89]
	s_add_i32 m0, s8, 0x2000
	s_nop 0
	global_load_lds_dwordx4 v[166:167], off
	v_lshl_add_u64 v[166:167], v[246:247], 0, s[88:89]
	s_mov_b32 m0, s53
	s_nop 0
	global_load_lds_dwordx4 v[166:167], off
	v_lshl_add_u64 v[166:167], v[248:249], 0, s[88:89]
	s_mov_b32 m0, s56
	s_nop 0
	global_load_lds_dwordx4 v[166:167], off
	s_waitcnt vmcnt(8)
	s_waitcnt lgkmcnt(0)
	s_barrier
	s_setprio 1
	s_waitcnt lgkmcnt(0)
	v_mfma_f32_16x16x32_bf16 v[62:65], v[142:145], v[208:211], v[62:65]
	v_mfma_f32_16x16x32_bf16 v[58:61], v[178:181], v[208:211], v[58:61]
	v_mfma_f32_16x16x32_bf16 v[46:49], v[142:145], v[216:219], v[46:49]
	v_mfma_f32_16x16x32_bf16 v[42:45], v[178:181], v[216:219], v[42:45]
	v_mfma_f32_16x16x32_bf16 v[30:33], v[142:145], v[224:227], v[30:33]
	v_mfma_f32_16x16x32_bf16 v[26:29], v[178:181], v[224:227], v[26:29]
	v_mfma_f32_16x16x32_bf16 v[14:17], v[142:145], v[232:235], v[14:17]
	v_mfma_f32_16x16x32_bf16 v[10:13], v[178:181], v[232:235], v[10:13]
	v_mfma_f32_16x16x32_bf16 v[62:65], v[174:177], v[212:215], v[62:65]
	v_mfma_f32_16x16x32_bf16 v[58:61], v[182:185], v[212:215], v[58:61]
	v_mfma_f32_16x16x32_bf16 v[46:49], v[174:177], v[220:223], v[46:49]
	v_mfma_f32_16x16x32_bf16 v[42:45], v[182:185], v[220:223], v[42:45]
	v_mfma_f32_16x16x32_bf16 v[30:33], v[174:177], v[228:231], v[30:33]
	v_mfma_f32_16x16x32_bf16 v[26:29], v[182:185], v[228:231], v[26:29]
	v_mfma_f32_16x16x32_bf16 v[14:17], v[174:177], v[236:239], v[14:17]
	v_mfma_f32_16x16x32_bf16 v[10:13], v[182:185], v[236:239], v[10:13]
	s_setprio 0
	s_setprio 1
	v_mfma_f32_16x16x32_bf16 v[54:57], v[192:195], v[208:211], v[54:57]
	v_mfma_f32_16x16x32_bf16 v[50:53], v[200:203], v[208:211], v[50:53]
	v_mfma_f32_16x16x32_bf16 v[38:41], v[192:195], v[216:219], v[38:41]
	v_mfma_f32_16x16x32_bf16 v[34:37], v[200:203], v[216:219], v[34:37]
	v_mfma_f32_16x16x32_bf16 v[22:25], v[192:195], v[224:227], v[22:25]
	v_mfma_f32_16x16x32_bf16 v[18:21], v[200:203], v[224:227], v[18:21]
	v_mfma_f32_16x16x32_bf16 v[6:9], v[192:195], v[232:235], v[6:9]
	v_mfma_f32_16x16x32_bf16 v[2:5], v[200:203], v[232:235], v[2:5]
	v_mfma_f32_16x16x32_bf16 v[54:57], v[196:199], v[212:215], v[54:57]
	v_mfma_f32_16x16x32_bf16 v[50:53], v[204:207], v[212:215], v[50:53]
	v_mfma_f32_16x16x32_bf16 v[38:41], v[196:199], v[220:223], v[38:41]
	v_mfma_f32_16x16x32_bf16 v[34:37], v[204:207], v[220:223], v[34:37]
	v_mfma_f32_16x16x32_bf16 v[22:25], v[196:199], v[228:231], v[22:25]
	v_mfma_f32_16x16x32_bf16 v[18:21], v[204:207], v[228:231], v[18:21]
	v_mfma_f32_16x16x32_bf16 v[6:9], v[196:199], v[236:239], v[6:9]
	v_mfma_f32_16x16x32_bf16 v[2:5], v[204:207], v[236:239], v[2:5]
	s_setprio 0
	s_barrier
	s_add_u32 s0, s0, 0x100
	s_addc_u32 s1, s1, 0
	s_add_u32 s10, s10, 0x100
	s_addc_u32 s11, s11, 0
	s_cmp_ge_i32 s40, s59
	s_mov_b32 s8, s40
	s_cbranch_scc0 .LBB0_308

; #define PG8_STAGE(bufoff, gbase, voff) do { _Pragma("unroll") for (int _i = 0; _i < 2; ++_i) \
;         __builtin_amdgcn_global_load_lds((const unsigned*)((const char*)(gbase) + (voff)[_i]), (PG8_LAS unsigned*)(lds + (bufoff) + ldsw + _i * 8192), 16, 0, 0); } while (0)
; #define PG8_LDA(dst, b, h) do { _Pragma("unroll") for (int m = 0; m < 4; ++m) _Pragma("unroll") for (int k = 0; k < 2; ++k) dst[m][k] = *(const PG8_LAS bf16x8*)(lds + PG8_SA(b, h) + aoff + m * 2048 + k * 1024); } while (0)
; #define PG8_LDB(dst, b, h) do { _Pragma("unroll") for (int n = 0; n < 2; ++n) _Pragma("unroll") for (int k = 0; k < 2; ++k) dst[n][k] = *(const PG8_LAS bf16x8*)(lds + PG8_SB(b, h) + boff + n * 2048 + k * 1024); } while (0)
; #define PG8_MMA(ai, bj, At, Bt) do { __builtin_amdgcn_s_setprio(1); _Pragma("unroll") for (int m = 0; m < 4; ++m) _Pragma("unroll") for (int n = 0; n < 2; ++n) _Pragma("unroll") for (int k = 0; k < 2; ++k) \
;         acc[ai][bj][m][n] = __builtin_amdgcn_mfma_f32_16x16x32_bf16(Bt[n][k], At[m][k], acc[ai][bj][m][n], 0, 0, 0); __builtin_amdgcn_s_setprio(0); } while (0)
; #define PG8_WAIT_V(n) asm volatile("s_waitcnt vmcnt(" #n ")" ::: "memory")
; #define PG8_WAIT_L(n) asm volatile("s_waitcnt lgkmcnt(" #n ")" ::: "memory")
; template <class Epi, class Sched, bool ALIGN_EPI = false, bool SP2 = false>
; __device__ __forceinline__ void gemm_phase(PG8_LAS unsigned char* lds, const Gemm g, const Sched& S, const Epi& E) {
;     ...
;             const bool last = (t == nt - 2);
;             const char* a1 = cA + (size_t)(t + 1) * kstep;
;             const char* a2 = last ? nA : cA + (size_t)(t + 2) * kstep; const char* b2 = last ? nB : cB + (size_t)(t + 2) * kstep;
;             const char* a3 = a2 + kstep; const char* b3 = b2 + kstep;
;             if (last && has_next) S.a_ready(nxt);
;             if constexpr (SP2) {
;             PG8_LDB(B0, 0, 0); PG8_LDB(B1, 0, 1); PG8_SCHED; PG8_LDA(At, 0, 0); PG8_STAGE(PG8_SA(1, 1), a1 + hstep, voffA);
;             PG8_WAIT_V(8); PG8_WAIT_L(0); PG8_BAR; PG8_MMA(0, 0, At, B0); PG8_MMA(0, 1, At, B1); PG8_BAR; PG8_SCHED;
;             PG8_LDA(At, 0, 1); PG8_STAGE(PG8_SB(0, 0), b2, voffB); PG8_STAGE(PG8_SB(0, 1), b2 + hstep, voffB); PG8_STAGE(PG8_SA(0, 0), a2, voffA);
;             PG8_WAIT_V(8); PG8_WAIT_L(0); PG8_BAR; PG8_MMA(1, 0, At, B0); PG8_MMA(1, 1, At, B1); PG8_BAR; PG8_SCHED;
.LBB0_376:
	s_add_i32 s40, s8, 2
	s_add_u32 s41, s0, 0x80
	s_addc_u32 s9, s1, 0
	s_add_i32 s86, 0, 0x10000
	s_cmp_eq_u32 s74, s8
	s_cselect_b32 s9, s35, s9
	s_cselect_b32 s8, s34, s41
	v_add_u32_e32 v146, s86, v148
	s_cselect_b32 s85, s37, s11
	s_cselect_b32 s84, s36, s10
	s_add_i32 s41, 0, 0x14000
	ds_read_b128 v[142:145], v146
	ds_read_b128 v[174:177], v146 offset:1024
	ds_read_b128 v[178:181], v146 offset:2048
	ds_read_b128 v[182:185], v146 offset:3072
	v_add_u32_e32 v146, s41, v148
	ds_read_b128 v[192:195], v146
	ds_read_b128 v[196:199], v146 offset:1024
	ds_read_b128 v[200:203], v146 offset:2048
	ds_read_b128 v[204:207], v146 offset:3072
	v_lshl_add_u64 v[166:167], s[0:1], 0, v[138:139]
	s_add_i32 m0, s45, 0xc000
	ds_read_b128 v[208:211], v173
	ds_read_b128 v[212:215], v173 offset:1024
	ds_read_b128 v[216:219], v173 offset:2048
	ds_read_b128 v[220:223], v173 offset:3072
	ds_read_b128 v[224:227], v173 offset:4096
	ds_read_b128 v[228:231], v173 offset:5120
	ds_read_b128 v[232:235], v173 offset:6144
	ds_read_b128 v[236:239], v173 offset:7168
	global_load_lds_dwordx4 v[166:167], off
	v_lshl_add_u64 v[166:167], s[0:1], 0, v[140:141]
	s_add_i32 m0, s45, 0xe000
	s_nop 0
	global_load_lds_dwordx4 v[166:167], off
	s_waitcnt vmcnt(8)
	s_waitcnt lgkmcnt(0)
	s_barrier
	s_setprio 1
	s_waitcnt lgkmcnt(0)
	v_mfma_f32_16x16x32_bf16 v[122:125], v[142:145], v[208:211], v[122:125]
	v_mfma_f32_16x16x32_bf16 v[118:121], v[178:181], v[208:211], v[118:121]
	v_mfma_f32_16x16x32_bf16 v[110:113], v[142:145], v[216:219], v[110:113]
	v_mfma_f32_16x16x32_bf16 v[102:105], v[178:181], v[216:219], v[102:105]
	v_mfma_f32_16x16x32_bf16 v[94:97], v[142:145], v[224:227], v[94:97]
	v_mfma_f32_16x16x32_bf16 v[86:89], v[178:181], v[224:227], v[86:89]
	v_mfma_f32_16x16x32_bf16 v[78:81], v[142:145], v[232:235], v[78:81]
	v_mfma_f32_16x16x32_bf16 v[70:73], v[178:181], v[232:235], v[70:73]
	v_mfma_f32_16x16x32_bf16 v[122:125], v[174:177], v[212:215], v[122:125]
	v_mfma_f32_16x16x32_bf16 v[118:121], v[182:185], v[212:215], v[118:121]
	v_mfma_f32_16x16x32_bf16 v[110:113], v[174:177], v[220:223], v[110:113]
	v_mfma_f32_16x16x32_bf16 v[102:105], v[182:185], v[220:223], v[102:105]
	v_mfma_f32_16x16x32_bf16 v[94:97], v[174:177], v[228:231], v[94:97]
	v_mfma_f32_16x16x32_bf16 v[86:89], v[182:185], v[228:231], v[86:89]
	v_mfma_f32_16x16x32_bf16 v[78:81], v[174:177], v[236:239], v[78:81]
	v_mfma_f32_16x16x32_bf16 v[70:73], v[182:185], v[236:239], v[70:73]
	s_setprio 0
	s_setprio 1
	v_mfma_f32_16x16x32_bf16 v[126:129], v[192:195], v[208:211], v[126:129]
	v_mfma_f32_16x16x32_bf16 v[114:117], v[200:203], v[208:211], v[114:117]
	v_mfma_f32_16x16x32_bf16 v[106:109], v[192:195], v[216:219], v[106:109]
	v_mfma_f32_16x16x32_bf16 v[98:101], v[200:203], v[216:219], v[98:101]
	v_mfma_f32_16x16x32_bf16 v[90:93], v[192:195], v[224:227], v[90:93]
	v_mfma_f32_16x16x32_bf16 v[82:85], v[200:203], v[224:227], v[82:85]
	v_mfma_f32_16x16x32_bf16 v[74:77], v[192:195], v[232:235], v[74:77]
	v_mfma_f32_16x16x32_bf16 v[66:69], v[200:203], v[232:235], v[66:69]
	v_mfma_f32_16x16x32_bf16 v[126:129], v[196:199], v[212:215], v[126:129]
	v_mfma_f32_16x16x32_bf16 v[114:117], v[204:207], v[212:215], v[114:117]
	v_mfma_f32_16x16x32_bf16 v[106:109], v[196:199], v[220:223], v[106:109]
	v_mfma_f32_16x16x32_bf16 v[98:101], v[204:207], v[220:223], v[98:101]
	v_mfma_f32_16x16x32_bf16 v[90:93], v[196:199], v[228:231], v[90:93]
	v_mfma_f32_16x16x32_bf16 v[82:85], v[204:207], v[228:231], v[82:85]
	v_mfma_f32_16x16x32_bf16 v[74:77], v[196:199], v[236:239], v[74:77]
	v_mfma_f32_16x16x32_bf16 v[66:69], v[204:207], v[236:239], v[66:69]
	s_setprio 0
	s_barrier
	s_add_i32 s86, s86, s4
	v_lshl_add_u64 v[166:167], s[84:85], 0, v[160:161]
	s_mov_b32 m0, s86
	ds_read_b128 v[208:211], v173 offset:16384
	ds_read_b128 v[212:215], v173 offset:17408
	ds_read_b128 v[216:219], v173 offset:18432
	ds_read_b128 v[220:223], v173 offset:19456
	ds_read_b128 v[224:227], v173 offset:20480
	ds_read_b128 v[228:231], v173 offset:21504
	ds_read_b128 v[232:235], v173 offset:22528
	ds_read_b128 v[236:239], v173 offset:23552
	global_load_lds_dwordx4 v[166:167], off
	s_add_i32 m0, s86, 0x2000
	v_lshl_add_u64 v[240:241], s[84:85], 0, v[134:135]
	s_add_u32 s84, s84, s14
	s_addc_u32 s85, s85, s15
	s_add_i32 s41, s41, s4
	global_load_lds_dwordx4 v[240:241], off
	v_lshl_add_u64 v[242:243], s[84:85], 0, v[160:161]
	s_mov_b32 m0, s41
	v_lshl_add_u64 v[244:245], s[84:85], 0, v[134:135]
	global_load_lds_dwordx4 v[242:243], off
	s_add_i32 m0, s41, 0x2000
	v_lshl_add_u64 v[246:247], s[8:9], 0, v[130:131]
	global_load_lds_dwordx4 v[244:245], off
	v_lshl_add_u64 v[248:249], s[8:9], 0, v[132:133]
	s_nop 0
	s_waitcnt vmcnt(6)
	s_waitcnt lgkmcnt(0)
	s_barrier
; #define PG8_STAGE(bufoff, gbase, voff) do { _Pragma("unroll") for (int _i = 0; _i < 2; ++_i) \
;         __builtin_amdgcn_global_load_lds((const unsigned*)((const char*)(gbase) + (voff)[_i]), (PG8_LAS unsigned*)(lds + (bufoff) + ldsw + _i * 8192), 16, 0, 0); } while (0)
; #define PG8_LDA(dst, b, h) do { _Pragma("unroll") for (int m = 0; m < 4; ++m) _Pragma("unroll") for (int k = 0; k < 2; ++k) dst[m][k] = *(const PG8_LAS bf16x8*)(lds + PG8_SA(b, h) + aoff + m * 2048 + k * 1024); } while (0)
; #define PG8_LDB(dst, b, h) do { _Pragma("unroll") for (int n = 0; n < 2; ++n) _Pragma("unroll") for (int k = 0; k < 2; ++k) dst[n][k] = *(const PG8_LAS bf16x8*)(lds + PG8_SB(b, h) + boff + n * 2048 + k * 1024); } while (0)
; #define PG8_MMA(ai, bj, At, Bt) do { __builtin_amdgcn_s_setprio(1); _Pragma("unroll") for (int m = 0; m < 4; ++m) _Pragma("unroll") for (int n = 0; n < 2; ++n) _Pragma("unroll") for (int k = 0; k < 2; ++k) \
;         acc[ai][bj][m][n] = __builtin_amdgcn_mfma_f32_16x16x32_bf16(Bt[n][k], At[m][k], acc[ai][bj][m][n], 0, 0, 0); __builtin_amdgcn_s_setprio(0); } while (0)
; #define PG8_WAIT_V(n) asm volatile("s_waitcnt vmcnt(" #n ")" ::: "memory")
; #define PG8_WAIT_L(n) asm volatile("s_waitcnt lgkmcnt(" #n ")" ::: "memory")
; #define PG8_BAR __builtin_amdgcn_s_barrier()
; #define PG8_SCHED __builtin_amdgcn_sched_barrier(0)
; template <class Epi, class Sched, bool ALIGN_EPI = false, bool SP2 = false>
; __device__ __forceinline__ void gemm_phase(PG8_LAS unsigned char* lds, const Gemm g, const Sched& S, const Epi& E) {
;     ...
;             PG8_WAIT_V(8); PG8_WAIT_L(0); PG8_BAR; PG8_MMA(1, 0, At, B0); PG8_MMA(1, 1, At, B1); PG8_BAR; PG8_SCHED;
;             PG8_LDB(B0, 1, 0); PG8_LDB(B1, 1, 1); PG8_SCHED; PG8_LDA(At, 1, 0); PG8_STAGE(PG8_SA(0, 1), a2 + hstep, voffA);
;             PG8_WAIT_V(8); PG8_WAIT_L(0); PG8_BAR; PG8_MMA(0, 0, At, B0); PG8_MMA(0, 1, At, B1); PG8_BAR; PG8_SCHED;
	s_setprio 1
	s_waitcnt lgkmcnt(0)
	v_mfma_f32_16x16x32_bf16 v[62:65], v[142:145], v[208:211], v[62:65]
	v_mfma_f32_16x16x32_bf16 v[54:57], v[178:181], v[208:211], v[54:57]
	v_mfma_f32_16x16x32_bf16 v[46:49], v[142:145], v[216:219], v[46:49]
	v_mfma_f32_16x16x32_bf16 v[38:41], v[178:181], v[216:219], v[38:41]
	v_mfma_f32_16x16x32_bf16 v[30:33], v[142:145], v[224:227], v[30:33]
	v_mfma_f32_16x16x32_bf16 v[22:25], v[178:181], v[224:227], v[22:25]
	v_mfma_f32_16x16x32_bf16 v[14:17], v[142:145], v[232:235], v[14:17]
	v_mfma_f32_16x16x32_bf16 v[6:9], v[178:181], v[232:235], v[6:9]
	v_mfma_f32_16x16x32_bf16 v[62:65], v[174:177], v[212:215], v[62:65]
	v_mfma_f32_16x16x32_bf16 v[54:57], v[182:185], v[212:215], v[54:57]
	v_mfma_f32_16x16x32_bf16 v[46:49], v[174:177], v[220:223], v[46:49]
	v_mfma_f32_16x16x32_bf16 v[38:41], v[182:185], v[220:223], v[38:41]
	v_mfma_f32_16x16x32_bf16 v[30:33], v[174:177], v[228:231], v[30:33]
	v_mfma_f32_16x16x32_bf16 v[22:25], v[182:185], v[228:231], v[22:25]
	v_mfma_f32_16x16x32_bf16 v[14:17], v[174:177], v[236:239], v[14:17]
	v_mfma_f32_16x16x32_bf16 v[6:9], v[182:185], v[236:239], v[6:9]
	s_setprio 0
	s_setprio 1
	v_mfma_f32_16x16x32_bf16 v[58:61], v[192:195], v[208:211], v[58:61]
	v_mfma_f32_16x16x32_bf16 v[50:53], v[200:203], v[208:211], v[50:53]
	v_mfma_f32_16x16x32_bf16 v[42:45], v[192:195], v[216:219], v[42:45]
	v_mfma_f32_16x16x32_bf16 v[34:37], v[200:203], v[216:219], v[34:37]
	v_mfma_f32_16x16x32_bf16 v[26:29], v[192:195], v[224:227], v[26:29]
	v_mfma_f32_16x16x32_bf16 v[18:21], v[200:203], v[224:227], v[18:21]
	v_mfma_f32_16x16x32_bf16 v[10:13], v[192:195], v[232:235], v[10:13]
	v_mfma_f32_16x16x32_bf16 v[2:5], v[200:203], v[232:235], v[2:5]
	v_mfma_f32_16x16x32_bf16 v[58:61], v[196:199], v[212:215], v[58:61]
	v_mfma_f32_16x16x32_bf16 v[50:53], v[204:207], v[212:215], v[50:53]
	v_mfma_f32_16x16x32_bf16 v[42:45], v[196:199], v[220:223], v[42:45]
	v_mfma_f32_16x16x32_bf16 v[34:37], v[204:207], v[220:223], v[34:37]
	v_mfma_f32_16x16x32_bf16 v[26:29], v[196:199], v[228:231], v[26:29]
	v_mfma_f32_16x16x32_bf16 v[18:21], v[204:207], v[228:231], v[18:21]
	v_mfma_f32_16x16x32_bf16 v[10:13], v[196:199], v[236:239], v[10:13]
	v_mfma_f32_16x16x32_bf16 v[2:5], v[204:207], v[236:239], v[2:5]
	s_setprio 0
	s_barrier
	s_add_i32 s41, 0, 0x18000
	v_add_u32_e32 v146, s41, v148
	s_add_i32 s84, 0, 0x1c000
	ds_read_b128 v[142:145], v146
	ds_read_b128 v[174:177], v146 offset:1024
	ds_read_b128 v[178:181], v146 offset:2048
	ds_read_b128 v[182:185], v146 offset:3072
	v_add_u32_e32 v146, s84, v148
	ds_read_b128 v[192:195], v146
	ds_read_b128 v[196:199], v146 offset:1024
	ds_read_b128 v[200:203], v146 offset:2048
	ds_read_b128 v[204:207], v146 offset:3072
	s_add_u32 s8, s8, s14
	s_addc_u32 s9, s9, s15
	s_mov_b32 m0, s45
	s_nop 0
	global_load_lds_dwordx4 v[246:247], off
	s_mov_b32 m0, s48
	s_nop 0
	global_load_lds_dwordx4 v[248:249], off
	s_mov_b32 m0, s49
	v_lshl_add_u64 v[250:251], s[8:9], 0, v[130:131]
	ds_read_b128 v[208:211], v173 offset:32768
	ds_read_b128 v[212:215], v173 offset:33792
	ds_read_b128 v[216:219], v173 offset:34816
	ds_read_b128 v[220:223], v173 offset:35840
	ds_read_b128 v[224:227], v173 offset:36864
	ds_read_b128 v[228:231], v173 offset:37888
	ds_read_b128 v[232:235], v173 offset:38912
	ds_read_b128 v[236:239], v173 offset:39936
	global_load_lds_dwordx4 v[250:251], off
	v_lshl_add_u64 v[250:251], s[8:9], 0, v[132:133]
	s_mov_b32 m0, s51
	s_nop 0
	global_load_lds_dwordx4 v[250:251], off
	s_waitcnt vmcnt(8)
	s_waitcnt lgkmcnt(0)
	s_barrier
	s_setprio 1
	s_waitcnt lgkmcnt(0)
	v_mfma_f32_16x16x32_bf16 v[122:125], v[142:145], v[208:211], v[122:125]
	v_mfma_f32_16x16x32_bf16 v[118:121], v[178:181], v[208:211], v[118:121]
	v_mfma_f32_16x16x32_bf16 v[110:113], v[142:145], v[216:219], v[110:113]
	v_mfma_f32_16x16x32_bf16 v[102:105], v[178:181], v[216:219], v[102:105]
	v_mfma_f32_16x16x32_bf16 v[94:97], v[142:145], v[224:227], v[94:97]
	v_mfma_f32_16x16x32_bf16 v[86:89], v[178:181], v[224:227], v[86:89]
	v_mfma_f32_16x16x32_bf16 v[78:81], v[142:145], v[232:235], v[78:81]
	v_mfma_f32_16x16x32_bf16 v[70:73], v[178:181], v[232:235], v[70:73]
	v_mfma_f32_16x16x32_bf16 v[122:125], v[174:177], v[212:215], v[122:125]
	v_mfma_f32_16x16x32_bf16 v[118:121], v[182:185], v[212:215], v[118:121]
	v_mfma_f32_16x16x32_bf16 v[110:113], v[174:177], v[220:223], v[110:113]
	v_mfma_f32_16x16x32_bf16 v[102:105], v[182:185], v[220:223], v[102:105]
	v_mfma_f32_16x16x32_bf16 v[94:97], v[174:177], v[228:231], v[94:97]
	v_mfma_f32_16x16x32_bf16 v[86:89], v[182:185], v[228:231], v[86:89]
	v_mfma_f32_16x16x32_bf16 v[78:81], v[174:177], v[236:239], v[78:81]
	v_mfma_f32_16x16x32_bf16 v[70:73], v[182:185], v[236:239], v[70:73]
	s_setprio 0
	s_setprio 1
	v_mfma_f32_16x16x32_bf16 v[126:129], v[192:195], v[208:211], v[126:129]
	v_mfma_f32_16x16x32_bf16 v[114:117], v[200:203], v[208:211], v[114:117]
	v_mfma_f32_16x16x32_bf16 v[106:109], v[192:195], v[216:219], v[106:109]
	v_mfma_f32_16x16x32_bf16 v[98:101], v[200:203], v[216:219], v[98:101]
	v_mfma_f32_16x16x32_bf16 v[90:93], v[192:195], v[224:227], v[90:93]
	v_mfma_f32_16x16x32_bf16 v[82:85], v[200:203], v[224:227], v[82:85]
	v_mfma_f32_16x16x32_bf16 v[74:77], v[192:195], v[232:235], v[74:77]
	v_mfma_f32_16x16x32_bf16 v[66:69], v[200:203], v[232:235], v[66:69]
	v_mfma_f32_16x16x32_bf16 v[126:129], v[196:199], v[212:215], v[126:129]
	v_mfma_f32_16x16x32_bf16 v[114:117], v[204:207], v[212:215], v[114:117]
	v_mfma_f32_16x16x32_bf16 v[106:109], v[196:199], v[220:223], v[106:109]
	v_mfma_f32_16x16x32_bf16 v[98:101], v[204:207], v[220:223], v[98:101]
	v_mfma_f32_16x16x32_bf16 v[90:93], v[196:199], v[228:231], v[90:93]
	v_mfma_f32_16x16x32_bf16 v[82:85], v[204:207], v[228:231], v[82:85]
	v_mfma_f32_16x16x32_bf16 v[74:77], v[196:199], v[236:239], v[74:77]
	v_mfma_f32_16x16x32_bf16 v[66:69], v[204:207], v[236:239], v[66:69]
	s_setprio 0
	s_barrier
; #define PG8_STAGE(bufoff, gbase, voff) do { _Pragma("unroll") for (int _i = 0; _i < 2; ++_i) \
;         __builtin_amdgcn_global_load_lds((const unsigned*)((const char*)(gbase) + (voff)[_i]), (PG8_LAS unsigned*)(lds + (bufoff) + ldsw + _i * 8192), 16, 0, 0); } while (0)
; #define PG8_LDA(dst, b, h) do { _Pragma("unroll") for (int m = 0; m < 4; ++m) _Pragma("unroll") for (int k = 0; k < 2; ++k) dst[m][k] = *(const PG8_LAS bf16x8*)(lds + PG8_SA(b, h) + aoff + m * 2048 + k * 1024); } while (0)
; #define PG8_MMA(ai, bj, At, Bt) do { __builtin_amdgcn_s_setprio(1); _Pragma("unroll") for (int m = 0; m < 4; ++m) _Pragma("unroll") for (int n = 0; n < 2; ++n) _Pragma("unroll") for (int k = 0; k < 2; ++k) \
;         acc[ai][bj][m][n] = __builtin_amdgcn_mfma_f32_16x16x32_bf16(Bt[n][k], At[m][k], acc[ai][bj][m][n], 0, 0, 0); __builtin_amdgcn_s_setprio(0); } while (0)
; #define PG8_WAIT_V(n) asm volatile("s_waitcnt vmcnt(" #n ")" ::: "memory")
; #define PG8_WAIT_L(n) asm volatile("s_waitcnt lgkmcnt(" #n ")" ::: "memory")
; #define PG8_BAR __builtin_amdgcn_s_barrier()
; #define PG8_SCHED __builtin_amdgcn_sched_barrier(0)
; template <class Epi, class Sched, bool ALIGN_EPI = false, bool SP2 = false>
; __device__ __forceinline__ void gemm_phase(PG8_LAS unsigned char* lds, const Gemm g, const Sched& S, const Epi& E) {
;     ...
;         for (int t = 0; t < nt; t += 2) {
;     ...
;             PG8_LDA(At, 1, 1); PG8_STAGE(PG8_SB(1, 0), b3, voffB); PG8_STAGE(PG8_SB(1, 1), b3 + hstep, voffB); PG8_STAGE(PG8_SA(1, 0), a3, voffA);
;             PG8_WAIT_V(8); PG8_WAIT_L(0); PG8_BAR; PG8_MMA(1, 0, At, B0); PG8_MMA(1, 1, At, B1); PG8_BAR; PG8_SCHED;
	s_add_i32 s8, s41, s4
	v_lshl_add_u64 v[166:167], v[166:167], 0, s[88:89]
	s_mov_b32 m0, s8
	ds_read_b128 v[208:211], v173 offset:49152
	ds_read_b128 v[212:215], v173 offset:50176
	ds_read_b128 v[216:219], v173 offset:51200
	ds_read_b128 v[220:223], v173 offset:52224
	ds_read_b128 v[224:227], v173 offset:53248
	ds_read_b128 v[228:231], v173 offset:54272
	ds_read_b128 v[232:235], v173 offset:55296
	ds_read_b128 v[236:239], v173 offset:56320
	global_load_lds_dwordx4 v[166:167], off
	v_lshl_add_u64 v[166:167], v[240:241], 0, s[88:89]
	s_add_i32 m0, s8, 0x2000
	s_add_i32 s8, s84, s4
	global_load_lds_dwordx4 v[166:167], off
	v_lshl_add_u64 v[166:167], v[242:243], 0, s[88:89]
	s_mov_b32 m0, s8
	s_nop 0
	global_load_lds_dwordx4 v[166:167], off
	v_lshl_add_u64 v[166:167], v[244:245], 0, s[88:89]
	s_add_i32 m0, s8, 0x2000
	s_nop 0
	global_load_lds_dwordx4 v[166:167], off
	v_lshl_add_u64 v[166:167], v[246:247], 0, s[88:89]
	s_mov_b32 m0, s52
	s_nop 0
	global_load_lds_dwordx4 v[166:167], off
	v_lshl_add_u64 v[166:167], v[248:249], 0, s[88:89]
	s_mov_b32 m0, s53
	s_nop 0
	global_load_lds_dwordx4 v[166:167], off
	s_waitcnt vmcnt(8)
	s_waitcnt lgkmcnt(0)
	s_barrier
	s_setprio 1
	s_waitcnt lgkmcnt(0)
	v_mfma_f32_16x16x32_bf16 v[62:65], v[142:145], v[208:211], v[62:65]
	v_mfma_f32_16x16x32_bf16 v[54:57], v[178:181], v[208:211], v[54:57]
	v_mfma_f32_16x16x32_bf16 v[46:49], v[142:145], v[216:219], v[46:49]
	v_mfma_f32_16x16x32_bf16 v[38:41], v[178:181], v[216:219], v[38:41]
	v_mfma_f32_16x16x32_bf16 v[30:33], v[142:145], v[224:227], v[30:33]
	v_mfma_f32_16x16x32_bf16 v[22:25], v[178:181], v[224:227], v[22:25]
	v_mfma_f32_16x16x32_bf16 v[14:17], v[142:145], v[232:235], v[14:17]
	v_mfma_f32_16x16x32_bf16 v[6:9], v[178:181], v[232:235], v[6:9]
	v_mfma_f32_16x16x32_bf16 v[62:65], v[174:177], v[212:215], v[62:65]
	v_mfma_f32_16x16x32_bf16 v[54:57], v[182:185], v[212:215], v[54:57]
	v_mfma_f32_16x16x32_bf16 v[46:49], v[174:177], v[220:223], v[46:49]
	v_mfma_f32_16x16x32_bf16 v[38:41], v[182:185], v[220:223], v[38:41]
	v_mfma_f32_16x16x32_bf16 v[30:33], v[174:177], v[228:231], v[30:33]
	v_mfma_f32_16x16x32_bf16 v[22:25], v[182:185], v[228:231], v[22:25]
	v_mfma_f32_16x16x32_bf16 v[14:17], v[174:177], v[236:239], v[14:17]
	v_mfma_f32_16x16x32_bf16 v[6:9], v[182:185], v[236:239], v[6:9]
	s_setprio 0
	s_setprio 1
	v_mfma_f32_16x16x32_bf16 v[58:61], v[192:195], v[208:211], v[58:61]
	v_mfma_f32_16x16x32_bf16 v[50:53], v[200:203], v[208:211], v[50:53]
	v_mfma_f32_16x16x32_bf16 v[42:45], v[192:195], v[216:219], v[42:45]
	v_mfma_f32_16x16x32_bf16 v[34:37], v[200:203], v[216:219], v[34:37]
	v_mfma_f32_16x16x32_bf16 v[26:29], v[192:195], v[224:227], v[26:29]
	v_mfma_f32_16x16x32_bf16 v[18:21], v[200:203], v[224:227], v[18:21]
	v_mfma_f32_16x16x32_bf16 v[10:13], v[192:195], v[232:235], v[10:13]
	v_mfma_f32_16x16x32_bf16 v[2:5], v[200:203], v[232:235], v[2:5]
	v_mfma_f32_16x16x32_bf16 v[58:61], v[196:199], v[212:215], v[58:61]
	v_mfma_f32_16x16x32_bf16 v[50:53], v[204:207], v[212:215], v[50:53]
	v_mfma_f32_16x16x32_bf16 v[42:45], v[196:199], v[220:223], v[42:45]
	v_mfma_f32_16x16x32_bf16 v[34:37], v[204:207], v[220:223], v[34:37]
	v_mfma_f32_16x16x32_bf16 v[26:29], v[196:199], v[228:231], v[26:29]
	v_mfma_f32_16x16x32_bf16 v[18:21], v[204:207], v[228:231], v[18:21]
	v_mfma_f32_16x16x32_bf16 v[10:13], v[196:199], v[236:239], v[10:13]
	v_mfma_f32_16x16x32_bf16 v[2:5], v[204:207], v[236:239], v[2:5]
	s_setprio 0
	s_barrier
	s_add_u32 s0, s0, 0x100
	s_addc_u32 s1, s1, 0
	s_add_u32 s10, s10, 0x100
	s_addc_u32 s11, s11, 0
	s_cmp_ge_i32 s40, s56
	s_mov_b32 s8, s40
	s_cbranch_scc0 .LBB0_376

; #define PG8_STAGE(bufoff, gbase, voff) do { _Pragma("unroll") for (int _i = 0; _i < 2; ++_i) \
;         __builtin_amdgcn_global_load_lds((const unsigned*)((const char*)(gbase) + (voff)[_i]), (PG8_LAS unsigned*)(lds + (bufoff) + ldsw + _i * 8192), 16, 0, 0); } while (0)
; #define PG8_LDA(dst, b, h) do { _Pragma("unroll") for (int m = 0; m < 4; ++m) _Pragma("unroll") for (int k = 0; k < 2; ++k) dst[m][k] = *(const PG8_LAS bf16x8*)(lds + PG8_SA(b, h) + aoff + m * 2048 + k * 1024); } while (0)
; #define PG8_LDB(dst, b, h) do { _Pragma("unroll") for (int n = 0; n < 2; ++n) _Pragma("unroll") for (int k = 0; k < 2; ++k) dst[n][k] = *(const PG8_LAS bf16x8*)(lds + PG8_SB(b, h) + boff + n * 2048 + k * 1024); } while (0)
; #define PG8_MMA(ai, bj, At, Bt) do { __builtin_amdgcn_s_setprio(1); _Pragma("unroll") for (int m = 0; m < 4; ++m) _Pragma("unroll") for (int n = 0; n < 2; ++n) _Pragma("unroll") for (int k = 0; k < 2; ++k) \
;         acc[ai][bj][m][n] = __builtin_amdgcn_mfma_f32_16x16x32_bf16(Bt[n][k], At[m][k], acc[ai][bj][m][n], 0, 0, 0); __builtin_amdgcn_s_setprio(0); } while (0)
; #define PG8_WAIT_V(n) asm volatile("s_waitcnt vmcnt(" #n ")" ::: "memory")
; #define PG8_WAIT_L(n) asm volatile("s_waitcnt lgkmcnt(" #n ")" ::: "memory")
; template <class Epi, class Sched, bool ALIGN_EPI = false, bool SP2 = false>
; __device__ __forceinline__ void gemm_phase(PG8_LAS unsigned char* lds, const Gemm g, const Sched& S, const Epi& E) {
;     ...
;             const bool last = (t == nt - 2);
;             const char* a1 = cA + (size_t)(t + 1) * kstep;
;             const char* a2 = last ? nA : cA + (size_t)(t + 2) * kstep; const char* b2 = last ? nB : cB + (size_t)(t + 2) * kstep;
;             const char* a3 = a2 + kstep; const char* b3 = b2 + kstep;
;             if (last && has_next) S.a_ready(nxt);
;             if constexpr (SP2) {
;             PG8_LDB(B0, 0, 0); PG8_LDB(B1, 0, 1); PG8_SCHED; PG8_LDA(At, 0, 0); PG8_STAGE(PG8_SA(1, 1), a1 + hstep, voffA);
;             PG8_WAIT_V(8); PG8_WAIT_L(0); PG8_BAR; PG8_MMA(0, 0, At, B0); PG8_MMA(0, 1, At, B1); PG8_BAR; PG8_SCHED;
;             PG8_LDA(At, 0, 1); PG8_STAGE(PG8_SB(0, 0), b2, voffB); PG8_STAGE(PG8_SB(0, 1), b2 + hstep, voffB); PG8_STAGE(PG8_SA(0, 0), a2, voffA);
;             PG8_WAIT_V(8); PG8_WAIT_L(0); PG8_BAR; PG8_MMA(1, 0, At, B0); PG8_MMA(1, 1, At, B1); PG8_BAR; PG8_SCHED;
.LBB0_441:
	s_add_i32 s79, s10, 2
	s_add_u32 s80, s34, 0x80
	s_addc_u32 s11, s35, 0
	s_add_i32 s83, 0, 0x10000
	s_cmp_eq_u32 s50, s10
	s_cselect_b32 s11, s1, s11
	s_cselect_b32 s10, s0, s80
	s_cselect_b32 s81, s31, s78
	s_cselect_b32 s80, s30, s75
	s_add_i32 s84, 0, 0x14000
	s_waitcnt vmcnt(0)
	v_add_u32_e32 v156, s83, v141
	v_add_u32_e32 v166, s84, v141
	ds_read_b128 v[144:147], v156
	ds_read_b128 v[148:151], v156 offset:1024
	ds_read_b128 v[152:155], v156 offset:2048
	ds_read_b128 v[156:159], v156 offset:3072
	ds_read_b128 v[168:171], v166
	ds_read_b128 v[172:175], v166 offset:1024
	ds_read_b128 v[176:179], v166 offset:2048
	ds_read_b128 v[180:183], v166 offset:3072
	v_lshl_add_u64 v[166:167], s[34:35], 0, v[136:137]
	s_add_i32 m0, s41, 0xc000
	ds_read_b128 v[192:195], v143
	ds_read_b128 v[196:199], v143 offset:1024
	ds_read_b128 v[200:203], v143 offset:2048
	ds_read_b128 v[204:207], v143 offset:3072
	ds_read_b128 v[208:211], v143 offset:4096
	ds_read_b128 v[212:215], v143 offset:5120
	ds_read_b128 v[216:219], v143 offset:6144
	ds_read_b128 v[220:223], v143 offset:7168
	global_load_lds_dwordx4 v[166:167], off
	v_lshl_add_u64 v[166:167], s[34:35], 0, v[138:139]
	s_add_i32 m0, s41, 0xe000
	s_nop 0
	global_load_lds_dwordx4 v[166:167], off
	s_waitcnt vmcnt(8)
	s_waitcnt lgkmcnt(0)
	s_barrier
	s_setprio 1
	s_waitcnt lgkmcnt(0)
	v_mfma_f32_16x16x32_bf16 v[122:125], v[144:147], v[192:195], v[122:125]
	v_mfma_f32_16x16x32_bf16 v[126:129], v[152:155], v[192:195], v[126:129]
	v_mfma_f32_16x16x32_bf16 v[110:113], v[144:147], v[200:203], v[110:113]
	v_mfma_f32_16x16x32_bf16 v[106:109], v[152:155], v[200:203], v[106:109]
	v_mfma_f32_16x16x32_bf16 v[94:97], v[144:147], v[208:211], v[94:97]
	v_mfma_f32_16x16x32_bf16 v[90:93], v[152:155], v[208:211], v[90:93]
	v_mfma_f32_16x16x32_bf16 v[78:81], v[144:147], v[216:219], v[78:81]
	v_mfma_f32_16x16x32_bf16 v[74:77], v[152:155], v[216:219], v[74:77]
	v_mfma_f32_16x16x32_bf16 v[122:125], v[148:151], v[196:199], v[122:125]
	v_mfma_f32_16x16x32_bf16 v[126:129], v[156:159], v[196:199], v[126:129]
	v_mfma_f32_16x16x32_bf16 v[110:113], v[148:151], v[204:207], v[110:113]
	v_mfma_f32_16x16x32_bf16 v[106:109], v[156:159], v[204:207], v[106:109]
	v_mfma_f32_16x16x32_bf16 v[94:97], v[148:151], v[212:215], v[94:97]
	v_mfma_f32_16x16x32_bf16 v[90:93], v[156:159], v[212:215], v[90:93]
	v_mfma_f32_16x16x32_bf16 v[78:81], v[148:151], v[220:223], v[78:81]
	v_mfma_f32_16x16x32_bf16 v[74:77], v[156:159], v[220:223], v[74:77]
	s_setprio 0
	s_setprio 1
	v_mfma_f32_16x16x32_bf16 v[118:121], v[168:171], v[192:195], v[118:121]
	v_mfma_f32_16x16x32_bf16 v[114:117], v[176:179], v[192:195], v[114:117]
	v_mfma_f32_16x16x32_bf16 v[102:105], v[168:171], v[200:203], v[102:105]
	v_mfma_f32_16x16x32_bf16 v[98:101], v[176:179], v[200:203], v[98:101]
	v_mfma_f32_16x16x32_bf16 v[86:89], v[168:171], v[208:211], v[86:89]
	v_mfma_f32_16x16x32_bf16 v[82:85], v[176:179], v[208:211], v[82:85]
	v_mfma_f32_16x16x32_bf16 v[70:73], v[168:171], v[216:219], v[70:73]
	v_mfma_f32_16x16x32_bf16 v[66:69], v[176:179], v[216:219], v[66:69]
	v_mfma_f32_16x16x32_bf16 v[118:121], v[172:175], v[196:199], v[118:121]
	v_mfma_f32_16x16x32_bf16 v[114:117], v[180:183], v[196:199], v[114:117]
	v_mfma_f32_16x16x32_bf16 v[102:105], v[172:175], v[204:207], v[102:105]
	v_mfma_f32_16x16x32_bf16 v[98:101], v[180:183], v[204:207], v[98:101]
	v_mfma_f32_16x16x32_bf16 v[86:89], v[172:175], v[212:215], v[86:89]
	v_mfma_f32_16x16x32_bf16 v[82:85], v[180:183], v[212:215], v[82:85]
	v_mfma_f32_16x16x32_bf16 v[70:73], v[172:175], v[220:223], v[70:73]
	v_mfma_f32_16x16x32_bf16 v[66:69], v[180:183], v[220:223], v[66:69]
	s_setprio 0
	s_barrier
	s_add_i32 s83, s83, s40
	v_lshl_add_u64 v[166:167], s[80:81], 0, v[160:161]
	s_mov_b32 m0, s83
	ds_read_b128 v[192:195], v143 offset:16384
	ds_read_b128 v[196:199], v143 offset:17408
	ds_read_b128 v[200:203], v143 offset:18432
	ds_read_b128 v[204:207], v143 offset:19456
	ds_read_b128 v[208:211], v143 offset:20480
	ds_read_b128 v[212:215], v143 offset:21504
	ds_read_b128 v[216:219], v143 offset:22528
	ds_read_b128 v[220:223], v143 offset:23552
	global_load_lds_dwordx4 v[166:167], off
	s_add_i32 m0, s83, 0x2000
	v_lshl_add_u64 v[184:185], s[80:81], 0, v[134:135]
	s_add_u32 s80, s80, s8
	s_addc_u32 s81, s81, s9
	s_add_i32 s83, s84, s40
	global_load_lds_dwordx4 v[184:185], off
	v_lshl_add_u64 v[224:225], s[80:81], 0, v[160:161]
	s_mov_b32 m0, s83
	v_lshl_add_u64 v[226:227], s[80:81], 0, v[134:135]
	global_load_lds_dwordx4 v[224:225], off
	s_add_i32 m0, s83, 0x2000
	v_lshl_add_u64 v[228:229], s[10:11], 0, v[130:131]
	global_load_lds_dwordx4 v[226:227], off
	v_lshl_add_u64 v[230:231], s[10:11], 0, v[132:133]
	s_nop 0
	s_waitcnt vmcnt(6)
	s_waitcnt lgkmcnt(0)
	s_barrier
; #define PG8_STAGE(bufoff, gbase, voff) do { _Pragma("unroll") for (int _i = 0; _i < 2; ++_i) \
;         __builtin_amdgcn_global_load_lds((const unsigned*)((const char*)(gbase) + (voff)[_i]), (PG8_LAS unsigned*)(lds + (bufoff) + ldsw + _i * 8192), 16, 0, 0); } while (0)
; #define PG8_LDA(dst, b, h) do { _Pragma("unroll") for (int m = 0; m < 4; ++m) _Pragma("unroll") for (int k = 0; k < 2; ++k) dst[m][k] = *(const PG8_LAS bf16x8*)(lds + PG8_SA(b, h) + aoff + m * 2048 + k * 1024); } while (0)
; #define PG8_LDB(dst, b, h) do { _Pragma("unroll") for (int n = 0; n < 2; ++n) _Pragma("unroll") for (int k = 0; k < 2; ++k) dst[n][k] = *(const PG8_LAS bf16x8*)(lds + PG8_SB(b, h) + boff + n * 2048 + k * 1024); } while (0)
; #define PG8_MMA(ai, bj, At, Bt) do { __builtin_amdgcn_s_setprio(1); _Pragma("unroll") for (int m = 0; m < 4; ++m) _Pragma("unroll") for (int n = 0; n < 2; ++n) _Pragma("unroll") for (int k = 0; k < 2; ++k) \
;         acc[ai][bj][m][n] = __builtin_amdgcn_mfma_f32_16x16x32_bf16(Bt[n][k], At[m][k], acc[ai][bj][m][n], 0, 0, 0); __builtin_amdgcn_s_setprio(0); } while (0)
; #define PG8_WAIT_V(n) asm volatile("s_waitcnt vmcnt(" #n ")" ::: "memory")
; #define PG8_WAIT_L(n) asm volatile("s_waitcnt lgkmcnt(" #n ")" ::: "memory")
; #define PG8_BAR __builtin_amdgcn_s_barrier()
; #define PG8_SCHED __builtin_amdgcn_sched_barrier(0)
; template <class Epi, class Sched, bool ALIGN_EPI = false, bool SP2 = false>
; __device__ __forceinline__ void gemm_phase(PG8_LAS unsigned char* lds, const Gemm g, const Sched& S, const Epi& E) {
;     ...
;             PG8_WAIT_V(8); PG8_WAIT_L(0); PG8_BAR; PG8_MMA(1, 0, At, B0); PG8_MMA(1, 1, At, B1); PG8_BAR; PG8_SCHED;
;             PG8_LDB(B0, 1, 0); PG8_LDB(B1, 1, 1); PG8_SCHED; PG8_LDA(At, 1, 0); PG8_STAGE(PG8_SA(0, 1), a2 + hstep, voffA);
;             PG8_WAIT_V(8); PG8_WAIT_L(0); PG8_BAR; PG8_MMA(0, 0, At, B0); PG8_MMA(0, 1, At, B1); PG8_BAR; PG8_SCHED;
	s_setprio 1
	s_waitcnt lgkmcnt(0)
	v_mfma_f32_16x16x32_bf16 v[62:65], v[144:147], v[192:195], v[62:65]
	v_mfma_f32_16x16x32_bf16 v[58:61], v[152:155], v[192:195], v[58:61]
	v_mfma_f32_16x16x32_bf16 v[46:49], v[144:147], v[200:203], v[46:49]
	v_mfma_f32_16x16x32_bf16 v[42:45], v[152:155], v[200:203], v[42:45]
	v_mfma_f32_16x16x32_bf16 v[30:33], v[144:147], v[208:211], v[30:33]
	v_mfma_f32_16x16x32_bf16 v[26:29], v[152:155], v[208:211], v[26:29]
	v_mfma_f32_16x16x32_bf16 v[14:17], v[144:147], v[216:219], v[14:17]
	v_mfma_f32_16x16x32_bf16 v[10:13], v[152:155], v[216:219], v[10:13]
	v_mfma_f32_16x16x32_bf16 v[62:65], v[148:151], v[196:199], v[62:65]
	v_mfma_f32_16x16x32_bf16 v[58:61], v[156:159], v[196:199], v[58:61]
	v_mfma_f32_16x16x32_bf16 v[46:49], v[148:151], v[204:207], v[46:49]
	v_mfma_f32_16x16x32_bf16 v[42:45], v[156:159], v[204:207], v[42:45]
	v_mfma_f32_16x16x32_bf16 v[30:33], v[148:151], v[212:215], v[30:33]
	v_mfma_f32_16x16x32_bf16 v[26:29], v[156:159], v[212:215], v[26:29]
	v_mfma_f32_16x16x32_bf16 v[14:17], v[148:151], v[220:223], v[14:17]
	v_mfma_f32_16x16x32_bf16 v[10:13], v[156:159], v[220:223], v[10:13]
	s_setprio 0
	s_setprio 1
	v_mfma_f32_16x16x32_bf16 v[54:57], v[168:171], v[192:195], v[54:57]
	v_mfma_f32_16x16x32_bf16 v[50:53], v[176:179], v[192:195], v[50:53]
	v_mfma_f32_16x16x32_bf16 v[38:41], v[168:171], v[200:203], v[38:41]
	v_mfma_f32_16x16x32_bf16 v[34:37], v[176:179], v[200:203], v[34:37]
	v_mfma_f32_16x16x32_bf16 v[22:25], v[168:171], v[208:211], v[22:25]
	v_mfma_f32_16x16x32_bf16 v[18:21], v[176:179], v[208:211], v[18:21]
	v_mfma_f32_16x16x32_bf16 v[6:9], v[168:171], v[216:219], v[6:9]
	v_mfma_f32_16x16x32_bf16 v[2:5], v[176:179], v[216:219], v[2:5]
	v_mfma_f32_16x16x32_bf16 v[54:57], v[172:175], v[196:199], v[54:57]
	v_mfma_f32_16x16x32_bf16 v[50:53], v[180:183], v[196:199], v[50:53]
	v_mfma_f32_16x16x32_bf16 v[38:41], v[172:175], v[204:207], v[38:41]
	v_mfma_f32_16x16x32_bf16 v[34:37], v[180:183], v[204:207], v[34:37]
	v_mfma_f32_16x16x32_bf16 v[22:25], v[172:175], v[212:215], v[22:25]
	v_mfma_f32_16x16x32_bf16 v[18:21], v[180:183], v[212:215], v[18:21]
	v_mfma_f32_16x16x32_bf16 v[6:9], v[172:175], v[220:223], v[6:9]
	v_mfma_f32_16x16x32_bf16 v[2:5], v[180:183], v[220:223], v[2:5]
	s_setprio 0
	s_barrier
	s_add_i32 s80, 0, 0x18000
	s_add_i32 s81, 0, 0x1c000
	v_add_u32_e32 v156, s80, v141
	v_add_u32_e32 v180, s81, v141
	ds_read_b128 v[144:147], v156
	ds_read_b128 v[148:151], v156 offset:1024
	ds_read_b128 v[152:155], v156 offset:2048
	ds_read_b128 v[156:159], v156 offset:3072
	ds_read_b128 v[168:171], v180
	ds_read_b128 v[172:175], v180 offset:1024
	ds_read_b128 v[176:179], v180 offset:2048
	ds_read_b128 v[180:183], v180 offset:3072
	s_add_u32 s10, s10, s8
	s_addc_u32 s11, s11, s9
	s_mov_b32 m0, s41
	s_nop 0
	global_load_lds_dwordx4 v[228:229], off
	s_mov_b32 m0, s42
	s_nop 0
	global_load_lds_dwordx4 v[230:231], off
	s_mov_b32 m0, s43
	v_lshl_add_u64 v[232:233], s[10:11], 0, v[130:131]
	ds_read_b128 v[192:195], v143 offset:32768
	ds_read_b128 v[196:199], v143 offset:33792
	ds_read_b128 v[200:203], v143 offset:34816
	ds_read_b128 v[204:207], v143 offset:35840
	ds_read_b128 v[208:211], v143 offset:36864
	ds_read_b128 v[212:215], v143 offset:37888
	ds_read_b128 v[216:219], v143 offset:38912
	ds_read_b128 v[220:223], v143 offset:39936
	global_load_lds_dwordx4 v[232:233], off
	v_lshl_add_u64 v[232:233], s[10:11], 0, v[132:133]
	s_mov_b32 m0, s44
	s_nop 0
	global_load_lds_dwordx4 v[232:233], off
	s_waitcnt vmcnt(8)
	s_waitcnt lgkmcnt(0)
	s_barrier
	s_setprio 1
	s_waitcnt lgkmcnt(0)
	v_mfma_f32_16x16x32_bf16 v[122:125], v[144:147], v[192:195], v[122:125]
	v_mfma_f32_16x16x32_bf16 v[126:129], v[152:155], v[192:195], v[126:129]
	v_mfma_f32_16x16x32_bf16 v[110:113], v[144:147], v[200:203], v[110:113]
	v_mfma_f32_16x16x32_bf16 v[106:109], v[152:155], v[200:203], v[106:109]
	v_mfma_f32_16x16x32_bf16 v[94:97], v[144:147], v[208:211], v[94:97]
	v_mfma_f32_16x16x32_bf16 v[90:93], v[152:155], v[208:211], v[90:93]
	v_mfma_f32_16x16x32_bf16 v[78:81], v[144:147], v[216:219], v[78:81]
	v_mfma_f32_16x16x32_bf16 v[74:77], v[152:155], v[216:219], v[74:77]
	v_mfma_f32_16x16x32_bf16 v[122:125], v[148:151], v[196:199], v[122:125]
	v_mfma_f32_16x16x32_bf16 v[126:129], v[156:159], v[196:199], v[126:129]
	v_mfma_f32_16x16x32_bf16 v[110:113], v[148:151], v[204:207], v[110:113]
	v_mfma_f32_16x16x32_bf16 v[106:109], v[156:159], v[204:207], v[106:109]
	v_mfma_f32_16x16x32_bf16 v[94:97], v[148:151], v[212:215], v[94:97]
	v_mfma_f32_16x16x32_bf16 v[90:93], v[156:159], v[212:215], v[90:93]
	v_mfma_f32_16x16x32_bf16 v[78:81], v[148:151], v[220:223], v[78:81]
	v_mfma_f32_16x16x32_bf16 v[74:77], v[156:159], v[220:223], v[74:77]
	s_setprio 0
	s_setprio 1
	v_mfma_f32_16x16x32_bf16 v[118:121], v[168:171], v[192:195], v[118:121]
	v_mfma_f32_16x16x32_bf16 v[114:117], v[176:179], v[192:195], v[114:117]
	v_mfma_f32_16x16x32_bf16 v[102:105], v[168:171], v[200:203], v[102:105]
	v_mfma_f32_16x16x32_bf16 v[98:101], v[176:179], v[200:203], v[98:101]
	v_mfma_f32_16x16x32_bf16 v[86:89], v[168:171], v[208:211], v[86:89]
	v_mfma_f32_16x16x32_bf16 v[82:85], v[176:179], v[208:211], v[82:85]
	v_mfma_f32_16x16x32_bf16 v[70:73], v[168:171], v[216:219], v[70:73]
	v_mfma_f32_16x16x32_bf16 v[66:69], v[176:179], v[216:219], v[66:69]
	v_mfma_f32_16x16x32_bf16 v[118:121], v[172:175], v[196:199], v[118:121]
	v_mfma_f32_16x16x32_bf16 v[114:117], v[180:183], v[196:199], v[114:117]
	v_mfma_f32_16x16x32_bf16 v[102:105], v[172:175], v[204:207], v[102:105]
	v_mfma_f32_16x16x32_bf16 v[98:101], v[180:183], v[204:207], v[98:101]
	v_mfma_f32_16x16x32_bf16 v[86:89], v[172:175], v[212:215], v[86:89]
	v_mfma_f32_16x16x32_bf16 v[82:85], v[180:183], v[212:215], v[82:85]
	v_mfma_f32_16x16x32_bf16 v[70:73], v[172:175], v[220:223], v[70:73]
	v_mfma_f32_16x16x32_bf16 v[66:69], v[180:183], v[220:223], v[66:69]
	s_setprio 0
	s_barrier
; #define PG8_STAGE(bufoff, gbase, voff) do { _Pragma("unroll") for (int _i = 0; _i < 2; ++_i) \
;         __builtin_amdgcn_global_load_lds((const unsigned*)((const char*)(gbase) + (voff)[_i]), (PG8_LAS unsigned*)(lds + (bufoff) + ldsw + _i * 8192), 16, 0, 0); } while (0)
; #define PG8_LDA(dst, b, h) do { _Pragma("unroll") for (int m = 0; m < 4; ++m) _Pragma("unroll") for (int k = 0; k < 2; ++k) dst[m][k] = *(const PG8_LAS bf16x8*)(lds + PG8_SA(b, h) + aoff + m * 2048 + k * 1024); } while (0)
; #define PG8_MMA(ai, bj, At, Bt) do { __builtin_amdgcn_s_setprio(1); _Pragma("unroll") for (int m = 0; m < 4; ++m) _Pragma("unroll") for (int n = 0; n < 2; ++n) _Pragma("unroll") for (int k = 0; k < 2; ++k) \
;         acc[ai][bj][m][n] = __builtin_amdgcn_mfma_f32_16x16x32_bf16(Bt[n][k], At[m][k], acc[ai][bj][m][n], 0, 0, 0); __builtin_amdgcn_s_setprio(0); } while (0)
; #define PG8_WAIT_V(n) asm volatile("s_waitcnt vmcnt(" #n ")" ::: "memory")
; #define PG8_WAIT_L(n) asm volatile("s_waitcnt lgkmcnt(" #n ")" ::: "memory")
; #define PG8_BAR __builtin_amdgcn_s_barrier()
; #define PG8_SCHED __builtin_amdgcn_sched_barrier(0)
; template <class Epi, class Sched, bool ALIGN_EPI = false, bool SP2 = false>
; __device__ __forceinline__ void gemm_phase(PG8_LAS unsigned char* lds, const Gemm g, const Sched& S, const Epi& E) {
;     ...
;         for (int t = 0; t < nt; t += 2) {
;     ...
;             PG8_LDA(At, 1, 1); PG8_STAGE(PG8_SB(1, 0), b3, voffB); PG8_STAGE(PG8_SB(1, 1), b3 + hstep, voffB); PG8_STAGE(PG8_SA(1, 0), a3, voffA);
;             PG8_WAIT_V(8); PG8_WAIT_L(0); PG8_BAR; PG8_MMA(1, 0, At, B0); PG8_MMA(1, 1, At, B1); PG8_BAR; PG8_SCHED;
	s_add_i32 s10, s80, s40
	v_lshl_add_u64 v[166:167], v[166:167], 0, s[88:89]
	s_mov_b32 m0, s10
	ds_read_b128 v[192:195], v143 offset:49152
	ds_read_b128 v[196:199], v143 offset:50176
	ds_read_b128 v[200:203], v143 offset:51200
	ds_read_b128 v[204:207], v143 offset:52224
	ds_read_b128 v[208:211], v143 offset:53248
	ds_read_b128 v[212:215], v143 offset:54272
	ds_read_b128 v[216:219], v143 offset:55296
	ds_read_b128 v[220:223], v143 offset:56320
	global_load_lds_dwordx4 v[166:167], off
	v_lshl_add_u64 v[166:167], v[184:185], 0, s[88:89]
	s_add_i32 m0, s10, 0x2000
	s_add_i32 s10, s81, s40
	global_load_lds_dwordx4 v[166:167], off
	v_lshl_add_u64 v[166:167], v[224:225], 0, s[88:89]
	s_mov_b32 m0, s10
	s_nop 0
	global_load_lds_dwordx4 v[166:167], off
	v_lshl_add_u64 v[166:167], v[226:227], 0, s[88:89]
	s_add_i32 m0, s10, 0x2000
	s_nop 0
	global_load_lds_dwordx4 v[166:167], off
	v_lshl_add_u64 v[166:167], v[228:229], 0, s[88:89]
	s_mov_b32 m0, s45
	s_nop 0
	global_load_lds_dwordx4 v[166:167], off
	v_lshl_add_u64 v[166:167], v[230:231], 0, s[88:89]
	s_mov_b32 m0, s48
	s_nop 0
	global_load_lds_dwordx4 v[166:167], off
	s_waitcnt vmcnt(8)
	s_waitcnt lgkmcnt(0)
	s_barrier
	s_setprio 1
	s_waitcnt lgkmcnt(0)
	v_mfma_f32_16x16x32_bf16 v[62:65], v[144:147], v[192:195], v[62:65]
	v_mfma_f32_16x16x32_bf16 v[58:61], v[152:155], v[192:195], v[58:61]
	v_mfma_f32_16x16x32_bf16 v[46:49], v[144:147], v[200:203], v[46:49]
	v_mfma_f32_16x16x32_bf16 v[42:45], v[152:155], v[200:203], v[42:45]
	v_mfma_f32_16x16x32_bf16 v[30:33], v[144:147], v[208:211], v[30:33]
	v_mfma_f32_16x16x32_bf16 v[26:29], v[152:155], v[208:211], v[26:29]
	v_mfma_f32_16x16x32_bf16 v[14:17], v[144:147], v[216:219], v[14:17]
	v_mfma_f32_16x16x32_bf16 v[10:13], v[152:155], v[216:219], v[10:13]
	v_mfma_f32_16x16x32_bf16 v[62:65], v[148:151], v[196:199], v[62:65]
	v_mfma_f32_16x16x32_bf16 v[58:61], v[156:159], v[196:199], v[58:61]
	v_mfma_f32_16x16x32_bf16 v[46:49], v[148:151], v[204:207], v[46:49]
	v_mfma_f32_16x16x32_bf16 v[42:45], v[156:159], v[204:207], v[42:45]
	v_mfma_f32_16x16x32_bf16 v[30:33], v[148:151], v[212:215], v[30:33]
	v_mfma_f32_16x16x32_bf16 v[26:29], v[156:159], v[212:215], v[26:29]
	v_mfma_f32_16x16x32_bf16 v[14:17], v[148:151], v[220:223], v[14:17]
	v_mfma_f32_16x16x32_bf16 v[10:13], v[156:159], v[220:223], v[10:13]
	s_setprio 0
	s_setprio 1
	v_mfma_f32_16x16x32_bf16 v[54:57], v[168:171], v[192:195], v[54:57]
	v_mfma_f32_16x16x32_bf16 v[50:53], v[176:179], v[192:195], v[50:53]
	v_mfma_f32_16x16x32_bf16 v[38:41], v[168:171], v[200:203], v[38:41]
	v_mfma_f32_16x16x32_bf16 v[34:37], v[176:179], v[200:203], v[34:37]
	v_mfma_f32_16x16x32_bf16 v[22:25], v[168:171], v[208:211], v[22:25]
	v_mfma_f32_16x16x32_bf16 v[18:21], v[176:179], v[208:211], v[18:21]
	v_mfma_f32_16x16x32_bf16 v[6:9], v[168:171], v[216:219], v[6:9]
	v_mfma_f32_16x16x32_bf16 v[2:5], v[176:179], v[216:219], v[2:5]
	v_mfma_f32_16x16x32_bf16 v[54:57], v[172:175], v[196:199], v[54:57]
	v_mfma_f32_16x16x32_bf16 v[50:53], v[180:183], v[196:199], v[50:53]
	v_mfma_f32_16x16x32_bf16 v[38:41], v[172:175], v[204:207], v[38:41]
	v_mfma_f32_16x16x32_bf16 v[34:37], v[180:183], v[204:207], v[34:37]
	v_mfma_f32_16x16x32_bf16 v[22:25], v[172:175], v[212:215], v[22:25]
	v_mfma_f32_16x16x32_bf16 v[18:21], v[180:183], v[212:215], v[18:21]
	v_mfma_f32_16x16x32_bf16 v[6:9], v[172:175], v[220:223], v[6:9]
	v_mfma_f32_16x16x32_bf16 v[2:5], v[180:183], v[220:223], v[2:5]
	s_setprio 0
	s_barrier
	s_add_u32 s34, s34, 0x100
	s_addc_u32 s35, s35, 0
	s_add_u32 s75, s75, 0x100
	s_addc_u32 s78, s78, 0
	s_cmp_ge_i32 s79, s49
	s_mov_b32 s10, s79
	s_cbranch_scc0 .LBB0_441
	s_movk_i32 s75, 0x4200

; #define PG8_STAGE(bufoff, gbase, voff) do { _Pragma("unroll") for (int _i = 0; _i < 2; ++_i) \
;         __builtin_amdgcn_global_load_lds((const unsigned*)((const char*)(gbase) + (voff)[_i]), (PG8_LAS unsigned*)(lds + (bufoff) + ldsw + _i * 8192), 16, 0, 0); } while (0)
; #define PG8_LDA(dst, b, h) do { _Pragma("unroll") for (int m = 0; m < 4; ++m) _Pragma("unroll") for (int k = 0; k < 2; ++k) dst[m][k] = *(const PG8_LAS bf16x8*)(lds + PG8_SA(b, h) + aoff + m * 2048 + k * 1024); } while (0)
; #define PG8_LDB(dst, b, h) do { _Pragma("unroll") for (int n = 0; n < 2; ++n) _Pragma("unroll") for (int k = 0; k < 2; ++k) dst[n][k] = *(const PG8_LAS bf16x8*)(lds + PG8_SB(b, h) + boff + n * 2048 + k * 1024); } while (0)
; #define PG8_MMA(ai, bj, At, Bt) do { __builtin_amdgcn_s_setprio(1); _Pragma("unroll") for (int m = 0; m < 4; ++m) _Pragma("unroll") for (int n = 0; n < 2; ++n) _Pragma("unroll") for (int k = 0; k < 2; ++k) \
;         acc[ai][bj][m][n] = __builtin_amdgcn_mfma_f32_16x16x32_bf16(Bt[n][k], At[m][k], acc[ai][bj][m][n], 0, 0, 0); __builtin_amdgcn_s_setprio(0); } while (0)
; #define PG8_WAIT_V(n) asm volatile("s_waitcnt vmcnt(" #n ")" ::: "memory")
; #define PG8_WAIT_L(n) asm volatile("s_waitcnt lgkmcnt(" #n ")" ::: "memory")
; template <class Epi, class Sched, bool ALIGN_EPI = false, bool SP2 = false>
; __device__ __forceinline__ void gemm_phase(PG8_LAS unsigned char* lds, const Gemm g, const Sched& S, const Epi& E) {
;     ...
;             const bool last = (t == nt - 2);
;             const char* a1 = cA + (size_t)(t + 1) * kstep;
;             const char* a2 = last ? nA : cA + (size_t)(t + 2) * kstep; const char* b2 = last ? nB : cB + (size_t)(t + 2) * kstep;
;             const char* a3 = a2 + kstep; const char* b3 = b2 + kstep;
;             if (last && has_next) S.a_ready(nxt);
;             if constexpr (SP2) {
;             PG8_LDB(B0, 0, 0); PG8_LDB(B1, 0, 1); PG8_SCHED; PG8_LDA(At, 0, 0); PG8_STAGE(PG8_SA(1, 1), a1 + hstep, voffA);
;             PG8_WAIT_V(8); PG8_WAIT_L(0); PG8_BAR; PG8_MMA(0, 0, At, B0); PG8_MMA(0, 1, At, B1); PG8_BAR; PG8_SCHED;
;             PG8_LDA(At, 0, 1); PG8_STAGE(PG8_SB(0, 0), b2, voffB); PG8_STAGE(PG8_SB(0, 1), b2 + hstep, voffB); PG8_STAGE(PG8_SA(0, 0), a2, voffA);
;             PG8_WAIT_V(8); PG8_WAIT_L(0); PG8_BAR; PG8_MMA(1, 0, At, B0); PG8_MMA(1, 1, At, B1); PG8_BAR; PG8_SCHED;
.LBB0_475:
	s_add_i32 s93, s10, 2
	s_add_u32 s94, s8, 0x80
	s_addc_u32 s11, s9, 0
	s_add_i32 s96, 0, 0x10000
	s_cmp_eq_u32 s79, s10
	s_cselect_b32 s11, s1, s11
	s_cselect_b32 s10, s0, s94
	v_add_u32_e32 v144, s96, v147
	s_cselect_b32 s95, s43, s92
	s_cselect_b32 s94, s42, s87
	s_add_i32 s97, 0, 0x14000
	ds_read_b128 v[140:143], v144
	s_waitcnt vmcnt(0)
	ds_read_b128 v[150:153], v144 offset:1024
	ds_read_b128 v[154:157], v144 offset:2048
	ds_read_b128 v[168:171], v144 offset:3072
	v_add_u32_e32 v144, s97, v147
	ds_read_b128 v[172:175], v144
	ds_read_b128 v[176:179], v144 offset:1024
	ds_read_b128 v[180:183], v144 offset:2048
	ds_read_b128 v[192:195], v144 offset:3072
	v_lshl_add_u64 v[144:145], s[8:9], 0, v[136:137]
	s_add_i32 m0, s50, 0xc000
	ds_read_b128 v[196:199], v149
	ds_read_b128 v[200:203], v149 offset:1024
	ds_read_b128 v[204:207], v149 offset:2048
	ds_read_b128 v[208:211], v149 offset:3072
	ds_read_b128 v[212:215], v149 offset:4096
	ds_read_b128 v[216:219], v149 offset:5120
	ds_read_b128 v[220:223], v149 offset:6144
	ds_read_b128 v[224:227], v149 offset:7168
	global_load_lds_dwordx4 v[144:145], off
	v_lshl_add_u64 v[144:145], s[8:9], 0, v[138:139]
	s_add_i32 m0, s50, 0xe000
	s_nop 0
	global_load_lds_dwordx4 v[144:145], off
	s_waitcnt vmcnt(8)
	s_waitcnt lgkmcnt(0)
	s_barrier
	s_setprio 1
	s_waitcnt lgkmcnt(0)
	v_mfma_f32_16x16x32_bf16 v[122:125], v[140:143], v[196:199], v[122:125]
	v_mfma_f32_16x16x32_bf16 v[126:129], v[154:157], v[196:199], v[126:129]
	v_mfma_f32_16x16x32_bf16 v[110:113], v[140:143], v[204:207], v[110:113]
	v_mfma_f32_16x16x32_bf16 v[106:109], v[154:157], v[204:207], v[106:109]
	v_mfma_f32_16x16x32_bf16 v[94:97], v[140:143], v[212:215], v[94:97]
	v_mfma_f32_16x16x32_bf16 v[90:93], v[154:157], v[212:215], v[90:93]
	v_mfma_f32_16x16x32_bf16 v[78:81], v[140:143], v[220:223], v[78:81]
	v_mfma_f32_16x16x32_bf16 v[74:77], v[154:157], v[220:223], v[74:77]
	v_mfma_f32_16x16x32_bf16 v[122:125], v[150:153], v[200:203], v[122:125]
	v_mfma_f32_16x16x32_bf16 v[126:129], v[168:171], v[200:203], v[126:129]
	v_mfma_f32_16x16x32_bf16 v[110:113], v[150:153], v[208:211], v[110:113]
	v_mfma_f32_16x16x32_bf16 v[106:109], v[168:171], v[208:211], v[106:109]
	v_mfma_f32_16x16x32_bf16 v[94:97], v[150:153], v[216:219], v[94:97]
	v_mfma_f32_16x16x32_bf16 v[90:93], v[168:171], v[216:219], v[90:93]
	v_mfma_f32_16x16x32_bf16 v[78:81], v[150:153], v[224:227], v[78:81]
	v_mfma_f32_16x16x32_bf16 v[74:77], v[168:171], v[224:227], v[74:77]
	s_setprio 0
	s_setprio 1
	v_mfma_f32_16x16x32_bf16 v[118:121], v[172:175], v[196:199], v[118:121]
	v_mfma_f32_16x16x32_bf16 v[114:117], v[180:183], v[196:199], v[114:117]
	v_mfma_f32_16x16x32_bf16 v[102:105], v[172:175], v[204:207], v[102:105]
	v_mfma_f32_16x16x32_bf16 v[98:101], v[180:183], v[204:207], v[98:101]
	v_mfma_f32_16x16x32_bf16 v[86:89], v[172:175], v[212:215], v[86:89]
	v_mfma_f32_16x16x32_bf16 v[82:85], v[180:183], v[212:215], v[82:85]
	v_mfma_f32_16x16x32_bf16 v[70:73], v[172:175], v[220:223], v[70:73]
	v_mfma_f32_16x16x32_bf16 v[66:69], v[180:183], v[220:223], v[66:69]
	v_mfma_f32_16x16x32_bf16 v[118:121], v[176:179], v[200:203], v[118:121]
	v_mfma_f32_16x16x32_bf16 v[114:117], v[192:195], v[200:203], v[114:117]
	v_mfma_f32_16x16x32_bf16 v[102:105], v[176:179], v[208:211], v[102:105]
	v_mfma_f32_16x16x32_bf16 v[98:101], v[192:195], v[208:211], v[98:101]
	v_mfma_f32_16x16x32_bf16 v[86:89], v[176:179], v[216:219], v[86:89]
	v_mfma_f32_16x16x32_bf16 v[82:85], v[192:195], v[216:219], v[82:85]
	v_mfma_f32_16x16x32_bf16 v[70:73], v[176:179], v[224:227], v[70:73]
	v_mfma_f32_16x16x32_bf16 v[66:69], v[192:195], v[224:227], v[66:69]
	s_setprio 0
	s_barrier
	s_add_i32 s96, s96, s45
	v_lshl_add_u64 v[144:145], s[94:95], 0, v[160:161]
	s_mov_b32 m0, s96
	ds_read_b128 v[196:199], v149 offset:16384
	ds_read_b128 v[200:203], v149 offset:17408
	ds_read_b128 v[204:207], v149 offset:18432
	ds_read_b128 v[208:211], v149 offset:19456
	ds_read_b128 v[212:215], v149 offset:20480
	ds_read_b128 v[216:219], v149 offset:21504
	ds_read_b128 v[220:223], v149 offset:22528
	ds_read_b128 v[224:227], v149 offset:23552
	global_load_lds_dwordx4 v[144:145], off
	s_add_i32 m0, s96, 0x2000
	v_lshl_add_u64 v[158:159], s[94:95], 0, v[134:135]
	s_add_u32 s94, s94, s14
	s_addc_u32 s95, s95, s15
	s_add_i32 s96, s97, s45
	global_load_lds_dwordx4 v[158:159], off
	v_lshl_add_u64 v[166:167], s[94:95], 0, v[160:161]
	s_mov_b32 m0, s96
	v_lshl_add_u64 v[184:185], s[94:95], 0, v[134:135]
	global_load_lds_dwordx4 v[166:167], off
	s_add_i32 m0, s96, 0x2000
	v_lshl_add_u64 v[228:229], s[10:11], 0, v[130:131]
	global_load_lds_dwordx4 v[184:185], off
	v_lshl_add_u64 v[230:231], s[10:11], 0, v[132:133]
	s_nop 0
	s_waitcnt vmcnt(6)
	s_waitcnt lgkmcnt(0)
	s_barrier
; #define PG8_STAGE(bufoff, gbase, voff) do { _Pragma("unroll") for (int _i = 0; _i < 2; ++_i) \
;         __builtin_amdgcn_global_load_lds((const unsigned*)((const char*)(gbase) + (voff)[_i]), (PG8_LAS unsigned*)(lds + (bufoff) + ldsw + _i * 8192), 16, 0, 0); } while (0)
; #define PG8_LDA(dst, b, h) do { _Pragma("unroll") for (int m = 0; m < 4; ++m) _Pragma("unroll") for (int k = 0; k < 2; ++k) dst[m][k] = *(const PG8_LAS bf16x8*)(lds + PG8_SA(b, h) + aoff + m * 2048 + k * 1024); } while (0)
; #define PG8_LDB(dst, b, h) do { _Pragma("unroll") for (int n = 0; n < 2; ++n) _Pragma("unroll") for (int k = 0; k < 2; ++k) dst[n][k] = *(const PG8_LAS bf16x8*)(lds + PG8_SB(b, h) + boff + n * 2048 + k * 1024); } while (0)
; #define PG8_MMA(ai, bj, At, Bt) do { __builtin_amdgcn_s_setprio(1); _Pragma("unroll") for (int m = 0; m < 4; ++m) _Pragma("unroll") for (int n = 0; n < 2; ++n) _Pragma("unroll") for (int k = 0; k < 2; ++k) \
;         acc[ai][bj][m][n] = __builtin_amdgcn_mfma_f32_16x16x32_bf16(Bt[n][k], At[m][k], acc[ai][bj][m][n], 0, 0, 0); __builtin_amdgcn_s_setprio(0); } while (0)
; #define PG8_WAIT_V(n) asm volatile("s_waitcnt vmcnt(" #n ")" ::: "memory")
; #define PG8_WAIT_L(n) asm volatile("s_waitcnt lgkmcnt(" #n ")" ::: "memory")
; #define PG8_BAR __builtin_amdgcn_s_barrier()
; #define PG8_SCHED __builtin_amdgcn_sched_barrier(0)
; template <class Epi, class Sched, bool ALIGN_EPI = false, bool SP2 = false>
; __device__ __forceinline__ void gemm_phase(PG8_LAS unsigned char* lds, const Gemm g, const Sched& S, const Epi& E) {
;     ...
;             PG8_WAIT_V(8); PG8_WAIT_L(0); PG8_BAR; PG8_MMA(1, 0, At, B0); PG8_MMA(1, 1, At, B1); PG8_BAR; PG8_SCHED;
;             PG8_LDB(B0, 1, 0); PG8_LDB(B1, 1, 1); PG8_SCHED; PG8_LDA(At, 1, 0); PG8_STAGE(PG8_SA(0, 1), a2 + hstep, voffA);
;             PG8_WAIT_V(8); PG8_WAIT_L(0); PG8_BAR; PG8_MMA(0, 0, At, B0); PG8_MMA(0, 1, At, B1); PG8_BAR; PG8_SCHED;
	s_setprio 1
	s_waitcnt lgkmcnt(0)
	v_mfma_f32_16x16x32_bf16 v[62:65], v[140:143], v[196:199], v[62:65]
	v_mfma_f32_16x16x32_bf16 v[58:61], v[154:157], v[196:199], v[58:61]
	v_mfma_f32_16x16x32_bf16 v[46:49], v[140:143], v[204:207], v[46:49]
	v_mfma_f32_16x16x32_bf16 v[42:45], v[154:157], v[204:207], v[42:45]
	v_mfma_f32_16x16x32_bf16 v[30:33], v[140:143], v[212:215], v[30:33]
	v_mfma_f32_16x16x32_bf16 v[26:29], v[154:157], v[212:215], v[26:29]
	v_mfma_f32_16x16x32_bf16 v[14:17], v[140:143], v[220:223], v[14:17]
	v_mfma_f32_16x16x32_bf16 v[10:13], v[154:157], v[220:223], v[10:13]
	v_mfma_f32_16x16x32_bf16 v[62:65], v[150:153], v[200:203], v[62:65]
	v_mfma_f32_16x16x32_bf16 v[58:61], v[168:171], v[200:203], v[58:61]
	v_mfma_f32_16x16x32_bf16 v[46:49], v[150:153], v[208:211], v[46:49]
	v_mfma_f32_16x16x32_bf16 v[42:45], v[168:171], v[208:211], v[42:45]
	v_mfma_f32_16x16x32_bf16 v[30:33], v[150:153], v[216:219], v[30:33]
	v_mfma_f32_16x16x32_bf16 v[26:29], v[168:171], v[216:219], v[26:29]
	v_mfma_f32_16x16x32_bf16 v[14:17], v[150:153], v[224:227], v[14:17]
	v_mfma_f32_16x16x32_bf16 v[10:13], v[168:171], v[224:227], v[10:13]
	s_setprio 0
	s_setprio 1
	v_mfma_f32_16x16x32_bf16 v[54:57], v[172:175], v[196:199], v[54:57]
	v_mfma_f32_16x16x32_bf16 v[50:53], v[180:183], v[196:199], v[50:53]
	v_mfma_f32_16x16x32_bf16 v[38:41], v[172:175], v[204:207], v[38:41]
	v_mfma_f32_16x16x32_bf16 v[34:37], v[180:183], v[204:207], v[34:37]
	v_mfma_f32_16x16x32_bf16 v[22:25], v[172:175], v[212:215], v[22:25]
	v_mfma_f32_16x16x32_bf16 v[18:21], v[180:183], v[212:215], v[18:21]
	v_mfma_f32_16x16x32_bf16 v[6:9], v[172:175], v[220:223], v[6:9]
	v_mfma_f32_16x16x32_bf16 v[2:5], v[180:183], v[220:223], v[2:5]
	v_mfma_f32_16x16x32_bf16 v[54:57], v[176:179], v[200:203], v[54:57]
	v_mfma_f32_16x16x32_bf16 v[50:53], v[192:195], v[200:203], v[50:53]
	v_mfma_f32_16x16x32_bf16 v[38:41], v[176:179], v[208:211], v[38:41]
	v_mfma_f32_16x16x32_bf16 v[34:37], v[192:195], v[208:211], v[34:37]
	v_mfma_f32_16x16x32_bf16 v[22:25], v[176:179], v[216:219], v[22:25]
	v_mfma_f32_16x16x32_bf16 v[18:21], v[192:195], v[216:219], v[18:21]
	v_mfma_f32_16x16x32_bf16 v[6:9], v[176:179], v[224:227], v[6:9]
	v_mfma_f32_16x16x32_bf16 v[2:5], v[192:195], v[224:227], v[2:5]
	s_setprio 0
	s_barrier
	s_add_i32 s94, 0, 0x18000
	s_add_i32 s95, 0, 0x1c000
	v_add_u32_e32 v168, s94, v147
	v_add_u32_e32 v191, s95, v147
	ds_read_b128 v[140:143], v168
	ds_read_b128 v[150:153], v168 offset:1024
	ds_read_b128 v[154:157], v168 offset:2048
	ds_read_b128 v[168:171], v168 offset:3072
	ds_read_b128 v[172:175], v191
	ds_read_b128 v[176:179], v191 offset:1024
	ds_read_b128 v[180:183], v191 offset:2048
	ds_read_b128 v[192:195], v191 offset:3072
	s_add_u32 s10, s10, s14
	s_addc_u32 s11, s11, s15
	s_mov_b32 m0, s50
	s_nop 0
	global_load_lds_dwordx4 v[228:229], off
	s_mov_b32 m0, s51
	s_nop 0
	global_load_lds_dwordx4 v[230:231], off
	s_mov_b32 m0, s52
	v_lshl_add_u64 v[232:233], s[10:11], 0, v[130:131]
	ds_read_b128 v[196:199], v149 offset:32768
	ds_read_b128 v[200:203], v149 offset:33792
	ds_read_b128 v[204:207], v149 offset:34816
	ds_read_b128 v[208:211], v149 offset:35840
	ds_read_b128 v[212:215], v149 offset:36864
	ds_read_b128 v[216:219], v149 offset:37888
	ds_read_b128 v[220:223], v149 offset:38912
	ds_read_b128 v[224:227], v149 offset:39936
	global_load_lds_dwordx4 v[232:233], off
	v_lshl_add_u64 v[232:233], s[10:11], 0, v[132:133]
	s_mov_b32 m0, s53
	s_nop 0
	global_load_lds_dwordx4 v[232:233], off
	s_waitcnt vmcnt(8)
	s_waitcnt lgkmcnt(0)
	s_barrier
	s_setprio 1
	s_waitcnt lgkmcnt(0)
	v_mfma_f32_16x16x32_bf16 v[122:125], v[140:143], v[196:199], v[122:125]
	v_mfma_f32_16x16x32_bf16 v[126:129], v[154:157], v[196:199], v[126:129]
	v_mfma_f32_16x16x32_bf16 v[110:113], v[140:143], v[204:207], v[110:113]
	v_mfma_f32_16x16x32_bf16 v[106:109], v[154:157], v[204:207], v[106:109]
	v_mfma_f32_16x16x32_bf16 v[94:97], v[140:143], v[212:215], v[94:97]
	v_mfma_f32_16x16x32_bf16 v[90:93], v[154:157], v[212:215], v[90:93]
	v_mfma_f32_16x16x32_bf16 v[78:81], v[140:143], v[220:223], v[78:81]
	v_mfma_f32_16x16x32_bf16 v[74:77], v[154:157], v[220:223], v[74:77]
	v_mfma_f32_16x16x32_bf16 v[122:125], v[150:153], v[200:203], v[122:125]
	v_mfma_f32_16x16x32_bf16 v[126:129], v[168:171], v[200:203], v[126:129]
	v_mfma_f32_16x16x32_bf16 v[110:113], v[150:153], v[208:211], v[110:113]
	v_mfma_f32_16x16x32_bf16 v[106:109], v[168:171], v[208:211], v[106:109]
	v_mfma_f32_16x16x32_bf16 v[94:97], v[150:153], v[216:219], v[94:97]
	v_mfma_f32_16x16x32_bf16 v[90:93], v[168:171], v[216:219], v[90:93]
	v_mfma_f32_16x16x32_bf16 v[78:81], v[150:153], v[224:227], v[78:81]
	v_mfma_f32_16x16x32_bf16 v[74:77], v[168:171], v[224:227], v[74:77]
	s_setprio 0
	s_setprio 1
	v_mfma_f32_16x16x32_bf16 v[118:121], v[172:175], v[196:199], v[118:121]
	v_mfma_f32_16x16x32_bf16 v[114:117], v[180:183], v[196:199], v[114:117]
	v_mfma_f32_16x16x32_bf16 v[102:105], v[172:175], v[204:207], v[102:105]
	v_mfma_f32_16x16x32_bf16 v[98:101], v[180:183], v[204:207], v[98:101]
	v_mfma_f32_16x16x32_bf16 v[86:89], v[172:175], v[212:215], v[86:89]
	v_mfma_f32_16x16x32_bf16 v[82:85], v[180:183], v[212:215], v[82:85]
	v_mfma_f32_16x16x32_bf16 v[70:73], v[172:175], v[220:223], v[70:73]
	v_mfma_f32_16x16x32_bf16 v[66:69], v[180:183], v[220:223], v[66:69]
	v_mfma_f32_16x16x32_bf16 v[118:121], v[176:179], v[200:203], v[118:121]
	v_mfma_f32_16x16x32_bf16 v[114:117], v[192:195], v[200:203], v[114:117]
	v_mfma_f32_16x16x32_bf16 v[102:105], v[176:179], v[208:211], v[102:105]
	v_mfma_f32_16x16x32_bf16 v[98:101], v[192:195], v[208:211], v[98:101]
	v_mfma_f32_16x16x32_bf16 v[86:89], v[176:179], v[216:219], v[86:89]
	v_mfma_f32_16x16x32_bf16 v[82:85], v[192:195], v[216:219], v[82:85]
	v_mfma_f32_16x16x32_bf16 v[70:73], v[176:179], v[224:227], v[70:73]
	v_mfma_f32_16x16x32_bf16 v[66:69], v[192:195], v[224:227], v[66:69]
	s_setprio 0
	s_barrier
; #define PG8_STAGE(bufoff, gbase, voff) do { _Pragma("unroll") for (int _i = 0; _i < 2; ++_i) \
;         __builtin_amdgcn_global_load_lds((const unsigned*)((const char*)(gbase) + (voff)[_i]), (PG8_LAS unsigned*)(lds + (bufoff) + ldsw + _i * 8192), 16, 0, 0); } while (0)
; #define PG8_LDA(dst, b, h) do { _Pragma("unroll") for (int m = 0; m < 4; ++m) _Pragma("unroll") for (int k = 0; k < 2; ++k) dst[m][k] = *(const PG8_LAS bf16x8*)(lds + PG8_SA(b, h) + aoff + m * 2048 + k * 1024); } while (0)
; #define PG8_MMA(ai, bj, At, Bt) do { __builtin_amdgcn_s_setprio(1); _Pragma("unroll") for (int m = 0; m < 4; ++m) _Pragma("unroll") for (int n = 0; n < 2; ++n) _Pragma("unroll") for (int k = 0; k < 2; ++k) \
;         acc[ai][bj][m][n] = __builtin_amdgcn_mfma_f32_16x16x32_bf16(Bt[n][k], At[m][k], acc[ai][bj][m][n], 0, 0, 0); __builtin_amdgcn_s_setprio(0); } while (0)
; #define PG8_WAIT_V(n) asm volatile("s_waitcnt vmcnt(" #n ")" ::: "memory")
; #define PG8_WAIT_L(n) asm volatile("s_waitcnt lgkmcnt(" #n ")" ::: "memory")
; #define PG8_BAR __builtin_amdgcn_s_barrier()
; #define PG8_SCHED __builtin_amdgcn_sched_barrier(0)
; template <class Epi, class Sched, bool ALIGN_EPI = false, bool SP2 = false>
; __device__ __forceinline__ void gemm_phase(PG8_LAS unsigned char* lds, const Gemm g, const Sched& S, const Epi& E) {
;     ...
;         for (int t = 0; t < nt; t += 2) {
;     ...
;             PG8_LDA(At, 1, 1); PG8_STAGE(PG8_SB(1, 0), b3, voffB); PG8_STAGE(PG8_SB(1, 1), b3 + hstep, voffB); PG8_STAGE(PG8_SA(1, 0), a3, voffA);
;             PG8_WAIT_V(8); PG8_WAIT_L(0); PG8_BAR; PG8_MMA(1, 0, At, B0); PG8_MMA(1, 1, At, B1); PG8_BAR; PG8_SCHED;
	s_add_i32 s10, s94, s45
	v_lshl_add_u64 v[144:145], v[144:145], 0, s[88:89]
	s_mov_b32 m0, s10
	ds_read_b128 v[196:199], v149 offset:49152
	ds_read_b128 v[200:203], v149 offset:50176
	ds_read_b128 v[204:207], v149 offset:51200
	ds_read_b128 v[208:211], v149 offset:52224
	ds_read_b128 v[212:215], v149 offset:53248
	ds_read_b128 v[216:219], v149 offset:54272
	ds_read_b128 v[220:223], v149 offset:55296
	ds_read_b128 v[224:227], v149 offset:56320
	global_load_lds_dwordx4 v[144:145], off
	v_lshl_add_u64 v[144:145], v[158:159], 0, s[88:89]
	s_add_i32 m0, s10, 0x2000
	s_add_i32 s10, s95, s45
	global_load_lds_dwordx4 v[144:145], off
	v_lshl_add_u64 v[144:145], v[166:167], 0, s[88:89]
	s_mov_b32 m0, s10
	s_nop 0
	global_load_lds_dwordx4 v[144:145], off
	v_lshl_add_u64 v[144:145], v[184:185], 0, s[88:89]
	s_add_i32 m0, s10, 0x2000
	s_nop 0
	global_load_lds_dwordx4 v[144:145], off
	v_lshl_add_u64 v[144:145], v[228:229], 0, s[88:89]
	s_mov_b32 m0, s59
	s_nop 0
	global_load_lds_dwordx4 v[144:145], off
	v_lshl_add_u64 v[144:145], v[230:231], 0, s[88:89]
	s_mov_b32 m0, s74
	s_nop 0
	global_load_lds_dwordx4 v[144:145], off
	s_waitcnt vmcnt(8)
	s_waitcnt lgkmcnt(0)
	s_barrier
	s_setprio 1
	s_waitcnt lgkmcnt(0)
	v_mfma_f32_16x16x32_bf16 v[62:65], v[140:143], v[196:199], v[62:65]
	v_mfma_f32_16x16x32_bf16 v[58:61], v[154:157], v[196:199], v[58:61]
	v_mfma_f32_16x16x32_bf16 v[46:49], v[140:143], v[204:207], v[46:49]
	v_mfma_f32_16x16x32_bf16 v[42:45], v[154:157], v[204:207], v[42:45]
	v_mfma_f32_16x16x32_bf16 v[30:33], v[140:143], v[212:215], v[30:33]
	v_mfma_f32_16x16x32_bf16 v[26:29], v[154:157], v[212:215], v[26:29]
	v_mfma_f32_16x16x32_bf16 v[14:17], v[140:143], v[220:223], v[14:17]
	v_mfma_f32_16x16x32_bf16 v[10:13], v[154:157], v[220:223], v[10:13]
	v_mfma_f32_16x16x32_bf16 v[62:65], v[150:153], v[200:203], v[62:65]
	v_mfma_f32_16x16x32_bf16 v[58:61], v[168:171], v[200:203], v[58:61]
	v_mfma_f32_16x16x32_bf16 v[46:49], v[150:153], v[208:211], v[46:49]
	v_mfma_f32_16x16x32_bf16 v[42:45], v[168:171], v[208:211], v[42:45]
	v_mfma_f32_16x16x32_bf16 v[30:33], v[150:153], v[216:219], v[30:33]
	v_mfma_f32_16x16x32_bf16 v[26:29], v[168:171], v[216:219], v[26:29]
	v_mfma_f32_16x16x32_bf16 v[14:17], v[150:153], v[224:227], v[14:17]
	v_mfma_f32_16x16x32_bf16 v[10:13], v[168:171], v[224:227], v[10:13]
	s_setprio 0
	s_setprio 1
	v_mfma_f32_16x16x32_bf16 v[54:57], v[172:175], v[196:199], v[54:57]
	v_mfma_f32_16x16x32_bf16 v[50:53], v[180:183], v[196:199], v[50:53]
	v_mfma_f32_16x16x32_bf16 v[38:41], v[172:175], v[204:207], v[38:41]
	v_mfma_f32_16x16x32_bf16 v[34:37], v[180:183], v[204:207], v[34:37]
	v_mfma_f32_16x16x32_bf16 v[22:25], v[172:175], v[212:215], v[22:25]
	v_mfma_f32_16x16x32_bf16 v[18:21], v[180:183], v[212:215], v[18:21]
	v_mfma_f32_16x16x32_bf16 v[6:9], v[172:175], v[220:223], v[6:9]
	v_mfma_f32_16x16x32_bf16 v[2:5], v[180:183], v[220:223], v[2:5]
	v_mfma_f32_16x16x32_bf16 v[54:57], v[176:179], v[200:203], v[54:57]
	v_mfma_f32_16x16x32_bf16 v[50:53], v[192:195], v[200:203], v[50:53]
	v_mfma_f32_16x16x32_bf16 v[38:41], v[176:179], v[208:211], v[38:41]
	v_mfma_f32_16x16x32_bf16 v[34:37], v[192:195], v[208:211], v[34:37]
	v_mfma_f32_16x16x32_bf16 v[22:25], v[176:179], v[216:219], v[22:25]
	v_mfma_f32_16x16x32_bf16 v[18:21], v[192:195], v[216:219], v[18:21]
	v_mfma_f32_16x16x32_bf16 v[6:9], v[176:179], v[224:227], v[6:9]
	v_mfma_f32_16x16x32_bf16 v[2:5], v[192:195], v[224:227], v[2:5]
	s_setprio 0
	s_barrier
	s_add_u32 s8, s8, 0x100
	s_addc_u32 s9, s9, 0
	s_add_u32 s87, s87, 0x100
	s_addc_u32 s92, s92, 0
	s_cmp_ge_i32 s93, s78
	s_mov_b32 s10, s93
	s_cbranch_scc0 .LBB0_475
	v_readlane_b32 s96, v254, 56
	v_readlane_b32 s94, v254, 55
	v_readlane_b32 s97, v254, 57
	s_movk_i32 s95, 0xc0
	s_movk_i32 s92, 0x2c00

; #define PG8_STAGE(bufoff, gbase, voff) do { _Pragma("unroll") for (int _i = 0; _i < 2; ++_i) \
;         __builtin_amdgcn_global_load_lds((const unsigned*)((const char*)(gbase) + (voff)[_i]), (PG8_LAS unsigned*)(lds + (bufoff) + ldsw + _i * 8192), 16, 0, 0); } while (0)
; #define PG8_LDA(dst, b, h) do { _Pragma("unroll") for (int m = 0; m < 4; ++m) _Pragma("unroll") for (int k = 0; k < 2; ++k) dst[m][k] = *(const PG8_LAS bf16x8*)(lds + PG8_SA(b, h) + aoff + m * 2048 + k * 1024); } while (0)
; #define PG8_LDB(dst, b, h) do { _Pragma("unroll") for (int n = 0; n < 2; ++n) _Pragma("unroll") for (int k = 0; k < 2; ++k) dst[n][k] = *(const PG8_LAS bf16x8*)(lds + PG8_SB(b, h) + boff + n * 2048 + k * 1024); } while (0)
; #define PG8_MMA(ai, bj, At, Bt) do { __builtin_amdgcn_s_setprio(1); _Pragma("unroll") for (int m = 0; m < 4; ++m) _Pragma("unroll") for (int n = 0; n < 2; ++n) _Pragma("unroll") for (int k = 0; k < 2; ++k) \
;         acc[ai][bj][m][n] = __builtin_amdgcn_mfma_f32_16x16x32_bf16(Bt[n][k], At[m][k], acc[ai][bj][m][n], 0, 0, 0); __builtin_amdgcn_s_setprio(0); } while (0)
; #define PG8_WAIT_V(n) asm volatile("s_waitcnt vmcnt(" #n ")" ::: "memory")
; #define PG8_WAIT_L(n) asm volatile("s_waitcnt lgkmcnt(" #n ")" ::: "memory")
; template <class Epi, class Sched, bool ALIGN_EPI = false, bool SP2 = false>
; __device__ __forceinline__ void gemm_phase(PG8_LAS unsigned char* lds, const Gemm g, const Sched& S, const Epi& E) {
;     ...
;             const bool last = (t == nt - 2);
;             const char* a1 = cA + (size_t)(t + 1) * kstep;
;             const char* a2 = last ? nA : cA + (size_t)(t + 2) * kstep; const char* b2 = last ? nB : cB + (size_t)(t + 2) * kstep;
;             const char* a3 = a2 + kstep; const char* b3 = b2 + kstep;
;             if (last && has_next) S.a_ready(nxt);
;             if constexpr (SP2) {
;             PG8_LDB(B0, 0, 0); PG8_LDB(B1, 0, 1); PG8_SCHED; PG8_LDA(At, 0, 0); PG8_STAGE(PG8_SA(1, 1), a1 + hstep, voffA);
;             PG8_WAIT_V(8); PG8_WAIT_L(0); PG8_BAR; PG8_MMA(0, 0, At, B0); PG8_MMA(0, 1, At, B1); PG8_BAR; PG8_SCHED;
;             PG8_LDA(At, 0, 1); PG8_STAGE(PG8_SB(0, 0), b2, voffB); PG8_STAGE(PG8_SB(0, 1), b2 + hstep, voffB); PG8_STAGE(PG8_SA(0, 0), a2, voffA);
;             PG8_WAIT_V(8); PG8_WAIT_L(0); PG8_BAR; PG8_MMA(1, 0, At, B0); PG8_MMA(1, 1, At, B1); PG8_BAR; PG8_SCHED;
.LBB0_525:
	s_add_u32 s8, s42, s44
	s_addc_u32 s9, s43, s45
	s_add_u32 s8, s8, 0x100
	s_addc_u32 s9, s9, 0
	s_add_u32 s84, s10, s44
	s_addc_u32 s85, s11, s45
	s_add_i32 s86, 0, 0x10000
	s_cmp_eq_u32 s74, s83
	s_cselect_b32 s9, s1, s9
	s_cselect_b32 s8, s0, s8
	v_add_u32_e32 v149, s86, v157
	s_cselect_b32 s85, s41, s85
	s_cselect_b32 s84, s40, s84
	s_add_i32 s87, 0, 0x14000
	ds_read_b128 v[130:133], v149
	ds_read_b128 v[134:137], v149 offset:1024
	ds_read_b128 v[168:171], v149 offset:2048
	ds_read_b128 v[172:175], v149 offset:3072
	v_add_u32_e32 v149, s87, v157
	ds_read_b128 v[176:179], v149
	ds_read_b128 v[180:183], v149 offset:1024
	ds_read_b128 v[192:195], v149 offset:2048
	ds_read_b128 v[196:199], v149 offset:3072
	v_lshl_add_u64 v[166:167], v[152:153], 0, s[44:45]
	s_add_i32 m0, s49, 0xc000
	ds_read_b128 v[200:203], v159
	ds_read_b128 v[204:207], v159 offset:1024
	ds_read_b128 v[208:211], v159 offset:2048
	ds_read_b128 v[212:215], v159 offset:3072
	ds_read_b128 v[216:219], v159 offset:4096
	ds_read_b128 v[220:223], v159 offset:5120
	ds_read_b128 v[224:227], v159 offset:6144
	ds_read_b128 v[228:231], v159 offset:7168
	global_load_lds_dwordx4 v[166:167], off
	v_lshl_add_u64 v[166:167], v[154:155], 0, s[44:45]
	s_add_i32 m0, s49, 0xe000
	s_nop 0
	global_load_lds_dwordx4 v[166:167], off
	s_waitcnt vmcnt(8)
	s_waitcnt lgkmcnt(0)
	s_barrier
	s_setprio 1
	s_waitcnt lgkmcnt(0)
	v_mfma_f32_16x16x32_bf16 v[118:121], v[130:133], v[200:203], v[118:121]
	v_mfma_f32_16x16x32_bf16 v[126:129], v[168:171], v[200:203], v[126:129]
	v_mfma_f32_16x16x32_bf16 v[110:113], v[130:133], v[208:211], v[110:113]
	v_mfma_f32_16x16x32_bf16 v[106:109], v[168:171], v[208:211], v[106:109]
	v_mfma_f32_16x16x32_bf16 v[94:97], v[130:133], v[216:219], v[94:97]
	v_mfma_f32_16x16x32_bf16 v[90:93], v[168:171], v[216:219], v[90:93]
	v_mfma_f32_16x16x32_bf16 v[78:81], v[130:133], v[224:227], v[78:81]
	v_mfma_f32_16x16x32_bf16 v[74:77], v[168:171], v[224:227], v[74:77]
	v_mfma_f32_16x16x32_bf16 v[118:121], v[134:137], v[204:207], v[118:121]
	v_mfma_f32_16x16x32_bf16 v[126:129], v[172:175], v[204:207], v[126:129]
	v_mfma_f32_16x16x32_bf16 v[110:113], v[134:137], v[212:215], v[110:113]
	v_mfma_f32_16x16x32_bf16 v[106:109], v[172:175], v[212:215], v[106:109]
	v_mfma_f32_16x16x32_bf16 v[94:97], v[134:137], v[220:223], v[94:97]
	v_mfma_f32_16x16x32_bf16 v[90:93], v[172:175], v[220:223], v[90:93]
	v_mfma_f32_16x16x32_bf16 v[78:81], v[134:137], v[228:231], v[78:81]
	v_mfma_f32_16x16x32_bf16 v[74:77], v[172:175], v[228:231], v[74:77]
	s_setprio 0
	s_setprio 1
	v_mfma_f32_16x16x32_bf16 v[122:125], v[176:179], v[200:203], v[122:125]
	v_mfma_f32_16x16x32_bf16 v[114:117], v[192:195], v[200:203], v[114:117]
	v_mfma_f32_16x16x32_bf16 v[102:105], v[176:179], v[208:211], v[102:105]
	v_mfma_f32_16x16x32_bf16 v[98:101], v[192:195], v[208:211], v[98:101]
	v_mfma_f32_16x16x32_bf16 v[86:89], v[176:179], v[216:219], v[86:89]
	v_mfma_f32_16x16x32_bf16 v[82:85], v[192:195], v[216:219], v[82:85]
	v_mfma_f32_16x16x32_bf16 v[70:73], v[176:179], v[224:227], v[70:73]
	v_mfma_f32_16x16x32_bf16 v[66:69], v[192:195], v[224:227], v[66:69]
	v_mfma_f32_16x16x32_bf16 v[122:125], v[180:183], v[204:207], v[122:125]
	v_mfma_f32_16x16x32_bf16 v[114:117], v[196:199], v[204:207], v[114:117]
	v_mfma_f32_16x16x32_bf16 v[102:105], v[180:183], v[212:215], v[102:105]
	v_mfma_f32_16x16x32_bf16 v[98:101], v[196:199], v[212:215], v[98:101]
	v_mfma_f32_16x16x32_bf16 v[86:89], v[180:183], v[220:223], v[86:89]
	v_mfma_f32_16x16x32_bf16 v[82:85], v[196:199], v[220:223], v[82:85]
	v_mfma_f32_16x16x32_bf16 v[70:73], v[180:183], v[228:231], v[70:73]
	v_mfma_f32_16x16x32_bf16 v[66:69], v[196:199], v[228:231], v[66:69]
	s_setprio 0
	s_barrier
	s_add_i32 s86, s86, s48
	v_lshl_add_u64 v[166:167], s[84:85], 0, v[160:161]
	s_mov_b32 m0, s86
	ds_read_b128 v[200:203], v159 offset:16384
	ds_read_b128 v[204:207], v159 offset:17408
	ds_read_b128 v[208:211], v159 offset:18432
	ds_read_b128 v[212:215], v159 offset:19456
	ds_read_b128 v[216:219], v159 offset:20480
	ds_read_b128 v[220:223], v159 offset:21504
	ds_read_b128 v[224:227], v159 offset:22528
	ds_read_b128 v[228:231], v159 offset:23552
	global_load_lds_dwordx4 v[166:167], off
	s_add_i32 m0, s86, 0x2000
	v_lshl_add_u64 v[184:185], s[84:85], 0, v[142:143]
	s_add_u32 s84, s84, s22
	s_addc_u32 s85, s85, s23
	s_add_i32 s86, s87, s48
	global_load_lds_dwordx4 v[184:185], off
	v_lshl_add_u64 v[232:233], s[84:85], 0, v[160:161]
	s_mov_b32 m0, s86
	v_lshl_add_u64 v[234:235], s[84:85], 0, v[142:143]
	global_load_lds_dwordx4 v[232:233], off
	s_add_i32 m0, s86, 0x2000
	v_lshl_add_u64 v[236:237], s[8:9], 0, v[138:139]
	global_load_lds_dwordx4 v[234:235], off
	v_lshl_add_u64 v[238:239], s[8:9], 0, v[140:141]
	s_nop 0
	s_waitcnt vmcnt(6)
	s_waitcnt lgkmcnt(0)
	s_barrier
; #define PG8_STAGE(bufoff, gbase, voff) do { _Pragma("unroll") for (int _i = 0; _i < 2; ++_i) \
;         __builtin_amdgcn_global_load_lds((const unsigned*)((const char*)(gbase) + (voff)[_i]), (PG8_LAS unsigned*)(lds + (bufoff) + ldsw + _i * 8192), 16, 0, 0); } while (0)
; #define PG8_LDA(dst, b, h) do { _Pragma("unroll") for (int m = 0; m < 4; ++m) _Pragma("unroll") for (int k = 0; k < 2; ++k) dst[m][k] = *(const PG8_LAS bf16x8*)(lds + PG8_SA(b, h) + aoff + m * 2048 + k * 1024); } while (0)
; #define PG8_LDB(dst, b, h) do { _Pragma("unroll") for (int n = 0; n < 2; ++n) _Pragma("unroll") for (int k = 0; k < 2; ++k) dst[n][k] = *(const PG8_LAS bf16x8*)(lds + PG8_SB(b, h) + boff + n * 2048 + k * 1024); } while (0)
; #define PG8_MMA(ai, bj, At, Bt) do { __builtin_amdgcn_s_setprio(1); _Pragma("unroll") for (int m = 0; m < 4; ++m) _Pragma("unroll") for (int n = 0; n < 2; ++n) _Pragma("unroll") for (int k = 0; k < 2; ++k) \
;         acc[ai][bj][m][n] = __builtin_amdgcn_mfma_f32_16x16x32_bf16(Bt[n][k], At[m][k], acc[ai][bj][m][n], 0, 0, 0); __builtin_amdgcn_s_setprio(0); } while (0)
; #define PG8_WAIT_V(n) asm volatile("s_waitcnt vmcnt(" #n ")" ::: "memory")
; #define PG8_WAIT_L(n) asm volatile("s_waitcnt lgkmcnt(" #n ")" ::: "memory")
; #define PG8_BAR __builtin_amdgcn_s_barrier()
; #define PG8_SCHED __builtin_amdgcn_sched_barrier(0)
; template <class Epi, class Sched, bool ALIGN_EPI = false, bool SP2 = false>
; __device__ __forceinline__ void gemm_phase(PG8_LAS unsigned char* lds, const Gemm g, const Sched& S, const Epi& E) {
;     ...
;             PG8_WAIT_V(8); PG8_WAIT_L(0); PG8_BAR; PG8_MMA(1, 0, At, B0); PG8_MMA(1, 1, At, B1); PG8_BAR; PG8_SCHED;
;             PG8_LDB(B0, 1, 0); PG8_LDB(B1, 1, 1); PG8_SCHED; PG8_LDA(At, 1, 0); PG8_STAGE(PG8_SA(0, 1), a2 + hstep, voffA);
;             PG8_WAIT_V(8); PG8_WAIT_L(0); PG8_BAR; PG8_MMA(0, 0, At, B0); PG8_MMA(0, 1, At, B1); PG8_BAR; PG8_SCHED;
	s_setprio 1
	s_waitcnt lgkmcnt(0)
	v_mfma_f32_16x16x32_bf16 v[62:65], v[130:133], v[200:203], v[62:65]
	v_mfma_f32_16x16x32_bf16 v[58:61], v[168:171], v[200:203], v[58:61]
	v_mfma_f32_16x16x32_bf16 v[46:49], v[130:133], v[208:211], v[46:49]
	v_mfma_f32_16x16x32_bf16 v[42:45], v[168:171], v[208:211], v[42:45]
	v_mfma_f32_16x16x32_bf16 v[30:33], v[130:133], v[216:219], v[30:33]
	v_mfma_f32_16x16x32_bf16 v[26:29], v[168:171], v[216:219], v[26:29]
	v_mfma_f32_16x16x32_bf16 v[14:17], v[130:133], v[224:227], v[14:17]
	v_mfma_f32_16x16x32_bf16 v[10:13], v[168:171], v[224:227], v[10:13]
	v_mfma_f32_16x16x32_bf16 v[62:65], v[134:137], v[204:207], v[62:65]
	v_mfma_f32_16x16x32_bf16 v[58:61], v[172:175], v[204:207], v[58:61]
	v_mfma_f32_16x16x32_bf16 v[46:49], v[134:137], v[212:215], v[46:49]
	v_mfma_f32_16x16x32_bf16 v[42:45], v[172:175], v[212:215], v[42:45]
	v_mfma_f32_16x16x32_bf16 v[30:33], v[134:137], v[220:223], v[30:33]
	v_mfma_f32_16x16x32_bf16 v[26:29], v[172:175], v[220:223], v[26:29]
	v_mfma_f32_16x16x32_bf16 v[14:17], v[134:137], v[228:231], v[14:17]
	v_mfma_f32_16x16x32_bf16 v[10:13], v[172:175], v[228:231], v[10:13]
	s_setprio 0
	s_setprio 1
	v_mfma_f32_16x16x32_bf16 v[54:57], v[176:179], v[200:203], v[54:57]
	v_mfma_f32_16x16x32_bf16 v[50:53], v[192:195], v[200:203], v[50:53]
	v_mfma_f32_16x16x32_bf16 v[38:41], v[176:179], v[208:211], v[38:41]
	v_mfma_f32_16x16x32_bf16 v[34:37], v[192:195], v[208:211], v[34:37]
	v_mfma_f32_16x16x32_bf16 v[22:25], v[176:179], v[216:219], v[22:25]
	v_mfma_f32_16x16x32_bf16 v[18:21], v[192:195], v[216:219], v[18:21]
	v_mfma_f32_16x16x32_bf16 v[6:9], v[176:179], v[224:227], v[6:9]
	v_mfma_f32_16x16x32_bf16 v[2:5], v[192:195], v[224:227], v[2:5]
	v_mfma_f32_16x16x32_bf16 v[54:57], v[180:183], v[204:207], v[54:57]
	v_mfma_f32_16x16x32_bf16 v[50:53], v[196:199], v[204:207], v[50:53]
	v_mfma_f32_16x16x32_bf16 v[38:41], v[180:183], v[212:215], v[38:41]
	v_mfma_f32_16x16x32_bf16 v[34:37], v[196:199], v[212:215], v[34:37]
	v_mfma_f32_16x16x32_bf16 v[22:25], v[180:183], v[220:223], v[22:25]
	v_mfma_f32_16x16x32_bf16 v[18:21], v[196:199], v[220:223], v[18:21]
	v_mfma_f32_16x16x32_bf16 v[6:9], v[180:183], v[228:231], v[6:9]
	v_mfma_f32_16x16x32_bf16 v[2:5], v[196:199], v[228:231], v[2:5]
	s_setprio 0
	s_barrier
	s_add_i32 s84, 0, 0x18000
	v_add_u32_e32 v149, s84, v157
	s_add_i32 s85, 0, 0x1c000
	ds_read_b128 v[130:133], v149
	ds_read_b128 v[134:137], v149 offset:1024
	ds_read_b128 v[168:171], v149 offset:2048
	ds_read_b128 v[172:175], v149 offset:3072
	v_add_u32_e32 v149, s85, v157
	ds_read_b128 v[176:179], v149
	ds_read_b128 v[180:183], v149 offset:1024
	ds_read_b128 v[192:195], v149 offset:2048
	ds_read_b128 v[196:199], v149 offset:3072
	s_add_u32 s8, s8, s22
	s_addc_u32 s9, s9, s23
	s_mov_b32 m0, s49
	s_nop 0
	global_load_lds_dwordx4 v[236:237], off
	s_mov_b32 m0, s50
	s_nop 0
	global_load_lds_dwordx4 v[238:239], off
	s_mov_b32 m0, s51
	v_lshl_add_u64 v[240:241], s[8:9], 0, v[138:139]
	ds_read_b128 v[200:203], v159 offset:32768
	ds_read_b128 v[204:207], v159 offset:33792
	ds_read_b128 v[208:211], v159 offset:34816
	ds_read_b128 v[212:215], v159 offset:35840
	ds_read_b128 v[216:219], v159 offset:36864
	ds_read_b128 v[220:223], v159 offset:37888
	ds_read_b128 v[224:227], v159 offset:38912
	ds_read_b128 v[228:231], v159 offset:39936
	global_load_lds_dwordx4 v[240:241], off
	v_lshl_add_u64 v[240:241], s[8:9], 0, v[140:141]
	s_mov_b32 m0, s52
	s_nop 0
	global_load_lds_dwordx4 v[240:241], off
	s_waitcnt vmcnt(8)
	s_waitcnt lgkmcnt(0)
	s_barrier
	s_setprio 1
	s_waitcnt lgkmcnt(0)
	v_mfma_f32_16x16x32_bf16 v[118:121], v[130:133], v[200:203], v[118:121]
	v_mfma_f32_16x16x32_bf16 v[126:129], v[168:171], v[200:203], v[126:129]
	v_mfma_f32_16x16x32_bf16 v[110:113], v[130:133], v[208:211], v[110:113]
	v_mfma_f32_16x16x32_bf16 v[106:109], v[168:171], v[208:211], v[106:109]
	v_mfma_f32_16x16x32_bf16 v[94:97], v[130:133], v[216:219], v[94:97]
	v_mfma_f32_16x16x32_bf16 v[90:93], v[168:171], v[216:219], v[90:93]
	v_mfma_f32_16x16x32_bf16 v[78:81], v[130:133], v[224:227], v[78:81]
	v_mfma_f32_16x16x32_bf16 v[74:77], v[168:171], v[224:227], v[74:77]
	v_mfma_f32_16x16x32_bf16 v[118:121], v[134:137], v[204:207], v[118:121]
	v_mfma_f32_16x16x32_bf16 v[126:129], v[172:175], v[204:207], v[126:129]
	v_mfma_f32_16x16x32_bf16 v[110:113], v[134:137], v[212:215], v[110:113]
	v_mfma_f32_16x16x32_bf16 v[106:109], v[172:175], v[212:215], v[106:109]
	v_mfma_f32_16x16x32_bf16 v[94:97], v[134:137], v[220:223], v[94:97]
	v_mfma_f32_16x16x32_bf16 v[90:93], v[172:175], v[220:223], v[90:93]
	v_mfma_f32_16x16x32_bf16 v[78:81], v[134:137], v[228:231], v[78:81]
	v_mfma_f32_16x16x32_bf16 v[74:77], v[172:175], v[228:231], v[74:77]
	s_setprio 0
	s_setprio 1
	v_mfma_f32_16x16x32_bf16 v[122:125], v[176:179], v[200:203], v[122:125]
	v_mfma_f32_16x16x32_bf16 v[114:117], v[192:195], v[200:203], v[114:117]
	v_mfma_f32_16x16x32_bf16 v[102:105], v[176:179], v[208:211], v[102:105]
	v_mfma_f32_16x16x32_bf16 v[98:101], v[192:195], v[208:211], v[98:101]
	v_mfma_f32_16x16x32_bf16 v[86:89], v[176:179], v[216:219], v[86:89]
	v_mfma_f32_16x16x32_bf16 v[82:85], v[192:195], v[216:219], v[82:85]
	v_mfma_f32_16x16x32_bf16 v[70:73], v[176:179], v[224:227], v[70:73]
	v_mfma_f32_16x16x32_bf16 v[66:69], v[192:195], v[224:227], v[66:69]
	v_mfma_f32_16x16x32_bf16 v[122:125], v[180:183], v[204:207], v[122:125]
	v_mfma_f32_16x16x32_bf16 v[114:117], v[196:199], v[204:207], v[114:117]
	v_mfma_f32_16x16x32_bf16 v[102:105], v[180:183], v[212:215], v[102:105]
	v_mfma_f32_16x16x32_bf16 v[98:101], v[196:199], v[212:215], v[98:101]
	v_mfma_f32_16x16x32_bf16 v[86:89], v[180:183], v[220:223], v[86:89]
	v_mfma_f32_16x16x32_bf16 v[82:85], v[196:199], v[220:223], v[82:85]
	v_mfma_f32_16x16x32_bf16 v[70:73], v[180:183], v[228:231], v[70:73]
	v_mfma_f32_16x16x32_bf16 v[66:69], v[196:199], v[228:231], v[66:69]
	s_setprio 0
	s_barrier
; #define PG8_STAGE(bufoff, gbase, voff) do { _Pragma("unroll") for (int _i = 0; _i < 2; ++_i) \
;         __builtin_amdgcn_global_load_lds((const unsigned*)((const char*)(gbase) + (voff)[_i]), (PG8_LAS unsigned*)(lds + (bufoff) + ldsw + _i * 8192), 16, 0, 0); } while (0)
; #define PG8_LDA(dst, b, h) do { _Pragma("unroll") for (int m = 0; m < 4; ++m) _Pragma("unroll") for (int k = 0; k < 2; ++k) dst[m][k] = *(const PG8_LAS bf16x8*)(lds + PG8_SA(b, h) + aoff + m * 2048 + k * 1024); } while (0)
; #define PG8_MMA(ai, bj, At, Bt) do { __builtin_amdgcn_s_setprio(1); _Pragma("unroll") for (int m = 0; m < 4; ++m) _Pragma("unroll") for (int n = 0; n < 2; ++n) _Pragma("unroll") for (int k = 0; k < 2; ++k) \
;         acc[ai][bj][m][n] = __builtin_amdgcn_mfma_f32_16x16x32_bf16(Bt[n][k], At[m][k], acc[ai][bj][m][n], 0, 0, 0); __builtin_amdgcn_s_setprio(0); } while (0)
; #define PG8_WAIT_V(n) asm volatile("s_waitcnt vmcnt(" #n ")" ::: "memory")
; #define PG8_WAIT_L(n) asm volatile("s_waitcnt lgkmcnt(" #n ")" ::: "memory")
; template <class Epi, class Sched, bool ALIGN_EPI = false, bool SP2 = false>
; __device__ __forceinline__ void gemm_phase(PG8_LAS unsigned char* lds, const Gemm g, const Sched& S, const Epi& E) {
;     ...
;             PG8_LDA(At, 1, 1); PG8_STAGE(PG8_SB(1, 0), b3, voffB); PG8_STAGE(PG8_SB(1, 1), b3 + hstep, voffB); PG8_STAGE(PG8_SA(1, 0), a3, voffA);
;             PG8_WAIT_V(8); PG8_WAIT_L(0); PG8_BAR; PG8_MMA(1, 0, At, B0); PG8_MMA(1, 1, At, B1); PG8_BAR; PG8_SCHED;
;     __device__ __forceinline__ void mid(f32x4 (&acc)[2][2][4][2], const Unit& u, int wr, int wc, int fr, int fq) const {
;         int rowb = u.pm * 256 + wr * 64 + fr, cb = u.pn * 256 + wc * 32 + 8 * fq;
;         asm volatile("" : "+v"(rowb), "+v"(cb));
; #pragma unroll
;         EP_ROWLOOP { EpFence fence_{(m & 1) == 1};
;             const int row = rowb + ai * 128 + m * 16;
; #pragma unroll
;             for (int bj = 0; bj < 2; ++bj) {
;                 const bf16_t* g = sg + (size_t)row * 4096 + cb + bj * 128; f32x4 a0, a1, b0, b1;
;                 unpack8(*(const u32x4*)g, a0, a1); unpack8(*(const u32x4*)(g + 2048), b0, b1);
; #pragma unroll
;                 for (int q = 0; q < 4; ++q) { acc[ai][bj][m][0][q] *= a0[q] * __builtin_amdgcn_rcpf(fmaxf(b0[q], 1e-30f)); acc[ai][bj][m][1][q] *= a1[q] * __builtin_amdgcn_rcpf(fmaxf(b1[q], 1e-30f)); }
	s_add_i32 s8, s84, s48
	v_lshl_add_u64 v[166:167], v[166:167], 0, s[88:89]
	s_mov_b32 m0, s8
	ds_read_b128 v[200:203], v159 offset:49152
	ds_read_b128 v[204:207], v159 offset:50176
	ds_read_b128 v[208:211], v159 offset:51200
	ds_read_b128 v[212:215], v159 offset:52224
	ds_read_b128 v[216:219], v159 offset:53248
	ds_read_b128 v[220:223], v159 offset:54272
	ds_read_b128 v[224:227], v159 offset:55296
	ds_read_b128 v[228:231], v159 offset:56320
	global_load_lds_dwordx4 v[166:167], off
	v_lshl_add_u64 v[166:167], v[184:185], 0, s[88:89]
	s_add_i32 m0, s8, 0x2000
	s_add_i32 s8, s85, s48
	global_load_lds_dwordx4 v[166:167], off
	v_lshl_add_u64 v[166:167], v[232:233], 0, s[88:89]
	s_mov_b32 m0, s8
	s_nop 0
	global_load_lds_dwordx4 v[166:167], off
	v_lshl_add_u64 v[166:167], v[234:235], 0, s[88:89]
	s_add_i32 m0, s8, 0x2000
	s_nop 0
	global_load_lds_dwordx4 v[166:167], off
	v_lshl_add_u64 v[166:167], v[236:237], 0, s[88:89]
	s_mov_b32 m0, s53
	s_nop 0
	global_load_lds_dwordx4 v[166:167], off
	v_lshl_add_u64 v[166:167], v[238:239], 0, s[88:89]
	s_mov_b32 m0, s56
	s_nop 0
	global_load_lds_dwordx4 v[166:167], off
	s_waitcnt vmcnt(8)
	s_waitcnt lgkmcnt(0)
	s_barrier
	s_setprio 1
	s_waitcnt lgkmcnt(0)
	v_mfma_f32_16x16x32_bf16 v[62:65], v[130:133], v[200:203], v[62:65]
	v_mfma_f32_16x16x32_bf16 v[58:61], v[168:171], v[200:203], v[58:61]
	v_mfma_f32_16x16x32_bf16 v[46:49], v[130:133], v[208:211], v[46:49]
	v_mfma_f32_16x16x32_bf16 v[42:45], v[168:171], v[208:211], v[42:45]
	v_mfma_f32_16x16x32_bf16 v[30:33], v[130:133], v[216:219], v[30:33]
	v_mfma_f32_16x16x32_bf16 v[26:29], v[168:171], v[216:219], v[26:29]
	v_mfma_f32_16x16x32_bf16 v[14:17], v[130:133], v[224:227], v[14:17]
	v_mfma_f32_16x16x32_bf16 v[10:13], v[168:171], v[224:227], v[10:13]
	v_mfma_f32_16x16x32_bf16 v[62:65], v[134:137], v[204:207], v[62:65]
	v_mfma_f32_16x16x32_bf16 v[58:61], v[172:175], v[204:207], v[58:61]
	v_mfma_f32_16x16x32_bf16 v[46:49], v[134:137], v[212:215], v[46:49]
	v_mfma_f32_16x16x32_bf16 v[42:45], v[172:175], v[212:215], v[42:45]
	v_mfma_f32_16x16x32_bf16 v[30:33], v[134:137], v[220:223], v[30:33]
	v_mfma_f32_16x16x32_bf16 v[26:29], v[172:175], v[220:223], v[26:29]
	v_mfma_f32_16x16x32_bf16 v[14:17], v[134:137], v[228:231], v[14:17]
	v_mfma_f32_16x16x32_bf16 v[10:13], v[172:175], v[228:231], v[10:13]
	s_setprio 0
	s_setprio 1
	v_mfma_f32_16x16x32_bf16 v[54:57], v[176:179], v[200:203], v[54:57]
	v_mfma_f32_16x16x32_bf16 v[50:53], v[192:195], v[200:203], v[50:53]
	v_mfma_f32_16x16x32_bf16 v[38:41], v[176:179], v[208:211], v[38:41]
	v_mfma_f32_16x16x32_bf16 v[34:37], v[192:195], v[208:211], v[34:37]
	v_mfma_f32_16x16x32_bf16 v[22:25], v[176:179], v[216:219], v[22:25]
	v_mfma_f32_16x16x32_bf16 v[18:21], v[192:195], v[216:219], v[18:21]
	v_mfma_f32_16x16x32_bf16 v[6:9], v[176:179], v[224:227], v[6:9]
	v_mfma_f32_16x16x32_bf16 v[2:5], v[192:195], v[224:227], v[2:5]
	v_mfma_f32_16x16x32_bf16 v[54:57], v[180:183], v[204:207], v[54:57]
	v_mfma_f32_16x16x32_bf16 v[50:53], v[196:199], v[204:207], v[50:53]
	v_mfma_f32_16x16x32_bf16 v[38:41], v[180:183], v[212:215], v[38:41]
	v_mfma_f32_16x16x32_bf16 v[34:37], v[196:199], v[212:215], v[34:37]
	v_mfma_f32_16x16x32_bf16 v[22:25], v[180:183], v[220:223], v[22:25]
	v_mfma_f32_16x16x32_bf16 v[18:21], v[196:199], v[220:223], v[18:21]
	v_mfma_f32_16x16x32_bf16 v[6:9], v[180:183], v[228:231], v[6:9]
	v_mfma_f32_16x16x32_bf16 v[2:5], v[196:199], v[228:231], v[2:5]
	s_setprio 0
	s_barrier
	s_cmp_lg_u32 s75, s83
	s_cbranch_scc1 .LBB0_524
	v_mov_b32_e32 v130, v148
	v_mov_b32_e32 v132, v150
	s_mov_b64 s[8:9], 0x20000
	v_ashrrev_i32_e32 v131, 31, v130
	v_lshlrev_b64 v[130:131], 13, v[130:131]
	v_ashrrev_i32_e32 v133, 31, v132
	v_lshl_add_u64 v[130:131], s[28:29], 0, v[130:131]
	v_lshl_add_u64 v[134:135], v[132:133], 1, v[130:131]
	v_add_co_u32_e32 v130, vcc, 0x1000, v134
	global_load_dwordx4 v[168:171], v[134:135], off
	s_nop 0
	v_addc_co_u32_e32 v131, vcc, 0, v135, vcc
	global_load_dwordx4 v[172:175], v[130:131], off
	s_waitcnt vmcnt(0)
	v_lshlrev_b32_e32 v166, 16, v168
	v_and_b32_e32 v167, 0xffff0000, v168
	v_lshlrev_b32_e32 v132, 16, v172
	v_and_b32_e32 v133, 0xffff0000, v172
	v_max_f32_e32 v132, v132, v132
	v_max_f32_e32 v133, v133, v133
	v_max_f32_e32 v132, 0xda24260, v132
	v_max_f32_e32 v133, 0xda24260, v133
	v_rcp_f32_e32 v132, v132
	v_rcp_f32_e32 v133, v133
	v_lshlrev_b32_e32 v136, 16, v174
	v_and_b32_e32 v137, 0xffff0000, v174
	v_max_f32_e32 v136, v136, v136
	v_pk_mul_f32 v[132:133], v[132:133], v[166:167]
	v_max_f32_e32 v136, 0xda24260, v136
	v_pk_mul_f32 v[118:119], v[118:119], v[132:133]
	v_max_f32_e32 v132, v137, v137
	v_max_f32_e32 v132, 0xda24260, v132
	v_rcp_f32_e32 v136, v136
	v_rcp_f32_e32 v137, v132
	v_lshlrev_b32_e32 v132, 16, v170
	v_and_b32_e32 v133, 0xffff0000, v170
	v_lshlrev_b32_e32 v172, 16, v175
	v_pk_mul_f32 v[132:133], v[136:137], v[132:133]
	v_lshlrev_b32_e32 v149, 16, v173
	v_pk_mul_f32 v[126:127], v[126:127], v[132:133]
	v_max_f32_e32 v133, v172, v172
	v_and_b32_e32 v151, 0xffff0000, v173
	v_max_f32_e32 v133, 0xda24260, v133
	v_max_f32_e32 v132, v149, v149
	v_rcp_f32_e32 v136, v133
	v_max_f32_e32 v133, v151, v151
	v_max_f32_e32 v132, 0xda24260, v132
	v_max_f32_e32 v133, 0xda24260, v133
	v_rcp_f32_e32 v132, v132
	v_rcp_f32_e32 v133, v133
	v_lshlrev_b32_e32 v166, 16, v169
	v_and_b32_e32 v167, 0xffff0000, v169
	v_and_b32_e32 v173, 0xffff0000, v175
	v_pk_mul_f32 v[132:133], v[132:133], v[166:167]
	s_nop 0
	v_pk_mul_f32 v[120:121], v[120:121], v[132:133]
	v_max_f32_e32 v132, v173, v173
	v_max_f32_e32 v132, 0xda24260, v132
	v_rcp_f32_e32 v137, v132
	v_lshlrev_b32_e32 v132, 16, v171
	v_and_b32_e32 v133, 0xffff0000, v171
	v_pk_mul_f32 v[132:133], v[136:137], v[132:133]
	s_nop 0
	v_pk_mul_f32 v[128:129], v[128:129], v[132:133]
	global_load_dwordx4 v[168:171], v[134:135], off offset:256
	s_nop 0
	global_load_dwordx4 v[130:133], v[130:131], off offset:256
	s_waitcnt vmcnt(0)
;     __device__ __forceinline__ void mid(f32x4 (&acc)[2][2][4][2], const Unit& u, int wr, int wc, int fr, int fq) const {
;     ...
;             for (int bj = 0; bj < 2; ++bj) {
;                 const bf16_t* g = sg + (size_t)row * 4096 + cb + bj * 128; f32x4 a0, a1, b0, b1;
;                 unpack8(*(const u32x4*)g, a0, a1); unpack8(*(const u32x4*)(g + 2048), b0, b1);
; #pragma unroll
;                 for (int q = 0; q < 4; ++q) { acc[ai][bj][m][0][q] *= a0[q] * __builtin_amdgcn_rcpf(fmaxf(b0[q], 1e-30f)); acc[ai][bj][m][1][q] *= a1[q] * __builtin_amdgcn_rcpf(fmaxf(b1[q], 1e-30f)); }
	v_lshlrev_b32_e32 v149, 16, v131
	v_and_b32_e32 v151, 0xffff0000, v131
	v_lshlrev_b32_e32 v131, 16, v132
	v_max_f32_e32 v131, v131, v131
	v_lshlrev_b32_e32 v136, 16, v130
	v_and_b32_e32 v137, 0xffff0000, v130
	v_max_f32_e32 v131, 0xda24260, v131
	v_and_b32_e32 v166, 0xffff0000, v132
	v_max_f32_e32 v130, v136, v136
	v_rcp_f32_e32 v132, v131
	v_max_f32_e32 v131, v137, v137
	v_max_f32_e32 v130, 0xda24260, v130
	v_max_f32_e32 v131, 0xda24260, v131
	v_rcp_f32_e32 v130, v130
	v_rcp_f32_e32 v131, v131
	v_lshlrev_b32_e32 v136, 16, v168
	v_and_b32_e32 v137, 0xffff0000, v168
	v_lshlrev_b32_e32 v167, 16, v133
	v_pk_mul_f32 v[130:131], v[130:131], v[136:137]
	v_and_b32_e32 v172, 0xffff0000, v133
	v_pk_mul_f32 v[122:123], v[122:123], v[130:131]
	v_max_f32_e32 v130, v166, v166
	v_max_f32_e32 v130, 0xda24260, v130
	v_rcp_f32_e32 v133, v130
	v_lshlrev_b32_e32 v130, 16, v170
	v_and_b32_e32 v131, 0xffff0000, v170
	v_lshlrev_b32_e32 v136, 16, v169
	v_pk_mul_f32 v[130:131], v[132:133], v[130:131]
	v_and_b32_e32 v137, 0xffff0000, v169
	v_pk_mul_f32 v[114:115], v[114:115], v[130:131]
	v_max_f32_e32 v131, v167, v167
	v_max_f32_e32 v131, 0xda24260, v131
	v_max_f32_e32 v130, v149, v149
	v_rcp_f32_e32 v132, v131
	v_max_f32_e32 v131, v151, v151
	v_max_f32_e32 v130, 0xda24260, v130
	v_max_f32_e32 v131, 0xda24260, v131
	v_rcp_f32_e32 v130, v130
	v_rcp_f32_e32 v131, v131
	s_nop 0
	v_pk_mul_f32 v[130:131], v[130:131], v[136:137]
	s_nop 0
	v_pk_mul_f32 v[124:125], v[124:125], v[130:131]
	v_max_f32_e32 v130, v172, v172
	v_max_f32_e32 v130, 0xda24260, v130
	v_rcp_f32_e32 v133, v130
	v_lshlrev_b32_e32 v130, 16, v171
	v_and_b32_e32 v131, 0xffff0000, v171
	v_pk_mul_f32 v[130:131], v[132:133], v[130:131]
	s_nop 0
	v_pk_mul_f32 v[116:117], v[116:117], v[130:131]
	v_lshl_add_u64 v[130:131], v[134:135], 0, s[8:9]
	s_mov_b32 s8, 0x21000
	v_add_co_u32_e32 v136, vcc, s8, v134
	s_mov_b64 s[8:9], 0x40000
	s_nop 0
	v_addc_co_u32_e32 v137, vcc, 0, v135, vcc
	global_load_dwordx4 v[168:171], v[136:137], off offset:-4096
	global_load_dwordx4 v[172:175], v[136:137], off
	s_waitcnt vmcnt(0)
	v_lshlrev_b32_e32 v132, 16, v172
	v_and_b32_e32 v133, 0xffff0000, v172
	v_max_f32_e32 v132, v132, v132
	v_max_f32_e32 v133, v133, v133
	v_max_f32_e32 v132, 0xda24260, v132
	v_max_f32_e32 v133, 0xda24260, v133
	v_rcp_f32_e32 v132, v132
	v_rcp_f32_e32 v133, v133
	v_lshlrev_b32_e32 v149, 16, v173
	v_and_b32_e32 v151, 0xffff0000, v173
	v_lshlrev_b32_e32 v172, 16, v168
	v_and_b32_e32 v173, 0xffff0000, v168
	v_lshlrev_b32_e32 v166, 16, v174
	v_and_b32_e32 v167, 0xffff0000, v174
	v_pk_mul_f32 v[132:133], v[132:133], v[172:173]
	v_max_f32_e32 v166, v166, v166
	v_pk_mul_f32 v[110:111], v[110:111], v[132:133]
	v_max_f32_e32 v132, v167, v167
	v_max_f32_e32 v166, 0xda24260, v166
	v_max_f32_e32 v132, 0xda24260, v132
	v_rcp_f32_e32 v166, v166
	v_rcp_f32_e32 v167, v132
	v_lshlrev_b32_e32 v132, 16, v170
	v_and_b32_e32 v133, 0xffff0000, v170
	v_lshlrev_b32_e32 v174, 16, v175
	v_pk_mul_f32 v[132:133], v[166:167], v[132:133]
	v_lshlrev_b32_e32 v168, 16, v169
	v_pk_mul_f32 v[106:107], v[106:107], v[132:133]
	v_max_f32_e32 v133, v174, v174
	v_max_f32_e32 v133, 0xda24260, v133
	v_max_f32_e32 v132, v149, v149
	v_rcp_f32_e32 v166, v133
	v_max_f32_e32 v133, v151, v151
	v_max_f32_e32 v132, 0xda24260, v132
	v_max_f32_e32 v133, 0xda24260, v133
	v_rcp_f32_e32 v132, v132
	v_rcp_f32_e32 v133, v133
	v_and_b32_e32 v169, 0xffff0000, v169
	v_and_b32_e32 v175, 0xffff0000, v175
	v_pk_mul_f32 v[132:133], v[132:133], v[168:169]
	s_nop 0
	v_pk_mul_f32 v[112:113], v[112:113], v[132:133]
	v_max_f32_e32 v132, v175, v175
	v_max_f32_e32 v132, 0xda24260, v132
	v_rcp_f32_e32 v167, v132
	v_lshlrev_b32_e32 v132, 16, v171
	v_and_b32_e32 v133, 0xffff0000, v171
	v_pk_mul_f32 v[132:133], v[166:167], v[132:133]
	s_nop 0
	v_pk_mul_f32 v[108:109], v[108:109], v[132:133]
	global_load_dwordx4 v[130:133], v[130:131], off offset:256
	s_nop 0
	global_load_dwordx4 v[168:171], v[136:137], off offset:256
	s_waitcnt vmcnt(0)
	v_lshlrev_b32_e32 v136, 16, v168
	v_and_b32_e32 v137, 0xffff0000, v168
	v_max_f32_e32 v136, v136, v136
	v_max_f32_e32 v137, v137, v137
	v_lshlrev_b32_e32 v166, 16, v170
	v_and_b32_e32 v167, 0xffff0000, v170
	v_max_f32_e32 v136, 0xda24260, v136
	v_max_f32_e32 v137, 0xda24260, v137
	v_lshlrev_b32_e32 v149, 16, v169
	v_and_b32_e32 v151, 0xffff0000, v169
	v_rcp_f32_e32 v136, v136
	v_max_f32_e32 v166, v166, v166
	v_rcp_f32_e32 v137, v137
	v_lshlrev_b32_e32 v168, 16, v130
	v_and_b32_e32 v169, 0xffff0000, v130
	v_max_f32_e32 v130, v167, v167
	v_max_f32_e32 v166, 0xda24260, v166
	v_max_f32_e32 v130, 0xda24260, v130
	v_rcp_f32_e32 v166, v166
	v_rcp_f32_e32 v167, v130
	v_pk_mul_f32 v[136:137], v[136:137], v[168:169]
	v_max_f32_e32 v130, v149, v149
	v_pk_mul_f32 v[102:103], v[102:103], v[136:137]
	v_lshlrev_b32_e32 v136, 16, v132
	v_and_b32_e32 v137, 0xffff0000, v132
	v_max_f32_e32 v132, v151, v151
	v_lshlrev_b32_e32 v170, 16, v171
	v_and_b32_e32 v171, 0xffff0000, v171
	v_pk_mul_f32 v[136:137], v[166:167], v[136:137]
	v_max_f32_e32 v130, 0xda24260, v130
	v_max_f32_e32 v132, 0xda24260, v132
	v_pk_mul_f32 v[98:99], v[98:99], v[136:137]
	v_rcp_f32_e32 v136, v130
	v_max_f32_e32 v130, v170, v170
	v_rcp_f32_e32 v137, v132
	v_lshlrev_b32_e32 v166, 16, v131
	v_and_b32_e32 v167, 0xffff0000, v131
	v_max_f32_e32 v131, v171, v171
	v_max_f32_e32 v130, 0xda24260, v130
	v_max_f32_e32 v131, 0xda24260, v131
	v_rcp_f32_e32 v130, v130
	v_rcp_f32_e32 v131, v131
	v_pk_mul_f32 v[136:137], v[136:137], v[166:167]
	v_lshl_add_u64 v[166:167], v[134:135], 0, s[8:9]
	s_mov_b32 s8, 0x41000
	v_pk_mul_f32 v[104:105], v[104:105], v[136:137]
	v_lshlrev_b32_e32 v132, 16, v133
	v_and_b32_e32 v133, 0xffff0000, v133
	v_add_co_u32_e32 v136, vcc, s8, v134
	v_pk_mul_f32 v[130:131], v[130:131], v[132:133]
	s_nop 0
	v_addc_co_u32_e32 v137, vcc, 0, v135, vcc
	v_pk_mul_f32 v[100:101], v[100:101], v[130:131]
	global_load_dwordx4 v[130:133], v[136:137], off offset:-4096
	global_load_dwordx4 v[168:171], v[136:137], off
	s_mov_b64 s[8:9], 0x60000
	s_waitcnt vmcnt(1)
;     __device__ __forceinline__ void mid(f32x4 (&acc)[2][2][4][2], const Unit& u, int wr, int wc, int fr, int fq) const {
;     ...
;             for (int bj = 0; bj < 2; ++bj) {
;                 const bf16_t* g = sg + (size_t)row * 4096 + cb + bj * 128; f32x4 a0, a1, b0, b1;
;                 unpack8(*(const u32x4*)g, a0, a1); unpack8(*(const u32x4*)(g + 2048), b0, b1);
; #pragma unroll
;                 for (int q = 0; q < 4; ++q) { acc[ai][bj][m][0][q] *= a0[q] * __builtin_amdgcn_rcpf(fmaxf(b0[q], 1e-30f)); acc[ai][bj][m][1][q] *= a1[q] * __builtin_amdgcn_rcpf(fmaxf(b1[q], 1e-30f)); }
	v_lshlrev_b32_e32 v172, 16, v130
	s_waitcnt vmcnt(0)
	v_lshlrev_b32_e32 v149, 16, v168
	v_max_f32_e32 v149, v149, v149
	v_lshlrev_b32_e32 v174, 16, v169
	v_and_b32_e32 v175, 0xffff0000, v169
	v_lshlrev_b32_e32 v169, 16, v170
	v_max_f32_e32 v149, 0xda24260, v149
	v_and_b32_e32 v151, 0xffff0000, v168
	v_rcp_f32_e32 v168, v149
	v_max_f32_e32 v149, v169, v169
	v_max_f32_e32 v149, 0xda24260, v149
	v_and_b32_e32 v176, 0xffff0000, v170
	v_rcp_f32_e32 v170, v149
	v_max_f32_e32 v149, v151, v151
	v_max_f32_e32 v149, 0xda24260, v149
	v_rcp_f32_e32 v169, v149
	v_and_b32_e32 v173, 0xffff0000, v130
	v_max_f32_e32 v130, v176, v176
	v_max_f32_e32 v130, 0xda24260, v130
	v_lshlrev_b32_e32 v177, 16, v171
	v_and_b32_e32 v178, 0xffff0000, v171
	v_rcp_f32_e32 v171, v130
	v_pk_mul_f32 v[168:169], v[168:169], v[172:173]
	v_max_f32_e32 v130, v174, v174
	v_pk_mul_f32 v[94:95], v[94:95], v[168:169]
	v_lshlrev_b32_e32 v168, 16, v132
	v_and_b32_e32 v169, 0xffff0000, v132
	v_pk_mul_f32 v[168:169], v[170:171], v[168:169]
	v_max_f32_e32 v130, 0xda24260, v130
	v_pk_mul_f32 v[90:91], v[90:91], v[168:169]
	v_rcp_f32_e32 v168, v130
	v_max_f32_e32 v130, v177, v177
	v_max_f32_e32 v132, v175, v175
	v_lshlrev_b32_e32 v170, 16, v131
	v_and_b32_e32 v171, 0xffff0000, v131
	v_max_f32_e32 v131, v178, v178
	v_max_f32_e32 v130, 0xda24260, v130
	v_max_f32_e32 v132, 0xda24260, v132
	v_max_f32_e32 v131, 0xda24260, v131
	v_rcp_f32_e32 v130, v130
	v_rcp_f32_e32 v169, v132
	v_rcp_f32_e32 v131, v131
	v_lshlrev_b32_e32 v132, 16, v133
	v_and_b32_e32 v133, 0xffff0000, v133
	v_pk_mul_f32 v[168:169], v[168:169], v[170:171]
	v_pk_mul_f32 v[130:131], v[130:131], v[132:133]
	v_pk_mul_f32 v[96:97], v[96:97], v[168:169]
	v_pk_mul_f32 v[92:93], v[92:93], v[130:131]
	global_load_dwordx4 v[130:133], v[166:167], off offset:256
	global_load_dwordx4 v[168:171], v[136:137], off offset:256
	s_waitcnt vmcnt(0)
	v_lshlrev_b32_e32 v136, 16, v168
	v_and_b32_e32 v137, 0xffff0000, v168
	v_max_f32_e32 v136, v136, v136
	v_max_f32_e32 v137, v137, v137
	v_lshlrev_b32_e32 v166, 16, v170
	v_and_b32_e32 v167, 0xffff0000, v170
	v_max_f32_e32 v136, 0xda24260, v136
	v_max_f32_e32 v137, 0xda24260, v137
	v_lshlrev_b32_e32 v149, 16, v169
	v_and_b32_e32 v151, 0xffff0000, v169
	v_rcp_f32_e32 v136, v136
	v_max_f32_e32 v166, v166, v166
	v_rcp_f32_e32 v137, v137
	v_lshlrev_b32_e32 v168, 16, v130
	v_and_b32_e32 v169, 0xffff0000, v130
	v_max_f32_e32 v130, v167, v167
	v_max_f32_e32 v166, 0xda24260, v166
	v_max_f32_e32 v130, 0xda24260, v130
	v_rcp_f32_e32 v166, v166
	v_rcp_f32_e32 v167, v130
	v_pk_mul_f32 v[136:137], v[136:137], v[168:169]
	v_max_f32_e32 v130, v149, v149
	v_pk_mul_f32 v[86:87], v[86:87], v[136:137]
	v_lshlrev_b32_e32 v136, 16, v132
	v_and_b32_e32 v137, 0xffff0000, v132
	v_lshlrev_b32_e32 v170, 16, v171
	v_and_b32_e32 v171, 0xffff0000, v171
	v_pk_mul_f32 v[136:137], v[166:167], v[136:137]
	v_max_f32_e32 v130, 0xda24260, v130
	v_pk_mul_f32 v[82:83], v[82:83], v[136:137]
	v_rcp_f32_e32 v136, v130
	v_max_f32_e32 v130, v170, v170
	v_lshlrev_b32_e32 v166, 16, v131
	v_and_b32_e32 v167, 0xffff0000, v131
	v_max_f32_e32 v131, v171, v171
	v_max_f32_e32 v130, 0xda24260, v130
	v_max_f32_e32 v132, v151, v151
	v_max_f32_e32 v131, 0xda24260, v131
	v_rcp_f32_e32 v130, v130
	v_max_f32_e32 v132, 0xda24260, v132
	v_rcp_f32_e32 v131, v131
	v_rcp_f32_e32 v137, v132
	v_lshlrev_b32_e32 v132, 16, v133
	v_and_b32_e32 v133, 0xffff0000, v133
	v_pk_mul_f32 v[130:131], v[130:131], v[132:133]
	v_pk_mul_f32 v[136:137], v[136:137], v[166:167]
	v_pk_mul_f32 v[84:85], v[84:85], v[130:131]
	v_lshl_add_u64 v[130:131], v[134:135], 0, s[8:9]
	s_mov_b32 s8, 0x61000
	v_pk_mul_f32 v[88:89], v[88:89], v[136:137]
	v_add_co_u32_e32 v136, vcc, s8, v134
	s_mov_b64 s[8:9], 0x100000
	s_nop 0
	v_addc_co_u32_e32 v137, vcc, 0, v135, vcc
	global_load_dwordx4 v[168:171], v[136:137], off offset:-4096
	global_load_dwordx4 v[172:175], v[136:137], off
	s_waitcnt vmcnt(0)
	v_lshlrev_b32_e32 v132, 16, v172
	v_and_b32_e32 v133, 0xffff0000, v172
	v_max_f32_e32 v132, v132, v132
	v_max_f32_e32 v133, v133, v133
	v_max_f32_e32 v132, 0xda24260, v132
	v_max_f32_e32 v133, 0xda24260, v133
	v_rcp_f32_e32 v132, v132
	v_rcp_f32_e32 v133, v133
	v_lshlrev_b32_e32 v149, 16, v173
	v_and_b32_e32 v151, 0xffff0000, v173
	v_lshlrev_b32_e32 v172, 16, v168
	v_and_b32_e32 v173, 0xffff0000, v168
	v_lshlrev_b32_e32 v166, 16, v174
	v_and_b32_e32 v167, 0xffff0000, v174
	v_pk_mul_f32 v[132:133], v[132:133], v[172:173]
	v_max_f32_e32 v166, v166, v166
	v_pk_mul_f32 v[78:79], v[78:79], v[132:133]
	v_max_f32_e32 v132, v167, v167
	v_max_f32_e32 v166, 0xda24260, v166
	v_max_f32_e32 v132, 0xda24260, v132
	v_rcp_f32_e32 v166, v166
	v_rcp_f32_e32 v167, v132
	v_lshlrev_b32_e32 v132, 16, v170
	v_and_b32_e32 v133, 0xffff0000, v170
	v_lshlrev_b32_e32 v174, 16, v175
	v_pk_mul_f32 v[132:133], v[166:167], v[132:133]
	v_lshlrev_b32_e32 v168, 16, v169
	v_pk_mul_f32 v[74:75], v[74:75], v[132:133]
	v_max_f32_e32 v133, v174, v174
	v_max_f32_e32 v133, 0xda24260, v133
	v_max_f32_e32 v132, v149, v149
	v_rcp_f32_e32 v166, v133
	v_max_f32_e32 v133, v151, v151
	v_max_f32_e32 v132, 0xda24260, v132
	v_max_f32_e32 v133, 0xda24260, v133
	v_rcp_f32_e32 v132, v132
	v_rcp_f32_e32 v133, v133
	v_and_b32_e32 v169, 0xffff0000, v169
	v_and_b32_e32 v175, 0xffff0000, v175
	v_pk_mul_f32 v[132:133], v[132:133], v[168:169]
	s_nop 0
	v_pk_mul_f32 v[80:81], v[80:81], v[132:133]
	v_max_f32_e32 v132, v175, v175
	v_max_f32_e32 v132, 0xda24260, v132
	v_rcp_f32_e32 v167, v132
	v_lshlrev_b32_e32 v132, 16, v171
	v_and_b32_e32 v133, 0xffff0000, v171
	v_pk_mul_f32 v[132:133], v[166:167], v[132:133]
	s_nop 0
	v_pk_mul_f32 v[76:77], v[76:77], v[132:133]
	global_load_dwordx4 v[130:133], v[130:131], off offset:256
	s_nop 0
	global_load_dwordx4 v[168:171], v[136:137], off offset:256
	s_waitcnt vmcnt(0)
; #define EP_ROWLOOP for (int ai = 0; ai < 2; ++ai) _Pragma("unroll") for (int m = 0; m < 4; ++m)
;     __device__ __forceinline__ void mid(f32x4 (&acc)[2][2][4][2], const Unit& u, int wr, int wc, int fr, int fq) const {
;         int rowb = u.pm * 256 + wr * 64 + fr, cb = u.pn * 256 + wc * 32 + 8 * fq;
;         asm volatile("" : "+v"(rowb), "+v"(cb));
; #pragma unroll
;         EP_ROWLOOP { EpFence fence_{(m & 1) == 1};
;             const int row = rowb + ai * 128 + m * 16;
; #pragma unroll
;             for (int bj = 0; bj < 2; ++bj) {
;                 const bf16_t* g = sg + (size_t)row * 4096 + cb + bj * 128; f32x4 a0, a1, b0, b1;
;                 unpack8(*(const u32x4*)g, a0, a1); unpack8(*(const u32x4*)(g + 2048), b0, b1);
; #pragma unroll
;                 for (int q = 0; q < 4; ++q) { acc[ai][bj][m][0][q] *= a0[q] * __builtin_amdgcn_rcpf(fmaxf(b0[q], 1e-30f)); acc[ai][bj][m][1][q] *= a1[q] * __builtin_amdgcn_rcpf(fmaxf(b1[q], 1e-30f)); }
;             }
	v_lshlrev_b32_e32 v136, 16, v168
	v_and_b32_e32 v137, 0xffff0000, v168
	v_max_f32_e32 v136, v136, v136
	v_max_f32_e32 v137, v137, v137
	v_lshlrev_b32_e32 v166, 16, v170
	v_and_b32_e32 v167, 0xffff0000, v170
	v_max_f32_e32 v136, 0xda24260, v136
	v_max_f32_e32 v137, 0xda24260, v137
	v_lshlrev_b32_e32 v149, 16, v169
	v_and_b32_e32 v151, 0xffff0000, v169
	v_rcp_f32_e32 v136, v136
	v_max_f32_e32 v166, v166, v166
	v_rcp_f32_e32 v137, v137
	v_lshlrev_b32_e32 v168, 16, v130
	v_and_b32_e32 v169, 0xffff0000, v130
	v_max_f32_e32 v130, v167, v167
	v_max_f32_e32 v166, 0xda24260, v166
	v_max_f32_e32 v130, 0xda24260, v130
	v_rcp_f32_e32 v166, v166
	v_rcp_f32_e32 v167, v130
	v_pk_mul_f32 v[136:137], v[136:137], v[168:169]
	v_max_f32_e32 v130, v149, v149
	v_pk_mul_f32 v[70:71], v[70:71], v[136:137]
	v_lshlrev_b32_e32 v136, 16, v132
	v_and_b32_e32 v137, 0xffff0000, v132
	v_max_f32_e32 v132, v151, v151
	v_lshlrev_b32_e32 v170, 16, v171
	v_and_b32_e32 v171, 0xffff0000, v171
	v_pk_mul_f32 v[136:137], v[166:167], v[136:137]
	v_max_f32_e32 v130, 0xda24260, v130
	v_max_f32_e32 v132, 0xda24260, v132
	v_pk_mul_f32 v[66:67], v[66:67], v[136:137]
	v_rcp_f32_e32 v136, v130
	v_max_f32_e32 v130, v170, v170
	v_rcp_f32_e32 v137, v132
	v_lshlrev_b32_e32 v166, 16, v131
	v_and_b32_e32 v167, 0xffff0000, v131
	v_max_f32_e32 v131, v171, v171
	v_max_f32_e32 v130, 0xda24260, v130
	v_max_f32_e32 v131, 0xda24260, v131
	v_rcp_f32_e32 v130, v130
	v_rcp_f32_e32 v131, v131
	v_pk_mul_f32 v[136:137], v[136:137], v[166:167]
	v_lshl_add_u64 v[166:167], v[134:135], 0, s[8:9]
	s_mov_b32 s8, 0x101000
	v_pk_mul_f32 v[72:73], v[72:73], v[136:137]
	v_lshlrev_b32_e32 v132, 16, v133
	v_and_b32_e32 v133, 0xffff0000, v133
	v_add_co_u32_e32 v136, vcc, s8, v134
	v_pk_mul_f32 v[130:131], v[130:131], v[132:133]
	s_nop 0
	v_addc_co_u32_e32 v137, vcc, 0, v135, vcc
	v_pk_mul_f32 v[68:69], v[68:69], v[130:131]
	global_load_dwordx4 v[130:133], v[136:137], off offset:-4096
	global_load_dwordx4 v[168:171], v[136:137], off
	s_mov_b64 s[8:9], 0x120000
	s_waitcnt vmcnt(1)
	v_lshlrev_b32_e32 v172, 16, v130
	s_waitcnt vmcnt(0)
	v_lshlrev_b32_e32 v149, 16, v168
	v_max_f32_e32 v149, v149, v149
	v_lshlrev_b32_e32 v174, 16, v169
	v_and_b32_e32 v175, 0xffff0000, v169
	v_lshlrev_b32_e32 v169, 16, v170
	v_max_f32_e32 v149, 0xda24260, v149
	v_and_b32_e32 v151, 0xffff0000, v168
	v_rcp_f32_e32 v168, v149
	v_max_f32_e32 v149, v169, v169
	v_max_f32_e32 v149, 0xda24260, v149
	v_and_b32_e32 v176, 0xffff0000, v170
	v_rcp_f32_e32 v170, v149
	v_max_f32_e32 v149, v151, v151
	v_max_f32_e32 v149, 0xda24260, v149
	v_rcp_f32_e32 v169, v149
	v_and_b32_e32 v173, 0xffff0000, v130
	v_max_f32_e32 v130, v176, v176
	v_max_f32_e32 v130, 0xda24260, v130
	v_lshlrev_b32_e32 v177, 16, v171
	v_and_b32_e32 v178, 0xffff0000, v171
	v_rcp_f32_e32 v171, v130
	v_pk_mul_f32 v[168:169], v[168:169], v[172:173]
	v_max_f32_e32 v130, v174, v174
	v_pk_mul_f32 v[62:63], v[62:63], v[168:169]
	v_lshlrev_b32_e32 v168, 16, v132
	v_and_b32_e32 v169, 0xffff0000, v132
	v_pk_mul_f32 v[168:169], v[170:171], v[168:169]
	v_max_f32_e32 v130, 0xda24260, v130
	v_pk_mul_f32 v[58:59], v[58:59], v[168:169]
	v_rcp_f32_e32 v168, v130
	v_max_f32_e32 v130, v177, v177
	v_max_f32_e32 v132, v175, v175
	v_lshlrev_b32_e32 v170, 16, v131
	v_and_b32_e32 v171, 0xffff0000, v131
	v_max_f32_e32 v131, v178, v178
	v_max_f32_e32 v130, 0xda24260, v130
	v_max_f32_e32 v132, 0xda24260, v132
	v_max_f32_e32 v131, 0xda24260, v131
	v_rcp_f32_e32 v130, v130
	v_rcp_f32_e32 v169, v132
	v_rcp_f32_e32 v131, v131
	v_lshlrev_b32_e32 v132, 16, v133
	v_and_b32_e32 v133, 0xffff0000, v133
	v_pk_mul_f32 v[168:169], v[168:169], v[170:171]
	v_pk_mul_f32 v[130:131], v[130:131], v[132:133]
	v_pk_mul_f32 v[64:65], v[64:65], v[168:169]
	v_pk_mul_f32 v[60:61], v[60:61], v[130:131]
	global_load_dwordx4 v[130:133], v[166:167], off offset:256
	global_load_dwordx4 v[168:171], v[136:137], off offset:256
	s_waitcnt vmcnt(0)
	v_lshlrev_b32_e32 v136, 16, v168
	v_and_b32_e32 v137, 0xffff0000, v168
	v_max_f32_e32 v136, v136, v136
	v_max_f32_e32 v137, v137, v137
	v_lshlrev_b32_e32 v166, 16, v170
	v_and_b32_e32 v167, 0xffff0000, v170
	v_max_f32_e32 v136, 0xda24260, v136
	v_max_f32_e32 v137, 0xda24260, v137
	v_lshlrev_b32_e32 v149, 16, v169
	v_and_b32_e32 v151, 0xffff0000, v169
	v_rcp_f32_e32 v136, v136
	v_max_f32_e32 v166, v166, v166
	v_rcp_f32_e32 v137, v137
	v_lshlrev_b32_e32 v168, 16, v130
	v_and_b32_e32 v169, 0xffff0000, v130
	v_max_f32_e32 v130, v167, v167
	v_max_f32_e32 v166, 0xda24260, v166
	v_max_f32_e32 v130, 0xda24260, v130
	v_rcp_f32_e32 v166, v166
	v_rcp_f32_e32 v167, v130
	v_pk_mul_f32 v[136:137], v[136:137], v[168:169]
	v_max_f32_e32 v130, v149, v149
	v_pk_mul_f32 v[54:55], v[54:55], v[136:137]
	v_lshlrev_b32_e32 v136, 16, v132
	v_and_b32_e32 v137, 0xffff0000, v132
	v_lshlrev_b32_e32 v170, 16, v171
	v_and_b32_e32 v171, 0xffff0000, v171
	v_pk_mul_f32 v[136:137], v[166:167], v[136:137]
	v_max_f32_e32 v130, 0xda24260, v130
	v_pk_mul_f32 v[50:51], v[50:51], v[136:137]
	v_rcp_f32_e32 v136, v130
	v_max_f32_e32 v130, v170, v170
	v_lshlrev_b32_e32 v166, 16, v131
	v_and_b32_e32 v167, 0xffff0000, v131
	v_max_f32_e32 v131, v171, v171
	v_max_f32_e32 v130, 0xda24260, v130
	v_max_f32_e32 v132, v151, v151
	v_max_f32_e32 v131, 0xda24260, v131
	v_rcp_f32_e32 v130, v130
	v_max_f32_e32 v132, 0xda24260, v132
	v_rcp_f32_e32 v131, v131
	v_rcp_f32_e32 v137, v132
	v_lshlrev_b32_e32 v132, 16, v133
	v_and_b32_e32 v133, 0xffff0000, v133
	v_pk_mul_f32 v[130:131], v[130:131], v[132:133]
	v_pk_mul_f32 v[136:137], v[136:137], v[166:167]
	v_pk_mul_f32 v[52:53], v[52:53], v[130:131]
	v_lshl_add_u64 v[130:131], v[134:135], 0, s[8:9]
	s_mov_b32 s8, 0x121000
	v_pk_mul_f32 v[56:57], v[56:57], v[136:137]
	v_add_co_u32_e32 v136, vcc, s8, v134
	s_mov_b64 s[8:9], 0x140000
	s_nop 0
	v_addc_co_u32_e32 v137, vcc, 0, v135, vcc
	global_load_dwordx4 v[168:171], v[136:137], off offset:-4096
	global_load_dwordx4 v[172:175], v[136:137], off
	s_waitcnt vmcnt(0)
; #define EP_ROWLOOP for (int ai = 0; ai < 2; ++ai) _Pragma("unroll") for (int m = 0; m < 4; ++m)
;     __device__ __forceinline__ void mid(f32x4 (&acc)[2][2][4][2], const Unit& u, int wr, int wc, int fr, int fq) const {
;         int rowb = u.pm * 256 + wr * 64 + fr, cb = u.pn * 256 + wc * 32 + 8 * fq;
;         asm volatile("" : "+v"(rowb), "+v"(cb));
; #pragma unroll
;         EP_ROWLOOP { EpFence fence_{(m & 1) == 1};
;             const int row = rowb + ai * 128 + m * 16;
; #pragma unroll
;             for (int bj = 0; bj < 2; ++bj) {
;                 const bf16_t* g = sg + (size_t)row * 4096 + cb + bj * 128; f32x4 a0, a1, b0, b1;
;                 unpack8(*(const u32x4*)g, a0, a1); unpack8(*(const u32x4*)(g + 2048), b0, b1);
; #pragma unroll
;                 for (int q = 0; q < 4; ++q) { acc[ai][bj][m][0][q] *= a0[q] * __builtin_amdgcn_rcpf(fmaxf(b0[q], 1e-30f)); acc[ai][bj][m][1][q] *= a1[q] * __builtin_amdgcn_rcpf(fmaxf(b1[q], 1e-30f)); }
;             }
	v_lshlrev_b32_e32 v132, 16, v172
	v_and_b32_e32 v133, 0xffff0000, v172
	v_max_f32_e32 v132, v132, v132
	v_max_f32_e32 v133, v133, v133
	v_max_f32_e32 v132, 0xda24260, v132
	v_max_f32_e32 v133, 0xda24260, v133
	v_rcp_f32_e32 v132, v132
	v_rcp_f32_e32 v133, v133
	v_lshlrev_b32_e32 v149, 16, v173
	v_and_b32_e32 v151, 0xffff0000, v173
	v_lshlrev_b32_e32 v172, 16, v168
	v_and_b32_e32 v173, 0xffff0000, v168
	v_lshlrev_b32_e32 v166, 16, v174
	v_and_b32_e32 v167, 0xffff0000, v174
	v_pk_mul_f32 v[132:133], v[132:133], v[172:173]
	v_max_f32_e32 v166, v166, v166
	v_pk_mul_f32 v[46:47], v[46:47], v[132:133]
	v_max_f32_e32 v132, v167, v167
	v_max_f32_e32 v166, 0xda24260, v166
	v_max_f32_e32 v132, 0xda24260, v132
	v_rcp_f32_e32 v166, v166
	v_rcp_f32_e32 v167, v132
	v_lshlrev_b32_e32 v132, 16, v170
	v_and_b32_e32 v133, 0xffff0000, v170
	v_lshlrev_b32_e32 v174, 16, v175
	v_pk_mul_f32 v[132:133], v[166:167], v[132:133]
	v_lshlrev_b32_e32 v168, 16, v169
	v_pk_mul_f32 v[42:43], v[42:43], v[132:133]
	v_max_f32_e32 v133, v174, v174
	v_max_f32_e32 v133, 0xda24260, v133
	v_max_f32_e32 v132, v149, v149
	v_rcp_f32_e32 v166, v133
	v_max_f32_e32 v133, v151, v151
	v_max_f32_e32 v132, 0xda24260, v132
	v_max_f32_e32 v133, 0xda24260, v133
	v_rcp_f32_e32 v132, v132
	v_rcp_f32_e32 v133, v133
	v_and_b32_e32 v169, 0xffff0000, v169
	v_and_b32_e32 v175, 0xffff0000, v175
	v_pk_mul_f32 v[132:133], v[132:133], v[168:169]
	s_nop 0
	v_pk_mul_f32 v[48:49], v[48:49], v[132:133]
	v_max_f32_e32 v132, v175, v175
	v_max_f32_e32 v132, 0xda24260, v132
	v_rcp_f32_e32 v167, v132
	v_lshlrev_b32_e32 v132, 16, v171
	v_and_b32_e32 v133, 0xffff0000, v171
	v_pk_mul_f32 v[132:133], v[166:167], v[132:133]
	s_nop 0
	v_pk_mul_f32 v[44:45], v[44:45], v[132:133]
	global_load_dwordx4 v[130:133], v[130:131], off offset:256
	s_nop 0
	global_load_dwordx4 v[168:171], v[136:137], off offset:256
	s_waitcnt vmcnt(0)
	v_lshlrev_b32_e32 v136, 16, v168
	v_and_b32_e32 v137, 0xffff0000, v168
	v_max_f32_e32 v136, v136, v136
	v_max_f32_e32 v137, v137, v137
	v_lshlrev_b32_e32 v166, 16, v170
	v_and_b32_e32 v167, 0xffff0000, v170
	v_max_f32_e32 v136, 0xda24260, v136
	v_max_f32_e32 v137, 0xda24260, v137
	v_lshlrev_b32_e32 v149, 16, v169
	v_and_b32_e32 v151, 0xffff0000, v169
	v_rcp_f32_e32 v136, v136
	v_max_f32_e32 v166, v166, v166
	v_rcp_f32_e32 v137, v137
	v_lshlrev_b32_e32 v168, 16, v130
	v_and_b32_e32 v169, 0xffff0000, v130
	v_max_f32_e32 v130, v167, v167
	v_max_f32_e32 v166, 0xda24260, v166
	v_max_f32_e32 v130, 0xda24260, v130
	v_rcp_f32_e32 v166, v166
	v_rcp_f32_e32 v167, v130
	v_pk_mul_f32 v[136:137], v[136:137], v[168:169]
	v_max_f32_e32 v130, v149, v149
	v_pk_mul_f32 v[38:39], v[38:39], v[136:137]
	v_lshlrev_b32_e32 v136, 16, v132
	v_and_b32_e32 v137, 0xffff0000, v132
	v_max_f32_e32 v132, v151, v151
	v_lshlrev_b32_e32 v170, 16, v171
	v_and_b32_e32 v171, 0xffff0000, v171
	v_pk_mul_f32 v[136:137], v[166:167], v[136:137]
	v_max_f32_e32 v130, 0xda24260, v130
	v_max_f32_e32 v132, 0xda24260, v132
	v_pk_mul_f32 v[34:35], v[34:35], v[136:137]
	v_rcp_f32_e32 v136, v130
	v_max_f32_e32 v130, v170, v170
	v_rcp_f32_e32 v137, v132
	v_lshlrev_b32_e32 v166, 16, v131
	v_and_b32_e32 v167, 0xffff0000, v131
	v_max_f32_e32 v131, v171, v171
	v_max_f32_e32 v130, 0xda24260, v130
	v_max_f32_e32 v131, 0xda24260, v131
	v_rcp_f32_e32 v130, v130
	v_rcp_f32_e32 v131, v131
	v_pk_mul_f32 v[136:137], v[136:137], v[166:167]
	v_lshl_add_u64 v[166:167], v[134:135], 0, s[8:9]
	s_mov_b32 s8, 0x141000
	v_pk_mul_f32 v[40:41], v[40:41], v[136:137]
	v_lshlrev_b32_e32 v132, 16, v133
	v_and_b32_e32 v133, 0xffff0000, v133
	v_add_co_u32_e32 v136, vcc, s8, v134
	v_pk_mul_f32 v[130:131], v[130:131], v[132:133]
	s_nop 0
	v_addc_co_u32_e32 v137, vcc, 0, v135, vcc
	v_pk_mul_f32 v[36:37], v[36:37], v[130:131]
	global_load_dwordx4 v[130:133], v[136:137], off offset:-4096
	global_load_dwordx4 v[168:171], v[136:137], off
	s_mov_b64 s[8:9], 0x160000
	s_waitcnt vmcnt(1)
	v_lshlrev_b32_e32 v172, 16, v130
	s_waitcnt vmcnt(0)
	v_lshlrev_b32_e32 v149, 16, v168
	v_max_f32_e32 v149, v149, v149
	v_lshlrev_b32_e32 v174, 16, v169
	v_and_b32_e32 v175, 0xffff0000, v169
	v_lshlrev_b32_e32 v169, 16, v170
	v_max_f32_e32 v149, 0xda24260, v149
	v_and_b32_e32 v151, 0xffff0000, v168
	v_rcp_f32_e32 v168, v149
	v_max_f32_e32 v149, v169, v169
	v_max_f32_e32 v149, 0xda24260, v149
	v_and_b32_e32 v176, 0xffff0000, v170
	v_rcp_f32_e32 v170, v149
	v_max_f32_e32 v149, v151, v151
	v_max_f32_e32 v149, 0xda24260, v149
	v_rcp_f32_e32 v169, v149
	v_and_b32_e32 v173, 0xffff0000, v130
	v_max_f32_e32 v130, v176, v176
	v_max_f32_e32 v130, 0xda24260, v130
	v_lshlrev_b32_e32 v177, 16, v171
	v_and_b32_e32 v178, 0xffff0000, v171
	v_rcp_f32_e32 v171, v130
	v_pk_mul_f32 v[168:169], v[168:169], v[172:173]
	v_max_f32_e32 v130, v174, v174
	v_pk_mul_f32 v[30:31], v[30:31], v[168:169]
	v_lshlrev_b32_e32 v168, 16, v132
	v_and_b32_e32 v169, 0xffff0000, v132
	v_pk_mul_f32 v[168:169], v[170:171], v[168:169]
	v_max_f32_e32 v130, 0xda24260, v130
	v_pk_mul_f32 v[26:27], v[26:27], v[168:169]
	v_rcp_f32_e32 v168, v130
	v_max_f32_e32 v130, v177, v177
	v_max_f32_e32 v132, v175, v175
	v_lshlrev_b32_e32 v170, 16, v131
	v_and_b32_e32 v171, 0xffff0000, v131
	v_max_f32_e32 v131, v178, v178
	v_max_f32_e32 v130, 0xda24260, v130
	v_max_f32_e32 v132, 0xda24260, v132
	v_max_f32_e32 v131, 0xda24260, v131
	v_rcp_f32_e32 v130, v130
	v_rcp_f32_e32 v169, v132
	v_rcp_f32_e32 v131, v131
	v_lshlrev_b32_e32 v132, 16, v133
	v_and_b32_e32 v133, 0xffff0000, v133
	v_pk_mul_f32 v[168:169], v[168:169], v[170:171]
	v_pk_mul_f32 v[130:131], v[130:131], v[132:133]
	v_pk_mul_f32 v[32:33], v[32:33], v[168:169]
	v_pk_mul_f32 v[28:29], v[28:29], v[130:131]
	global_load_dwordx4 v[130:133], v[166:167], off offset:256
	global_load_dwordx4 v[168:171], v[136:137], off offset:256
	s_waitcnt vmcnt(0)
; #define EP_ROWLOOP for (int ai = 0; ai < 2; ++ai) _Pragma("unroll") for (int m = 0; m < 4; ++m)
;     __device__ __forceinline__ void mid(f32x4 (&acc)[2][2][4][2], const Unit& u, int wr, int wc, int fr, int fq) const {
;         int rowb = u.pm * 256 + wr * 64 + fr, cb = u.pn * 256 + wc * 32 + 8 * fq;
;         asm volatile("" : "+v"(rowb), "+v"(cb));
; #pragma unroll
;         EP_ROWLOOP { EpFence fence_{(m & 1) == 1};
;             const int row = rowb + ai * 128 + m * 16;
; #pragma unroll
;             for (int bj = 0; bj < 2; ++bj) {
;                 const bf16_t* g = sg + (size_t)row * 4096 + cb + bj * 128; f32x4 a0, a1, b0, b1;
;                 unpack8(*(const u32x4*)g, a0, a1); unpack8(*(const u32x4*)(g + 2048), b0, b1);
; #pragma unroll
;                 for (int q = 0; q < 4; ++q) { acc[ai][bj][m][0][q] *= a0[q] * __builtin_amdgcn_rcpf(fmaxf(b0[q], 1e-30f)); acc[ai][bj][m][1][q] *= a1[q] * __builtin_amdgcn_rcpf(fmaxf(b1[q], 1e-30f)); }
;             }
	v_lshlrev_b32_e32 v136, 16, v168
	v_and_b32_e32 v137, 0xffff0000, v168
	v_max_f32_e32 v136, v136, v136
	v_max_f32_e32 v137, v137, v137
	v_lshlrev_b32_e32 v166, 16, v170
	v_and_b32_e32 v167, 0xffff0000, v170
	v_max_f32_e32 v136, 0xda24260, v136
	v_max_f32_e32 v137, 0xda24260, v137
	v_lshlrev_b32_e32 v149, 16, v169
	v_and_b32_e32 v151, 0xffff0000, v169
	v_rcp_f32_e32 v136, v136
	v_max_f32_e32 v166, v166, v166
	v_rcp_f32_e32 v137, v137
	v_lshlrev_b32_e32 v168, 16, v130
	v_and_b32_e32 v169, 0xffff0000, v130
	v_max_f32_e32 v130, v167, v167
	v_max_f32_e32 v166, 0xda24260, v166
	v_max_f32_e32 v130, 0xda24260, v130
	v_rcp_f32_e32 v166, v166
	v_rcp_f32_e32 v167, v130
	v_pk_mul_f32 v[136:137], v[136:137], v[168:169]
	v_max_f32_e32 v130, v149, v149
	v_pk_mul_f32 v[22:23], v[22:23], v[136:137]
	v_lshlrev_b32_e32 v136, 16, v132
	v_and_b32_e32 v137, 0xffff0000, v132
	v_lshlrev_b32_e32 v170, 16, v171
	v_and_b32_e32 v171, 0xffff0000, v171
	v_pk_mul_f32 v[136:137], v[166:167], v[136:137]
	v_max_f32_e32 v130, 0xda24260, v130
	v_pk_mul_f32 v[18:19], v[18:19], v[136:137]
	v_rcp_f32_e32 v136, v130
	v_max_f32_e32 v130, v170, v170
	v_lshlrev_b32_e32 v166, 16, v131
	v_and_b32_e32 v167, 0xffff0000, v131
	v_max_f32_e32 v131, v171, v171
	v_max_f32_e32 v130, 0xda24260, v130
	v_max_f32_e32 v131, 0xda24260, v131
	v_rcp_f32_e32 v130, v130
	v_rcp_f32_e32 v131, v131
	v_max_f32_e32 v132, v151, v151
	v_max_f32_e32 v132, 0xda24260, v132
	v_rcp_f32_e32 v137, v132
	v_lshlrev_b32_e32 v132, 16, v133
	v_and_b32_e32 v133, 0xffff0000, v133
	v_pk_mul_f32 v[130:131], v[130:131], v[132:133]
	v_pk_mul_f32 v[136:137], v[136:137], v[166:167]
	v_pk_mul_f32 v[20:21], v[20:21], v[130:131]
	v_lshl_add_u64 v[130:131], v[134:135], 0, s[8:9]
	s_mov_b32 s8, 0x161000
	v_add_co_u32_e32 v134, vcc, s8, v134
	v_pk_mul_f32 v[24:25], v[24:25], v[136:137]
	s_nop 0
	v_addc_co_u32_e32 v135, vcc, 0, v135, vcc
	global_load_dwordx4 v[168:171], v[134:135], off offset:-4096
	global_load_dwordx4 v[172:175], v[134:135], off
	s_waitcnt vmcnt(1)
	v_lshlrev_b32_e32 v166, 16, v168
	s_waitcnt vmcnt(0)
	v_lshlrev_b32_e32 v132, 16, v172
	v_and_b32_e32 v133, 0xffff0000, v172
	v_max_f32_e32 v132, v132, v132
	v_max_f32_e32 v133, v133, v133
	v_max_f32_e32 v132, 0xda24260, v132
	v_max_f32_e32 v133, 0xda24260, v133
	v_rcp_f32_e32 v132, v132
	v_rcp_f32_e32 v133, v133
	v_and_b32_e32 v167, 0xffff0000, v168
	v_lshlrev_b32_e32 v136, 16, v174
	v_and_b32_e32 v137, 0xffff0000, v174
	v_pk_mul_f32 v[132:133], v[132:133], v[166:167]
	v_max_f32_e32 v136, v136, v136
	v_pk_mul_f32 v[14:15], v[14:15], v[132:133]
	v_max_f32_e32 v132, v137, v137
	v_max_f32_e32 v136, 0xda24260, v136
	v_max_f32_e32 v132, 0xda24260, v132
	v_rcp_f32_e32 v136, v136
	v_rcp_f32_e32 v137, v132
	v_lshlrev_b32_e32 v132, 16, v170
	v_and_b32_e32 v133, 0xffff0000, v170
	v_lshlrev_b32_e32 v172, 16, v175
	v_pk_mul_f32 v[132:133], v[136:137], v[132:133]
	v_lshlrev_b32_e32 v149, 16, v173
	v_pk_mul_f32 v[10:11], v[10:11], v[132:133]
	v_max_f32_e32 v133, v172, v172
	v_and_b32_e32 v151, 0xffff0000, v173
	v_max_f32_e32 v133, 0xda24260, v133
	v_max_f32_e32 v132, v149, v149
	v_rcp_f32_e32 v136, v133
	v_max_f32_e32 v133, v151, v151
	v_max_f32_e32 v132, 0xda24260, v132
	v_max_f32_e32 v133, 0xda24260, v133
	v_rcp_f32_e32 v132, v132
	v_rcp_f32_e32 v133, v133
	v_lshlrev_b32_e32 v166, 16, v169
	v_and_b32_e32 v167, 0xffff0000, v169
	v_and_b32_e32 v173, 0xffff0000, v175
	v_pk_mul_f32 v[132:133], v[132:133], v[166:167]
	s_nop 0
	v_pk_mul_f32 v[16:17], v[16:17], v[132:133]
	v_max_f32_e32 v132, v173, v173
	v_max_f32_e32 v132, 0xda24260, v132
	v_rcp_f32_e32 v137, v132
	v_lshlrev_b32_e32 v132, 16, v171
	v_and_b32_e32 v133, 0xffff0000, v171
	v_pk_mul_f32 v[132:133], v[136:137], v[132:133]
	s_nop 0
	v_pk_mul_f32 v[12:13], v[12:13], v[132:133]
	global_load_dwordx4 v[130:133], v[130:131], off offset:256
	s_nop 0
	global_load_dwordx4 v[134:137], v[134:135], off offset:256
	s_waitcnt vmcnt(1)
	v_lshlrev_b32_e32 v166, 16, v130
	s_waitcnt vmcnt(0)
	v_lshlrev_b32_e32 v168, 16, v135
	v_and_b32_e32 v169, 0xffff0000, v135
	v_lshlrev_b32_e32 v135, 16, v136
	v_max_f32_e32 v135, v135, v135
	v_lshlrev_b32_e32 v149, 16, v134
	v_and_b32_e32 v151, 0xffff0000, v134
	v_max_f32_e32 v135, 0xda24260, v135
	v_and_b32_e32 v170, 0xffff0000, v136
	v_max_f32_e32 v134, v149, v149
	v_rcp_f32_e32 v136, v135
	v_max_f32_e32 v135, v151, v151
	v_max_f32_e32 v134, 0xda24260, v134
	v_max_f32_e32 v135, 0xda24260, v135
	v_rcp_f32_e32 v134, v134
	v_rcp_f32_e32 v135, v135
	v_and_b32_e32 v167, 0xffff0000, v130
	v_max_f32_e32 v130, v170, v170
	v_max_f32_e32 v130, 0xda24260, v130
	v_lshlrev_b32_e32 v171, 16, v137
	v_and_b32_e32 v172, 0xffff0000, v137
	v_rcp_f32_e32 v137, v130
	v_pk_mul_f32 v[134:135], v[134:135], v[166:167]
	v_max_f32_e32 v130, v168, v168
	v_pk_mul_f32 v[6:7], v[6:7], v[134:135]
	v_lshlrev_b32_e32 v134, 16, v132
	v_and_b32_e32 v135, 0xffff0000, v132
	v_pk_mul_f32 v[134:135], v[136:137], v[134:135]
	v_max_f32_e32 v130, 0xda24260, v130
	v_pk_mul_f32 v[2:3], v[2:3], v[134:135]
	v_rcp_f32_e32 v134, v130
	v_max_f32_e32 v130, v171, v171
	v_max_f32_e32 v132, v169, v169
	v_lshlrev_b32_e32 v136, 16, v131
	v_and_b32_e32 v137, 0xffff0000, v131
	v_max_f32_e32 v131, v172, v172
	v_max_f32_e32 v130, 0xda24260, v130
	v_max_f32_e32 v132, 0xda24260, v132
	v_max_f32_e32 v131, 0xda24260, v131
	v_rcp_f32_e32 v130, v130
	v_rcp_f32_e32 v135, v132
	v_rcp_f32_e32 v131, v131
	v_lshlrev_b32_e32 v132, 16, v133
	v_and_b32_e32 v133, 0xffff0000, v133
	v_pk_mul_f32 v[134:135], v[134:135], v[136:137]
	v_pk_mul_f32 v[130:131], v[130:131], v[132:133]
	v_pk_mul_f32 v[8:9], v[8:9], v[134:135]
	v_pk_mul_f32 v[4:5], v[4:5], v[130:131]
	s_branch .LBB0_524

; #define PG8_STAGE(bufoff, gbase, voff) do { _Pragma("unroll") for (int _i = 0; _i < 2; ++_i) \
;         __builtin_amdgcn_global_load_lds((const unsigned*)((const char*)(gbase) + (voff)[_i]), (PG8_LAS unsigned*)(lds + (bufoff) + ldsw + _i * 8192), 16, 0, 0); } while (0)
; #define PG8_LDA(dst, b, h) do { _Pragma("unroll") for (int m = 0; m < 4; ++m) _Pragma("unroll") for (int k = 0; k < 2; ++k) dst[m][k] = *(const PG8_LAS bf16x8*)(lds + PG8_SA(b, h) + aoff + m * 2048 + k * 1024); } while (0)
; #define PG8_LDB(dst, b, h) do { _Pragma("unroll") for (int n = 0; n < 2; ++n) _Pragma("unroll") for (int k = 0; k < 2; ++k) dst[n][k] = *(const PG8_LAS bf16x8*)(lds + PG8_SB(b, h) + boff + n * 2048 + k * 1024); } while (0)
; #define PG8_MMA(ai, bj, At, Bt) do { __builtin_amdgcn_s_setprio(1); _Pragma("unroll") for (int m = 0; m < 4; ++m) _Pragma("unroll") for (int n = 0; n < 2; ++n) _Pragma("unroll") for (int k = 0; k < 2; ++k) \
;         acc[ai][bj][m][n] = __builtin_amdgcn_mfma_f32_16x16x32_bf16(Bt[n][k], At[m][k], acc[ai][bj][m][n], 0, 0, 0); __builtin_amdgcn_s_setprio(0); } while (0)
; #define PG8_WAIT_V(n) asm volatile("s_waitcnt vmcnt(" #n ")" ::: "memory")
; #define PG8_WAIT_L(n) asm volatile("s_waitcnt lgkmcnt(" #n ")" ::: "memory")
; #define PG8_BAR __builtin_amdgcn_s_barrier()
; #define PG8_SCHED __builtin_amdgcn_sched_barrier(0)
; template <class Epi, class Sched, bool ALIGN_EPI = false, bool SP2 = false>
; __device__ __forceinline__ void gemm_phase(PG8_LAS unsigned char* lds, const Gemm g, const Sched& S, const Epi& E) {
;     ...
;             const bool last = (t == nt - 2);
;             const char* a1 = cA + (size_t)(t + 1) * kstep;
;             const char* a2 = last ? nA : cA + (size_t)(t + 2) * kstep; const char* b2 = last ? nB : cB + (size_t)(t + 2) * kstep;
;             const char* a3 = a2 + kstep; const char* b3 = b2 + kstep;
;             if (last && has_next) S.a_ready(nxt);
;             if constexpr (SP2) {
;             PG8_LDB(B0, 0, 0); PG8_LDB(B1, 0, 1); PG8_SCHED; PG8_LDA(At, 0, 0); PG8_STAGE(PG8_SA(1, 1), a1 + hstep, voffA);
;             PG8_WAIT_V(8); PG8_WAIT_L(0); PG8_BAR; PG8_MMA(0, 0, At, B0); PG8_MMA(0, 1, At, B1); PG8_BAR; PG8_SCHED;
;             PG8_LDA(At, 0, 1); PG8_STAGE(PG8_SB(0, 0), b2, voffB); PG8_STAGE(PG8_SB(0, 1), b2 + hstep, voffB); PG8_STAGE(PG8_SA(0, 0), a2, voffA);
.LBB0_566:
	s_add_i32 s40, s8, 2
	s_add_u32 s41, s0, 0x80
	s_addc_u32 s9, s1, 0
	s_add_i32 s93, 0, 0x10000
	s_cmp_eq_u32 s84, s8
	s_cselect_b32 s9, s37, s9
	s_cselect_b32 s8, s36, s41
	v_add_u32_e32 v160, s93, v157
	s_cselect_b32 s45, s51, s11
	s_cselect_b32 s44, s50, s10
	s_add_i32 s41, 0, 0x14000
	ds_read_b128 v[144:147], v160
	ds_read_b128 v[148:151], v160 offset:1024
	ds_read_b128 v[152:155], v160 offset:2048
	ds_read_b128 v[192:195], v160 offset:3072
	v_add_u32_e32 v160, s41, v157
	ds_read_b128 v[196:199], v160
	ds_read_b128 v[200:203], v160 offset:1024
	ds_read_b128 v[204:207], v160 offset:2048
	ds_read_b128 v[208:211], v160 offset:3072
	v_lshl_add_u64 v[166:167], s[0:1], 0, v[140:141]
	s_add_i32 m0, s59, 0xc000
	ds_read_b128 v[212:215], v182
	ds_read_b128 v[216:219], v182 offset:1024
	ds_read_b128 v[220:223], v182 offset:2048
	ds_read_b128 v[224:227], v182 offset:3072
	ds_read_b128 v[228:231], v182 offset:4096
	ds_read_b128 v[232:235], v182 offset:5120
	ds_read_b128 v[236:239], v182 offset:6144
	ds_read_b128 v[240:243], v182 offset:7168
	global_load_lds_dwordx4 v[166:167], off
	v_lshl_add_u64 v[166:167], s[0:1], 0, v[142:143]
	s_add_i32 m0, s59, 0xe000
	s_nop 0
	global_load_lds_dwordx4 v[166:167], off
	s_waitcnt vmcnt(8)
	s_waitcnt lgkmcnt(0)
	s_barrier
	s_setprio 1
	s_waitcnt lgkmcnt(0)
	v_mfma_f32_16x16x32_bf16 v[126:129], v[144:147], v[212:215], v[126:129]
	v_mfma_f32_16x16x32_bf16 v[122:125], v[152:155], v[212:215], v[122:125]
	v_mfma_f32_16x16x32_bf16 v[110:113], v[144:147], v[220:223], v[110:113]
	v_mfma_f32_16x16x32_bf16 v[106:109], v[152:155], v[220:223], v[106:109]
	v_mfma_f32_16x16x32_bf16 v[94:97], v[144:147], v[228:231], v[94:97]
	v_mfma_f32_16x16x32_bf16 v[90:93], v[152:155], v[228:231], v[90:93]
	v_mfma_f32_16x16x32_bf16 v[78:81], v[144:147], v[236:239], v[78:81]
	v_mfma_f32_16x16x32_bf16 v[74:77], v[152:155], v[236:239], v[74:77]
	v_mfma_f32_16x16x32_bf16 v[126:129], v[148:151], v[216:219], v[126:129]
	v_mfma_f32_16x16x32_bf16 v[122:125], v[192:195], v[216:219], v[122:125]
	v_mfma_f32_16x16x32_bf16 v[110:113], v[148:151], v[224:227], v[110:113]
	v_mfma_f32_16x16x32_bf16 v[106:109], v[192:195], v[224:227], v[106:109]
	v_mfma_f32_16x16x32_bf16 v[94:97], v[148:151], v[232:235], v[94:97]
	v_mfma_f32_16x16x32_bf16 v[90:93], v[192:195], v[232:235], v[90:93]
	v_mfma_f32_16x16x32_bf16 v[78:81], v[148:151], v[240:243], v[78:81]
	v_mfma_f32_16x16x32_bf16 v[74:77], v[192:195], v[240:243], v[74:77]
	s_setprio 0
	s_setprio 1
	v_mfma_f32_16x16x32_bf16 v[118:121], v[196:199], v[212:215], v[118:121]
	v_mfma_f32_16x16x32_bf16 v[114:117], v[204:207], v[212:215], v[114:117]
	v_mfma_f32_16x16x32_bf16 v[102:105], v[196:199], v[220:223], v[102:105]
	v_mfma_f32_16x16x32_bf16 v[98:101], v[204:207], v[220:223], v[98:101]
	v_mfma_f32_16x16x32_bf16 v[86:89], v[196:199], v[228:231], v[86:89]
	v_mfma_f32_16x16x32_bf16 v[82:85], v[204:207], v[228:231], v[82:85]
	v_mfma_f32_16x16x32_bf16 v[70:73], v[196:199], v[236:239], v[70:73]
	v_mfma_f32_16x16x32_bf16 v[66:69], v[204:207], v[236:239], v[66:69]
	v_mfma_f32_16x16x32_bf16 v[118:121], v[200:203], v[216:219], v[118:121]
	v_mfma_f32_16x16x32_bf16 v[114:117], v[208:211], v[216:219], v[114:117]
	v_mfma_f32_16x16x32_bf16 v[102:105], v[200:203], v[224:227], v[102:105]
	v_mfma_f32_16x16x32_bf16 v[98:101], v[208:211], v[224:227], v[98:101]
	v_mfma_f32_16x16x32_bf16 v[86:89], v[200:203], v[232:235], v[86:89]
	v_mfma_f32_16x16x32_bf16 v[82:85], v[208:211], v[232:235], v[82:85]
	v_mfma_f32_16x16x32_bf16 v[70:73], v[200:203], v[240:243], v[70:73]
	v_mfma_f32_16x16x32_bf16 v[66:69], v[208:211], v[240:243], v[66:69]
	s_setprio 0
	s_barrier
	s_add_i32 s93, s93, s4
	v_lshl_add_u64 v[166:167], s[44:45], 0, v[132:133]
	s_mov_b32 m0, s93
	ds_read_b128 v[212:215], v182 offset:16384
	ds_read_b128 v[216:219], v182 offset:17408
	ds_read_b128 v[220:223], v182 offset:18432
	ds_read_b128 v[224:227], v182 offset:19456
	ds_read_b128 v[228:231], v182 offset:20480
	ds_read_b128 v[232:235], v182 offset:21504
	ds_read_b128 v[236:239], v182 offset:22528
	ds_read_b128 v[240:243], v182 offset:23552
	global_load_lds_dwordx4 v[166:167], off
	s_add_i32 m0, s93, 0x2000
	v_lshl_add_u64 v[184:185], s[44:45], 0, v[136:137]
	s_add_u32 s44, s44, s14
	s_addc_u32 s45, s45, s15
	s_add_i32 s41, s41, s4
	global_load_lds_dwordx4 v[184:185], off
	v_lshl_add_u64 v[244:245], s[44:45], 0, v[132:133]
	s_mov_b32 m0, s41
	v_lshl_add_u64 v[246:247], s[44:45], 0, v[136:137]
	global_load_lds_dwordx4 v[244:245], off
	s_add_i32 m0, s41, 0x2000
	v_lshl_add_u64 v[248:249], s[8:9], 0, v[130:131]
	global_load_lds_dwordx4 v[246:247], off
	v_lshl_add_u64 v[250:251], s[8:9], 0, v[134:135]
	s_nop 0
	s_waitcnt vmcnt(6)
	s_waitcnt lgkmcnt(0)
	s_barrier
; #define PG8_STAGE(bufoff, gbase, voff) do { _Pragma("unroll") for (int _i = 0; _i < 2; ++_i) \
;         __builtin_amdgcn_global_load_lds((const unsigned*)((const char*)(gbase) + (voff)[_i]), (PG8_LAS unsigned*)(lds + (bufoff) + ldsw + _i * 8192), 16, 0, 0); } while (0)
; #define PG8_LDA(dst, b, h) do { _Pragma("unroll") for (int m = 0; m < 4; ++m) _Pragma("unroll") for (int k = 0; k < 2; ++k) dst[m][k] = *(const PG8_LAS bf16x8*)(lds + PG8_SA(b, h) + aoff + m * 2048 + k * 1024); } while (0)
; #define PG8_LDB(dst, b, h) do { _Pragma("unroll") for (int n = 0; n < 2; ++n) _Pragma("unroll") for (int k = 0; k < 2; ++k) dst[n][k] = *(const PG8_LAS bf16x8*)(lds + PG8_SB(b, h) + boff + n * 2048 + k * 1024); } while (0)
; #define PG8_MMA(ai, bj, At, Bt) do { __builtin_amdgcn_s_setprio(1); _Pragma("unroll") for (int m = 0; m < 4; ++m) _Pragma("unroll") for (int n = 0; n < 2; ++n) _Pragma("unroll") for (int k = 0; k < 2; ++k) \
;         acc[ai][bj][m][n] = __builtin_amdgcn_mfma_f32_16x16x32_bf16(Bt[n][k], At[m][k], acc[ai][bj][m][n], 0, 0, 0); __builtin_amdgcn_s_setprio(0); } while (0)
; #define PG8_WAIT_V(n) asm volatile("s_waitcnt vmcnt(" #n ")" ::: "memory")
; #define PG8_WAIT_L(n) asm volatile("s_waitcnt lgkmcnt(" #n ")" ::: "memory")
; #define PG8_BAR __builtin_amdgcn_s_barrier()
; #define PG8_SCHED __builtin_amdgcn_sched_barrier(0)
; template <class Epi, class Sched, bool ALIGN_EPI = false, bool SP2 = false>
; __device__ __forceinline__ void gemm_phase(PG8_LAS unsigned char* lds, const Gemm g, const Sched& S, const Epi& E) {
;     ...
;             PG8_WAIT_V(8); PG8_WAIT_L(0); PG8_BAR; PG8_MMA(1, 0, At, B0); PG8_MMA(1, 1, At, B1); PG8_BAR; PG8_SCHED;
;             PG8_LDB(B0, 1, 0); PG8_LDB(B1, 1, 1); PG8_SCHED; PG8_LDA(At, 1, 0); PG8_STAGE(PG8_SA(0, 1), a2 + hstep, voffA);
;             PG8_WAIT_V(8); PG8_WAIT_L(0); PG8_BAR; PG8_MMA(0, 0, At, B0); PG8_MMA(0, 1, At, B1); PG8_BAR; PG8_SCHED;
	s_setprio 1
	s_waitcnt lgkmcnt(0)
	v_mfma_f32_16x16x32_bf16 v[62:65], v[144:147], v[212:215], v[62:65]
	v_mfma_f32_16x16x32_bf16 v[58:61], v[152:155], v[212:215], v[58:61]
	v_mfma_f32_16x16x32_bf16 v[46:49], v[144:147], v[220:223], v[46:49]
	v_mfma_f32_16x16x32_bf16 v[42:45], v[152:155], v[220:223], v[42:45]
	v_mfma_f32_16x16x32_bf16 v[30:33], v[144:147], v[228:231], v[30:33]
	v_mfma_f32_16x16x32_bf16 v[26:29], v[152:155], v[228:231], v[26:29]
	v_mfma_f32_16x16x32_bf16 v[14:17], v[144:147], v[236:239], v[14:17]
	v_mfma_f32_16x16x32_bf16 v[10:13], v[152:155], v[236:239], v[10:13]
	v_mfma_f32_16x16x32_bf16 v[62:65], v[148:151], v[216:219], v[62:65]
	v_mfma_f32_16x16x32_bf16 v[58:61], v[192:195], v[216:219], v[58:61]
	v_mfma_f32_16x16x32_bf16 v[46:49], v[148:151], v[224:227], v[46:49]
	v_mfma_f32_16x16x32_bf16 v[42:45], v[192:195], v[224:227], v[42:45]
	v_mfma_f32_16x16x32_bf16 v[30:33], v[148:151], v[232:235], v[30:33]
	v_mfma_f32_16x16x32_bf16 v[26:29], v[192:195], v[232:235], v[26:29]
	v_mfma_f32_16x16x32_bf16 v[14:17], v[148:151], v[240:243], v[14:17]
	v_mfma_f32_16x16x32_bf16 v[10:13], v[192:195], v[240:243], v[10:13]
	s_setprio 0
	s_setprio 1
	v_mfma_f32_16x16x32_bf16 v[54:57], v[196:199], v[212:215], v[54:57]
	v_mfma_f32_16x16x32_bf16 v[50:53], v[204:207], v[212:215], v[50:53]
	v_mfma_f32_16x16x32_bf16 v[38:41], v[196:199], v[220:223], v[38:41]
	v_mfma_f32_16x16x32_bf16 v[34:37], v[204:207], v[220:223], v[34:37]
	v_mfma_f32_16x16x32_bf16 v[22:25], v[196:199], v[228:231], v[22:25]
	v_mfma_f32_16x16x32_bf16 v[18:21], v[204:207], v[228:231], v[18:21]
	v_mfma_f32_16x16x32_bf16 v[6:9], v[196:199], v[236:239], v[6:9]
	v_mfma_f32_16x16x32_bf16 v[2:5], v[204:207], v[236:239], v[2:5]
	v_mfma_f32_16x16x32_bf16 v[54:57], v[200:203], v[216:219], v[54:57]
	v_mfma_f32_16x16x32_bf16 v[50:53], v[208:211], v[216:219], v[50:53]
	v_mfma_f32_16x16x32_bf16 v[38:41], v[200:203], v[224:227], v[38:41]
	v_mfma_f32_16x16x32_bf16 v[34:37], v[208:211], v[224:227], v[34:37]
	v_mfma_f32_16x16x32_bf16 v[22:25], v[200:203], v[232:235], v[22:25]
	v_mfma_f32_16x16x32_bf16 v[18:21], v[208:211], v[232:235], v[18:21]
	v_mfma_f32_16x16x32_bf16 v[6:9], v[200:203], v[240:243], v[6:9]
	v_mfma_f32_16x16x32_bf16 v[2:5], v[208:211], v[240:243], v[2:5]
	s_setprio 0
	s_barrier
	s_add_i32 s41, 0, 0x18000
	v_add_u32_e32 v160, s41, v157
	s_add_i32 s44, 0, 0x1c000
	ds_read_b128 v[144:147], v160
	ds_read_b128 v[148:151], v160 offset:1024
	ds_read_b128 v[152:155], v160 offset:2048
	ds_read_b128 v[192:195], v160 offset:3072
	v_add_u32_e32 v160, s44, v157
	ds_read_b128 v[196:199], v160
	ds_read_b128 v[200:203], v160 offset:1024
	ds_read_b128 v[204:207], v160 offset:2048
	ds_read_b128 v[208:211], v160 offset:3072
	s_add_u32 s8, s8, s14
	s_addc_u32 s9, s9, s15
	s_mov_b32 m0, s59
	s_nop 0
	global_load_lds_dwordx4 v[248:249], off
	s_mov_b32 m0, s74
	s_nop 0
	global_load_lds_dwordx4 v[250:251], off
	s_mov_b32 m0, s75
	v_lshl_add_u64 v[252:253], s[8:9], 0, v[130:131]
	ds_read_b128 v[212:215], v182 offset:32768
	ds_read_b128 v[216:219], v182 offset:33792
	ds_read_b128 v[220:223], v182 offset:34816
	ds_read_b128 v[224:227], v182 offset:35840
	ds_read_b128 v[228:231], v182 offset:36864
	ds_read_b128 v[232:235], v182 offset:37888
	ds_read_b128 v[236:239], v182 offset:38912
	ds_read_b128 v[240:243], v182 offset:39936
	global_load_lds_dwordx4 v[252:253], off
	v_lshl_add_u64 v[252:253], s[8:9], 0, v[134:135]
	s_mov_b32 m0, s78
	s_nop 0
	global_load_lds_dwordx4 v[252:253], off
	s_waitcnt vmcnt(8)
	s_waitcnt lgkmcnt(0)
	s_barrier
	s_setprio 1
	s_waitcnt lgkmcnt(0)
	v_mfma_f32_16x16x32_bf16 v[126:129], v[144:147], v[212:215], v[126:129]
	v_mfma_f32_16x16x32_bf16 v[122:125], v[152:155], v[212:215], v[122:125]
	v_mfma_f32_16x16x32_bf16 v[110:113], v[144:147], v[220:223], v[110:113]
	v_mfma_f32_16x16x32_bf16 v[106:109], v[152:155], v[220:223], v[106:109]
	v_mfma_f32_16x16x32_bf16 v[94:97], v[144:147], v[228:231], v[94:97]
	v_mfma_f32_16x16x32_bf16 v[90:93], v[152:155], v[228:231], v[90:93]
	v_mfma_f32_16x16x32_bf16 v[78:81], v[144:147], v[236:239], v[78:81]
	v_mfma_f32_16x16x32_bf16 v[74:77], v[152:155], v[236:239], v[74:77]
	v_mfma_f32_16x16x32_bf16 v[126:129], v[148:151], v[216:219], v[126:129]
	v_mfma_f32_16x16x32_bf16 v[122:125], v[192:195], v[216:219], v[122:125]
	v_mfma_f32_16x16x32_bf16 v[110:113], v[148:151], v[224:227], v[110:113]
	v_mfma_f32_16x16x32_bf16 v[106:109], v[192:195], v[224:227], v[106:109]
	v_mfma_f32_16x16x32_bf16 v[94:97], v[148:151], v[232:235], v[94:97]
	v_mfma_f32_16x16x32_bf16 v[90:93], v[192:195], v[232:235], v[90:93]
	v_mfma_f32_16x16x32_bf16 v[78:81], v[148:151], v[240:243], v[78:81]
	v_mfma_f32_16x16x32_bf16 v[74:77], v[192:195], v[240:243], v[74:77]
	s_setprio 0
	s_setprio 1
	v_mfma_f32_16x16x32_bf16 v[118:121], v[196:199], v[212:215], v[118:121]
	v_mfma_f32_16x16x32_bf16 v[114:117], v[204:207], v[212:215], v[114:117]
	v_mfma_f32_16x16x32_bf16 v[102:105], v[196:199], v[220:223], v[102:105]
	v_mfma_f32_16x16x32_bf16 v[98:101], v[204:207], v[220:223], v[98:101]
	v_mfma_f32_16x16x32_bf16 v[86:89], v[196:199], v[228:231], v[86:89]
	v_mfma_f32_16x16x32_bf16 v[82:85], v[204:207], v[228:231], v[82:85]
	v_mfma_f32_16x16x32_bf16 v[70:73], v[196:199], v[236:239], v[70:73]
	v_mfma_f32_16x16x32_bf16 v[66:69], v[204:207], v[236:239], v[66:69]
	v_mfma_f32_16x16x32_bf16 v[118:121], v[200:203], v[216:219], v[118:121]
	v_mfma_f32_16x16x32_bf16 v[114:117], v[208:211], v[216:219], v[114:117]
	v_mfma_f32_16x16x32_bf16 v[102:105], v[200:203], v[224:227], v[102:105]
	v_mfma_f32_16x16x32_bf16 v[98:101], v[208:211], v[224:227], v[98:101]
	v_mfma_f32_16x16x32_bf16 v[86:89], v[200:203], v[232:235], v[86:89]
	v_mfma_f32_16x16x32_bf16 v[82:85], v[208:211], v[232:235], v[82:85]
	v_mfma_f32_16x16x32_bf16 v[70:73], v[200:203], v[240:243], v[70:73]
	v_mfma_f32_16x16x32_bf16 v[66:69], v[208:211], v[240:243], v[66:69]
	s_setprio 0
	s_barrier
; #define PG8_STAGE(bufoff, gbase, voff) do { _Pragma("unroll") for (int _i = 0; _i < 2; ++_i) \
;         __builtin_amdgcn_global_load_lds((const unsigned*)((const char*)(gbase) + (voff)[_i]), (PG8_LAS unsigned*)(lds + (bufoff) + ldsw + _i * 8192), 16, 0, 0); } while (0)
; #define PG8_LDA(dst, b, h) do { _Pragma("unroll") for (int m = 0; m < 4; ++m) _Pragma("unroll") for (int k = 0; k < 2; ++k) dst[m][k] = *(const PG8_LAS bf16x8*)(lds + PG8_SA(b, h) + aoff + m * 2048 + k * 1024); } while (0)
; #define PG8_MMA(ai, bj, At, Bt) do { __builtin_amdgcn_s_setprio(1); _Pragma("unroll") for (int m = 0; m < 4; ++m) _Pragma("unroll") for (int n = 0; n < 2; ++n) _Pragma("unroll") for (int k = 0; k < 2; ++k) \
;         acc[ai][bj][m][n] = __builtin_amdgcn_mfma_f32_16x16x32_bf16(Bt[n][k], At[m][k], acc[ai][bj][m][n], 0, 0, 0); __builtin_amdgcn_s_setprio(0); } while (0)
; #define PG8_WAIT_V(n) asm volatile("s_waitcnt vmcnt(" #n ")" ::: "memory")
; #define PG8_WAIT_L(n) asm volatile("s_waitcnt lgkmcnt(" #n ")" ::: "memory")
; #define PG8_BAR __builtin_amdgcn_s_barrier()
; #define PG8_SCHED __builtin_amdgcn_sched_barrier(0)
; template <class Epi, class Sched, bool ALIGN_EPI = false, bool SP2 = false>
; __device__ __forceinline__ void gemm_phase(PG8_LAS unsigned char* lds, const Gemm g, const Sched& S, const Epi& E) {
;     ...
;         for (int t = 0; t < nt; t += 2) {
;     ...
;             PG8_LDA(At, 1, 1); PG8_STAGE(PG8_SB(1, 0), b3, voffB); PG8_STAGE(PG8_SB(1, 1), b3 + hstep, voffB); PG8_STAGE(PG8_SA(1, 0), a3, voffA);
;             PG8_WAIT_V(8); PG8_WAIT_L(0); PG8_BAR; PG8_MMA(1, 0, At, B0); PG8_MMA(1, 1, At, B1); PG8_BAR; PG8_SCHED;
	s_add_i32 s8, s41, s4
	v_lshl_add_u64 v[166:167], v[166:167], 0, s[88:89]
	s_mov_b32 m0, s8
	ds_read_b128 v[212:215], v182 offset:49152
	ds_read_b128 v[216:219], v182 offset:50176
	ds_read_b128 v[220:223], v182 offset:51200
	ds_read_b128 v[224:227], v182 offset:52224
	ds_read_b128 v[228:231], v182 offset:53248
	ds_read_b128 v[232:235], v182 offset:54272
	ds_read_b128 v[236:239], v182 offset:55296
	ds_read_b128 v[240:243], v182 offset:56320
	global_load_lds_dwordx4 v[166:167], off
	v_lshl_add_u64 v[166:167], v[184:185], 0, s[88:89]
	s_add_i32 m0, s8, 0x2000
	s_add_i32 s8, s44, s4
	global_load_lds_dwordx4 v[166:167], off
	v_lshl_add_u64 v[166:167], v[244:245], 0, s[88:89]
	s_mov_b32 m0, s8
	s_nop 0
	global_load_lds_dwordx4 v[166:167], off
	v_lshl_add_u64 v[166:167], v[246:247], 0, s[88:89]
	s_add_i32 m0, s8, 0x2000
	s_nop 0
	global_load_lds_dwordx4 v[166:167], off
	v_lshl_add_u64 v[166:167], v[248:249], 0, s[88:89]
	s_mov_b32 m0, s79
	s_nop 0
	global_load_lds_dwordx4 v[166:167], off
	v_lshl_add_u64 v[166:167], v[250:251], 0, s[88:89]
	s_mov_b32 m0, s80
	s_nop 0
	global_load_lds_dwordx4 v[166:167], off
	s_waitcnt vmcnt(8)
	s_waitcnt lgkmcnt(0)
	s_barrier
	s_setprio 1
	s_waitcnt lgkmcnt(0)
	v_mfma_f32_16x16x32_bf16 v[62:65], v[144:147], v[212:215], v[62:65]
	v_mfma_f32_16x16x32_bf16 v[58:61], v[152:155], v[212:215], v[58:61]
	v_mfma_f32_16x16x32_bf16 v[46:49], v[144:147], v[220:223], v[46:49]
	v_mfma_f32_16x16x32_bf16 v[42:45], v[152:155], v[220:223], v[42:45]
	v_mfma_f32_16x16x32_bf16 v[30:33], v[144:147], v[228:231], v[30:33]
	v_mfma_f32_16x16x32_bf16 v[26:29], v[152:155], v[228:231], v[26:29]
	v_mfma_f32_16x16x32_bf16 v[14:17], v[144:147], v[236:239], v[14:17]
	v_mfma_f32_16x16x32_bf16 v[10:13], v[152:155], v[236:239], v[10:13]
	v_mfma_f32_16x16x32_bf16 v[62:65], v[148:151], v[216:219], v[62:65]
	v_mfma_f32_16x16x32_bf16 v[58:61], v[192:195], v[216:219], v[58:61]
	v_mfma_f32_16x16x32_bf16 v[46:49], v[148:151], v[224:227], v[46:49]
	v_mfma_f32_16x16x32_bf16 v[42:45], v[192:195], v[224:227], v[42:45]
	v_mfma_f32_16x16x32_bf16 v[30:33], v[148:151], v[232:235], v[30:33]
	v_mfma_f32_16x16x32_bf16 v[26:29], v[192:195], v[232:235], v[26:29]
	v_mfma_f32_16x16x32_bf16 v[14:17], v[148:151], v[240:243], v[14:17]
	v_mfma_f32_16x16x32_bf16 v[10:13], v[192:195], v[240:243], v[10:13]
	s_setprio 0
	s_setprio 1
	v_mfma_f32_16x16x32_bf16 v[54:57], v[196:199], v[212:215], v[54:57]
	v_mfma_f32_16x16x32_bf16 v[50:53], v[204:207], v[212:215], v[50:53]
	v_mfma_f32_16x16x32_bf16 v[38:41], v[196:199], v[220:223], v[38:41]
	v_mfma_f32_16x16x32_bf16 v[34:37], v[204:207], v[220:223], v[34:37]
	v_mfma_f32_16x16x32_bf16 v[22:25], v[196:199], v[228:231], v[22:25]
	v_mfma_f32_16x16x32_bf16 v[18:21], v[204:207], v[228:231], v[18:21]
	v_mfma_f32_16x16x32_bf16 v[6:9], v[196:199], v[236:239], v[6:9]
	v_mfma_f32_16x16x32_bf16 v[2:5], v[204:207], v[236:239], v[2:5]
	v_mfma_f32_16x16x32_bf16 v[54:57], v[200:203], v[216:219], v[54:57]
	v_mfma_f32_16x16x32_bf16 v[50:53], v[208:211], v[216:219], v[50:53]
	v_mfma_f32_16x16x32_bf16 v[38:41], v[200:203], v[224:227], v[38:41]
	v_mfma_f32_16x16x32_bf16 v[34:37], v[208:211], v[224:227], v[34:37]
	v_mfma_f32_16x16x32_bf16 v[22:25], v[200:203], v[232:235], v[22:25]
	v_mfma_f32_16x16x32_bf16 v[18:21], v[208:211], v[232:235], v[18:21]
	v_mfma_f32_16x16x32_bf16 v[6:9], v[200:203], v[240:243], v[6:9]
	v_mfma_f32_16x16x32_bf16 v[2:5], v[208:211], v[240:243], v[2:5]
	s_setprio 0
	s_barrier
	s_add_u32 s0, s0, 0x100
	s_addc_u32 s1, s1, 0
	s_add_u32 s10, s10, 0x100
	s_addc_u32 s11, s11, 0
	s_cmp_ge_i32 s40, s81
	s_mov_b32 s8, s40
	s_cbranch_scc0 .LBB0_566

; #define PG8_STAGE(bufoff, gbase, voff) do { _Pragma("unroll") for (int _i = 0; _i < 2; ++_i) \
;         __builtin_amdgcn_global_load_lds((const unsigned*)((const char*)(gbase) + (voff)[_i]), (PG8_LAS unsigned*)(lds + (bufoff) + ldsw + _i * 8192), 16, 0, 0); } while (0)
; #define PG8_LDA(dst, b, h) do { _Pragma("unroll") for (int m = 0; m < 4; ++m) _Pragma("unroll") for (int k = 0; k < 2; ++k) dst[m][k] = *(const PG8_LAS bf16x8*)(lds + PG8_SA(b, h) + aoff + m * 2048 + k * 1024); } while (0)
; #define PG8_LDB(dst, b, h) do { _Pragma("unroll") for (int n = 0; n < 2; ++n) _Pragma("unroll") for (int k = 0; k < 2; ++k) dst[n][k] = *(const PG8_LAS bf16x8*)(lds + PG8_SB(b, h) + boff + n * 2048 + k * 1024); } while (0)
; #define PG8_MMA(ai, bj, At, Bt) do { __builtin_amdgcn_s_setprio(1); _Pragma("unroll") for (int m = 0; m < 4; ++m) _Pragma("unroll") for (int n = 0; n < 2; ++n) _Pragma("unroll") for (int k = 0; k < 2; ++k) \
;         acc[ai][bj][m][n] = __builtin_amdgcn_mfma_f32_16x16x32_bf16(Bt[n][k], At[m][k], acc[ai][bj][m][n], 0, 0, 0); __builtin_amdgcn_s_setprio(0); } while (0)
; #define PG8_WAIT_V(n) asm volatile("s_waitcnt vmcnt(" #n ")" ::: "memory")
; #define PG8_WAIT_L(n) asm volatile("s_waitcnt lgkmcnt(" #n ")" ::: "memory")
; #define PG8_BAR __builtin_amdgcn_s_barrier()
; #define PG8_SCHED __builtin_amdgcn_sched_barrier(0)
; template <class Epi, class Sched, bool ALIGN_EPI = false, bool SP2 = false>
; __device__ __forceinline__ void gemm_phase(PG8_LAS unsigned char* lds, const Gemm g, const Sched& S, const Epi& E) {
;     ...
;             const bool last = (t == nt - 2);
;             const char* a1 = cA + (size_t)(t + 1) * kstep;
;             const char* a2 = last ? nA : cA + (size_t)(t + 2) * kstep; const char* b2 = last ? nB : cB + (size_t)(t + 2) * kstep;
;             const char* a3 = a2 + kstep; const char* b3 = b2 + kstep;
;             if (last && has_next) S.a_ready(nxt);
;             if constexpr (SP2) {
;             PG8_LDB(B0, 0, 0); PG8_LDB(B1, 0, 1); PG8_SCHED; PG8_LDA(At, 0, 0); PG8_STAGE(PG8_SA(1, 1), a1 + hstep, voffA);
;             PG8_WAIT_V(8); PG8_WAIT_L(0); PG8_BAR; PG8_MMA(0, 0, At, B0); PG8_MMA(0, 1, At, B1); PG8_BAR; PG8_SCHED;
;             PG8_LDA(At, 0, 1); PG8_STAGE(PG8_SB(0, 0), b2, voffB); PG8_STAGE(PG8_SB(0, 1), b2 + hstep, voffB); PG8_STAGE(PG8_SA(0, 0), a2, voffA);
.LBB0_659:
	s_add_i32 s36, s8, 2
	s_add_u32 s37, s0, 0x80
	s_addc_u32 s9, s1, 0
	s_add_i32 s43, 0, 0x10000
	s_cmp_eq_u32 s81, s8
	s_cselect_b32 s9, s31, s9
	s_cselect_b32 s8, s30, s37
	v_add_u32_e32 v148, s43, v151
	s_cselect_b32 s93, s35, s11
	s_cselect_b32 s92, s34, s10
	s_add_i32 s37, 0, 0x14000
	ds_read_b128 v[174:177], v148
	ds_read_b128 v[178:181], v148 offset:1024
	ds_read_b128 v[182:185], v148 offset:2048
	ds_read_b128 v[192:195], v148 offset:3072
	v_add_u32_e32 v148, s37, v151
	ds_read_b128 v[196:199], v148
	ds_read_b128 v[200:203], v148 offset:1024
	ds_read_b128 v[204:207], v148 offset:2048
	ds_read_b128 v[208:211], v148 offset:3072
	v_lshl_add_u64 v[148:149], s[0:1], 0, v[144:145]
	s_add_i32 m0, s53, 0xc000
	ds_read_b128 v[212:215], v172
	ds_read_b128 v[216:219], v172 offset:1024
	ds_read_b128 v[220:223], v172 offset:2048
	ds_read_b128 v[224:227], v172 offset:3072
	ds_read_b128 v[228:231], v172 offset:4096
	ds_read_b128 v[232:235], v172 offset:5120
	ds_read_b128 v[236:239], v172 offset:6144
	ds_read_b128 v[240:243], v172 offset:7168
	global_load_lds_dwordx4 v[148:149], off
	v_lshl_add_u64 v[148:149], s[0:1], 0, v[146:147]
	s_add_i32 m0, s53, 0xe000
	s_nop 0
	global_load_lds_dwordx4 v[148:149], off
	s_waitcnt vmcnt(8)
	s_waitcnt lgkmcnt(0)
	s_barrier
	s_setprio 1
	s_waitcnt lgkmcnt(0)
	v_mfma_f32_16x16x32_bf16 v[126:129], v[174:177], v[212:215], v[126:129]
	v_mfma_f32_16x16x32_bf16 v[122:125], v[182:185], v[212:215], v[122:125]
	v_mfma_f32_16x16x32_bf16 v[110:113], v[174:177], v[220:223], v[110:113]
	v_mfma_f32_16x16x32_bf16 v[106:109], v[182:185], v[220:223], v[106:109]
	v_mfma_f32_16x16x32_bf16 v[94:97], v[174:177], v[228:231], v[94:97]
	v_mfma_f32_16x16x32_bf16 v[90:93], v[182:185], v[228:231], v[90:93]
	v_mfma_f32_16x16x32_bf16 v[78:81], v[174:177], v[236:239], v[78:81]
	v_mfma_f32_16x16x32_bf16 v[74:77], v[182:185], v[236:239], v[74:77]
	v_mfma_f32_16x16x32_bf16 v[126:129], v[178:181], v[216:219], v[126:129]
	v_mfma_f32_16x16x32_bf16 v[122:125], v[192:195], v[216:219], v[122:125]
	v_mfma_f32_16x16x32_bf16 v[110:113], v[178:181], v[224:227], v[110:113]
	v_mfma_f32_16x16x32_bf16 v[106:109], v[192:195], v[224:227], v[106:109]
	v_mfma_f32_16x16x32_bf16 v[94:97], v[178:181], v[232:235], v[94:97]
	v_mfma_f32_16x16x32_bf16 v[90:93], v[192:195], v[232:235], v[90:93]
	v_mfma_f32_16x16x32_bf16 v[78:81], v[178:181], v[240:243], v[78:81]
	v_mfma_f32_16x16x32_bf16 v[74:77], v[192:195], v[240:243], v[74:77]
	s_setprio 0
	s_setprio 1
	v_mfma_f32_16x16x32_bf16 v[118:121], v[196:199], v[212:215], v[118:121]
	v_mfma_f32_16x16x32_bf16 v[114:117], v[204:207], v[212:215], v[114:117]
	v_mfma_f32_16x16x32_bf16 v[102:105], v[196:199], v[220:223], v[102:105]
	v_mfma_f32_16x16x32_bf16 v[98:101], v[204:207], v[220:223], v[98:101]
	v_mfma_f32_16x16x32_bf16 v[86:89], v[196:199], v[228:231], v[86:89]
	v_mfma_f32_16x16x32_bf16 v[82:85], v[204:207], v[228:231], v[82:85]
	v_mfma_f32_16x16x32_bf16 v[70:73], v[196:199], v[236:239], v[70:73]
	v_mfma_f32_16x16x32_bf16 v[66:69], v[204:207], v[236:239], v[66:69]
	v_mfma_f32_16x16x32_bf16 v[118:121], v[200:203], v[216:219], v[118:121]
	v_mfma_f32_16x16x32_bf16 v[114:117], v[208:211], v[216:219], v[114:117]
	v_mfma_f32_16x16x32_bf16 v[102:105], v[200:203], v[224:227], v[102:105]
	v_mfma_f32_16x16x32_bf16 v[98:101], v[208:211], v[224:227], v[98:101]
	v_mfma_f32_16x16x32_bf16 v[86:89], v[200:203], v[232:235], v[86:89]
	v_mfma_f32_16x16x32_bf16 v[82:85], v[208:211], v[232:235], v[82:85]
	v_mfma_f32_16x16x32_bf16 v[70:73], v[200:203], v[240:243], v[70:73]
	v_mfma_f32_16x16x32_bf16 v[66:69], v[208:211], v[240:243], v[66:69]
	s_setprio 0
	s_barrier
	s_add_i32 s43, s43, s4
	v_lshl_add_u64 v[148:149], s[92:93], 0, v[132:133]
	s_mov_b32 m0, s43
	ds_read_b128 v[212:215], v172 offset:16384
	ds_read_b128 v[216:219], v172 offset:17408
	ds_read_b128 v[220:223], v172 offset:18432
	ds_read_b128 v[224:227], v172 offset:19456
	ds_read_b128 v[228:231], v172 offset:20480
	ds_read_b128 v[232:235], v172 offset:21504
	ds_read_b128 v[236:239], v172 offset:22528
	ds_read_b128 v[240:243], v172 offset:23552
	global_load_lds_dwordx4 v[148:149], off
	s_add_i32 m0, s43, 0x2000
	v_lshl_add_u64 v[244:245], s[92:93], 0, v[136:137]
	s_add_u32 s92, s92, s20
	s_addc_u32 s93, s93, s21
	s_add_i32 s37, s37, s4
	global_load_lds_dwordx4 v[244:245], off
	v_lshl_add_u64 v[246:247], s[92:93], 0, v[132:133]
	s_mov_b32 m0, s37
	v_lshl_add_u64 v[248:249], s[92:93], 0, v[136:137]
	global_load_lds_dwordx4 v[246:247], off
	s_add_i32 m0, s37, 0x2000
	v_lshl_add_u64 v[250:251], s[8:9], 0, v[130:131]
	global_load_lds_dwordx4 v[248:249], off
	v_lshl_add_u64 v[252:253], s[8:9], 0, v[134:135]
	s_nop 0
	s_waitcnt vmcnt(6)
	s_waitcnt lgkmcnt(0)
	s_barrier
; #define PG8_STAGE(bufoff, gbase, voff) do { _Pragma("unroll") for (int _i = 0; _i < 2; ++_i) \
;         __builtin_amdgcn_global_load_lds((const unsigned*)((const char*)(gbase) + (voff)[_i]), (PG8_LAS unsigned*)(lds + (bufoff) + ldsw + _i * 8192), 16, 0, 0); } while (0)
; #define PG8_LDA(dst, b, h) do { _Pragma("unroll") for (int m = 0; m < 4; ++m) _Pragma("unroll") for (int k = 0; k < 2; ++k) dst[m][k] = *(const PG8_LAS bf16x8*)(lds + PG8_SA(b, h) + aoff + m * 2048 + k * 1024); } while (0)
; #define PG8_LDB(dst, b, h) do { _Pragma("unroll") for (int n = 0; n < 2; ++n) _Pragma("unroll") for (int k = 0; k < 2; ++k) dst[n][k] = *(const PG8_LAS bf16x8*)(lds + PG8_SB(b, h) + boff + n * 2048 + k * 1024); } while (0)
; #define PG8_MMA(ai, bj, At, Bt) do { __builtin_amdgcn_s_setprio(1); _Pragma("unroll") for (int m = 0; m < 4; ++m) _Pragma("unroll") for (int n = 0; n < 2; ++n) _Pragma("unroll") for (int k = 0; k < 2; ++k) \
;         acc[ai][bj][m][n] = __builtin_amdgcn_mfma_f32_16x16x32_bf16(Bt[n][k], At[m][k], acc[ai][bj][m][n], 0, 0, 0); __builtin_amdgcn_s_setprio(0); } while (0)
; #define PG8_WAIT_V(n) asm volatile("s_waitcnt vmcnt(" #n ")" ::: "memory")
; #define PG8_WAIT_L(n) asm volatile("s_waitcnt lgkmcnt(" #n ")" ::: "memory")
; #define PG8_BAR __builtin_amdgcn_s_barrier()
; #define PG8_SCHED __builtin_amdgcn_sched_barrier(0)
; template <class Epi, class Sched, bool ALIGN_EPI = false, bool SP2 = false>
; __device__ __forceinline__ void gemm_phase(PG8_LAS unsigned char* lds, const Gemm g, const Sched& S, const Epi& E) {
;     ...
;             PG8_WAIT_V(8); PG8_WAIT_L(0); PG8_BAR; PG8_MMA(1, 0, At, B0); PG8_MMA(1, 1, At, B1); PG8_BAR; PG8_SCHED;
;             PG8_LDB(B0, 1, 0); PG8_LDB(B1, 1, 1); PG8_SCHED; PG8_LDA(At, 1, 0); PG8_STAGE(PG8_SA(0, 1), a2 + hstep, voffA);
;             PG8_WAIT_V(8); PG8_WAIT_L(0); PG8_BAR; PG8_MMA(0, 0, At, B0); PG8_MMA(0, 1, At, B1); PG8_BAR; PG8_SCHED;
	s_setprio 1
	s_waitcnt lgkmcnt(0)
	v_mfma_f32_16x16x32_bf16 v[62:65], v[174:177], v[212:215], v[62:65]
	v_mfma_f32_16x16x32_bf16 v[58:61], v[182:185], v[212:215], v[58:61]
	v_mfma_f32_16x16x32_bf16 v[46:49], v[174:177], v[220:223], v[46:49]
	v_mfma_f32_16x16x32_bf16 v[42:45], v[182:185], v[220:223], v[42:45]
	v_mfma_f32_16x16x32_bf16 v[30:33], v[174:177], v[228:231], v[30:33]
	v_mfma_f32_16x16x32_bf16 v[26:29], v[182:185], v[228:231], v[26:29]
	v_mfma_f32_16x16x32_bf16 v[14:17], v[174:177], v[236:239], v[14:17]
	v_mfma_f32_16x16x32_bf16 v[10:13], v[182:185], v[236:239], v[10:13]
	v_mfma_f32_16x16x32_bf16 v[62:65], v[178:181], v[216:219], v[62:65]
	v_mfma_f32_16x16x32_bf16 v[58:61], v[192:195], v[216:219], v[58:61]
	v_mfma_f32_16x16x32_bf16 v[46:49], v[178:181], v[224:227], v[46:49]
	v_mfma_f32_16x16x32_bf16 v[42:45], v[192:195], v[224:227], v[42:45]
	v_mfma_f32_16x16x32_bf16 v[30:33], v[178:181], v[232:235], v[30:33]
	v_mfma_f32_16x16x32_bf16 v[26:29], v[192:195], v[232:235], v[26:29]
	v_mfma_f32_16x16x32_bf16 v[14:17], v[178:181], v[240:243], v[14:17]
	v_mfma_f32_16x16x32_bf16 v[10:13], v[192:195], v[240:243], v[10:13]
	s_setprio 0
	s_setprio 1
	v_mfma_f32_16x16x32_bf16 v[54:57], v[196:199], v[212:215], v[54:57]
	v_mfma_f32_16x16x32_bf16 v[50:53], v[204:207], v[212:215], v[50:53]
	v_mfma_f32_16x16x32_bf16 v[38:41], v[196:199], v[220:223], v[38:41]
	v_mfma_f32_16x16x32_bf16 v[34:37], v[204:207], v[220:223], v[34:37]
	v_mfma_f32_16x16x32_bf16 v[22:25], v[196:199], v[228:231], v[22:25]
	v_mfma_f32_16x16x32_bf16 v[18:21], v[204:207], v[228:231], v[18:21]
	v_mfma_f32_16x16x32_bf16 v[6:9], v[196:199], v[236:239], v[6:9]
	v_mfma_f32_16x16x32_bf16 v[2:5], v[204:207], v[236:239], v[2:5]
	v_mfma_f32_16x16x32_bf16 v[54:57], v[200:203], v[216:219], v[54:57]
	v_mfma_f32_16x16x32_bf16 v[50:53], v[208:211], v[216:219], v[50:53]
	v_mfma_f32_16x16x32_bf16 v[38:41], v[200:203], v[224:227], v[38:41]
	v_mfma_f32_16x16x32_bf16 v[34:37], v[208:211], v[224:227], v[34:37]
	v_mfma_f32_16x16x32_bf16 v[22:25], v[200:203], v[232:235], v[22:25]
	v_mfma_f32_16x16x32_bf16 v[18:21], v[208:211], v[232:235], v[18:21]
	v_mfma_f32_16x16x32_bf16 v[6:9], v[200:203], v[240:243], v[6:9]
	v_mfma_f32_16x16x32_bf16 v[2:5], v[208:211], v[240:243], v[2:5]
	s_setprio 0
	s_barrier
	s_add_i32 s37, 0, 0x18000
	v_add_u32_e32 v166, s37, v151
	s_add_i32 s43, 0, 0x1c000
	ds_read_b128 v[174:177], v166
	ds_read_b128 v[178:181], v166 offset:1024
	ds_read_b128 v[182:185], v166 offset:2048
	ds_read_b128 v[192:195], v166 offset:3072
	v_add_u32_e32 v166, s43, v151
	ds_read_b128 v[196:199], v166
	ds_read_b128 v[200:203], v166 offset:1024
	ds_read_b128 v[204:207], v166 offset:2048
	ds_read_b128 v[208:211], v166 offset:3072
	s_add_u32 s8, s8, s20
	s_addc_u32 s9, s9, s21
	s_mov_b32 m0, s53
	s_nop 0
	global_load_lds_dwordx4 v[250:251], off
	s_mov_b32 m0, s56
	s_nop 0
	global_load_lds_dwordx4 v[252:253], off
	s_mov_b32 m0, s59
	v_lshl_add_u64 v[166:167], s[8:9], 0, v[130:131]
	ds_read_b128 v[212:215], v172 offset:32768
	ds_read_b128 v[216:219], v172 offset:33792
	ds_read_b128 v[220:223], v172 offset:34816
	ds_read_b128 v[224:227], v172 offset:35840
	ds_read_b128 v[228:231], v172 offset:36864
	ds_read_b128 v[232:235], v172 offset:37888
	ds_read_b128 v[236:239], v172 offset:38912
	ds_read_b128 v[240:243], v172 offset:39936
	global_load_lds_dwordx4 v[166:167], off
	v_lshl_add_u64 v[166:167], s[8:9], 0, v[134:135]
	s_mov_b32 m0, s74
	s_nop 0
	global_load_lds_dwordx4 v[166:167], off
	s_waitcnt vmcnt(8)
	s_waitcnt lgkmcnt(0)
	s_barrier
	s_setprio 1
	s_waitcnt lgkmcnt(0)
	v_mfma_f32_16x16x32_bf16 v[126:129], v[174:177], v[212:215], v[126:129]
	v_mfma_f32_16x16x32_bf16 v[122:125], v[182:185], v[212:215], v[122:125]
	v_mfma_f32_16x16x32_bf16 v[110:113], v[174:177], v[220:223], v[110:113]
	v_mfma_f32_16x16x32_bf16 v[106:109], v[182:185], v[220:223], v[106:109]
	v_mfma_f32_16x16x32_bf16 v[94:97], v[174:177], v[228:231], v[94:97]
	v_mfma_f32_16x16x32_bf16 v[90:93], v[182:185], v[228:231], v[90:93]
	v_mfma_f32_16x16x32_bf16 v[78:81], v[174:177], v[236:239], v[78:81]
	v_mfma_f32_16x16x32_bf16 v[74:77], v[182:185], v[236:239], v[74:77]
	v_mfma_f32_16x16x32_bf16 v[126:129], v[178:181], v[216:219], v[126:129]
	v_mfma_f32_16x16x32_bf16 v[122:125], v[192:195], v[216:219], v[122:125]
	v_mfma_f32_16x16x32_bf16 v[110:113], v[178:181], v[224:227], v[110:113]
	v_mfma_f32_16x16x32_bf16 v[106:109], v[192:195], v[224:227], v[106:109]
	v_mfma_f32_16x16x32_bf16 v[94:97], v[178:181], v[232:235], v[94:97]
	v_mfma_f32_16x16x32_bf16 v[90:93], v[192:195], v[232:235], v[90:93]
	v_mfma_f32_16x16x32_bf16 v[78:81], v[178:181], v[240:243], v[78:81]
	v_mfma_f32_16x16x32_bf16 v[74:77], v[192:195], v[240:243], v[74:77]
	s_setprio 0
	s_setprio 1
	v_mfma_f32_16x16x32_bf16 v[118:121], v[196:199], v[212:215], v[118:121]
	v_mfma_f32_16x16x32_bf16 v[114:117], v[204:207], v[212:215], v[114:117]
	v_mfma_f32_16x16x32_bf16 v[102:105], v[196:199], v[220:223], v[102:105]
	v_mfma_f32_16x16x32_bf16 v[98:101], v[204:207], v[220:223], v[98:101]
	v_mfma_f32_16x16x32_bf16 v[86:89], v[196:199], v[228:231], v[86:89]
	v_mfma_f32_16x16x32_bf16 v[82:85], v[204:207], v[228:231], v[82:85]
	v_mfma_f32_16x16x32_bf16 v[70:73], v[196:199], v[236:239], v[70:73]
	v_mfma_f32_16x16x32_bf16 v[66:69], v[204:207], v[236:239], v[66:69]
	v_mfma_f32_16x16x32_bf16 v[118:121], v[200:203], v[216:219], v[118:121]
	v_mfma_f32_16x16x32_bf16 v[114:117], v[208:211], v[216:219], v[114:117]
	v_mfma_f32_16x16x32_bf16 v[102:105], v[200:203], v[224:227], v[102:105]
	v_mfma_f32_16x16x32_bf16 v[98:101], v[208:211], v[224:227], v[98:101]
	v_mfma_f32_16x16x32_bf16 v[86:89], v[200:203], v[232:235], v[86:89]
	v_mfma_f32_16x16x32_bf16 v[82:85], v[208:211], v[232:235], v[82:85]
	v_mfma_f32_16x16x32_bf16 v[70:73], v[200:203], v[240:243], v[70:73]
	v_mfma_f32_16x16x32_bf16 v[66:69], v[208:211], v[240:243], v[66:69]
	s_setprio 0
	s_barrier
; #define PG8_STAGE(bufoff, gbase, voff) do { _Pragma("unroll") for (int _i = 0; _i < 2; ++_i) \
;         __builtin_amdgcn_global_load_lds((const unsigned*)((const char*)(gbase) + (voff)[_i]), (PG8_LAS unsigned*)(lds + (bufoff) + ldsw + _i * 8192), 16, 0, 0); } while (0)
; #define PG8_LDA(dst, b, h) do { _Pragma("unroll") for (int m = 0; m < 4; ++m) _Pragma("unroll") for (int k = 0; k < 2; ++k) dst[m][k] = *(const PG8_LAS bf16x8*)(lds + PG8_SA(b, h) + aoff + m * 2048 + k * 1024); } while (0)
; #define PG8_MMA(ai, bj, At, Bt) do { __builtin_amdgcn_s_setprio(1); _Pragma("unroll") for (int m = 0; m < 4; ++m) _Pragma("unroll") for (int n = 0; n < 2; ++n) _Pragma("unroll") for (int k = 0; k < 2; ++k) \
;         acc[ai][bj][m][n] = __builtin_amdgcn_mfma_f32_16x16x32_bf16(Bt[n][k], At[m][k], acc[ai][bj][m][n], 0, 0, 0); __builtin_amdgcn_s_setprio(0); } while (0)
; #define PG8_WAIT_V(n) asm volatile("s_waitcnt vmcnt(" #n ")" ::: "memory")
; #define PG8_WAIT_L(n) asm volatile("s_waitcnt lgkmcnt(" #n ")" ::: "memory")
; #define PG8_BAR __builtin_amdgcn_s_barrier()
; #define PG8_SCHED __builtin_amdgcn_sched_barrier(0)
; template <class Epi, class Sched, bool ALIGN_EPI = false, bool SP2 = false>
; __device__ __forceinline__ void gemm_phase(PG8_LAS unsigned char* lds, const Gemm g, const Sched& S, const Epi& E) {
;     ...
;         for (int t = 0; t < nt; t += 2) {
;     ...
;             PG8_LDA(At, 1, 1); PG8_STAGE(PG8_SB(1, 0), b3, voffB); PG8_STAGE(PG8_SB(1, 1), b3 + hstep, voffB); PG8_STAGE(PG8_SA(1, 0), a3, voffA);
;             PG8_WAIT_V(8); PG8_WAIT_L(0); PG8_BAR; PG8_MMA(1, 0, At, B0); PG8_MMA(1, 1, At, B1); PG8_BAR; PG8_SCHED;
	s_add_i32 s8, s37, s4
	v_lshl_add_u64 v[148:149], v[148:149], 0, s[88:89]
	s_mov_b32 m0, s8
	ds_read_b128 v[212:215], v172 offset:49152
	ds_read_b128 v[216:219], v172 offset:50176
	ds_read_b128 v[220:223], v172 offset:51200
	ds_read_b128 v[224:227], v172 offset:52224
	ds_read_b128 v[228:231], v172 offset:53248
	ds_read_b128 v[232:235], v172 offset:54272
	ds_read_b128 v[236:239], v172 offset:55296
	ds_read_b128 v[240:243], v172 offset:56320
	global_load_lds_dwordx4 v[148:149], off
	v_lshl_add_u64 v[148:149], v[244:245], 0, s[88:89]
	s_add_i32 m0, s8, 0x2000
	s_add_i32 s8, s43, s4
	global_load_lds_dwordx4 v[148:149], off
	v_lshl_add_u64 v[148:149], v[246:247], 0, s[88:89]
	s_mov_b32 m0, s8
	s_nop 0
	global_load_lds_dwordx4 v[148:149], off
	v_lshl_add_u64 v[148:149], v[248:249], 0, s[88:89]
	s_add_i32 m0, s8, 0x2000
	s_nop 0
	global_load_lds_dwordx4 v[148:149], off
	v_lshl_add_u64 v[148:149], v[250:251], 0, s[88:89]
	s_mov_b32 m0, s75
	s_nop 0
	global_load_lds_dwordx4 v[148:149], off
	v_lshl_add_u64 v[148:149], v[252:253], 0, s[88:89]
	s_mov_b32 m0, s78
	s_nop 0
	global_load_lds_dwordx4 v[148:149], off
	s_waitcnt vmcnt(8)
	s_waitcnt lgkmcnt(0)
	s_barrier
	s_setprio 1
	s_waitcnt lgkmcnt(0)
	v_mfma_f32_16x16x32_bf16 v[62:65], v[174:177], v[212:215], v[62:65]
	v_mfma_f32_16x16x32_bf16 v[58:61], v[182:185], v[212:215], v[58:61]
	v_mfma_f32_16x16x32_bf16 v[46:49], v[174:177], v[220:223], v[46:49]
	v_mfma_f32_16x16x32_bf16 v[42:45], v[182:185], v[220:223], v[42:45]
	v_mfma_f32_16x16x32_bf16 v[30:33], v[174:177], v[228:231], v[30:33]
	v_mfma_f32_16x16x32_bf16 v[26:29], v[182:185], v[228:231], v[26:29]
	v_mfma_f32_16x16x32_bf16 v[14:17], v[174:177], v[236:239], v[14:17]
	v_mfma_f32_16x16x32_bf16 v[10:13], v[182:185], v[236:239], v[10:13]
	v_mfma_f32_16x16x32_bf16 v[62:65], v[178:181], v[216:219], v[62:65]
	v_mfma_f32_16x16x32_bf16 v[58:61], v[192:195], v[216:219], v[58:61]
	v_mfma_f32_16x16x32_bf16 v[46:49], v[178:181], v[224:227], v[46:49]
	v_mfma_f32_16x16x32_bf16 v[42:45], v[192:195], v[224:227], v[42:45]
	v_mfma_f32_16x16x32_bf16 v[30:33], v[178:181], v[232:235], v[30:33]
	v_mfma_f32_16x16x32_bf16 v[26:29], v[192:195], v[232:235], v[26:29]
	v_mfma_f32_16x16x32_bf16 v[14:17], v[178:181], v[240:243], v[14:17]
	v_mfma_f32_16x16x32_bf16 v[10:13], v[192:195], v[240:243], v[10:13]
	s_setprio 0
	s_setprio 1
	v_mfma_f32_16x16x32_bf16 v[54:57], v[196:199], v[212:215], v[54:57]
	v_mfma_f32_16x16x32_bf16 v[50:53], v[204:207], v[212:215], v[50:53]
	v_mfma_f32_16x16x32_bf16 v[38:41], v[196:199], v[220:223], v[38:41]
	v_mfma_f32_16x16x32_bf16 v[34:37], v[204:207], v[220:223], v[34:37]
	v_mfma_f32_16x16x32_bf16 v[22:25], v[196:199], v[228:231], v[22:25]
	v_mfma_f32_16x16x32_bf16 v[18:21], v[204:207], v[228:231], v[18:21]
	v_mfma_f32_16x16x32_bf16 v[6:9], v[196:199], v[236:239], v[6:9]
	v_mfma_f32_16x16x32_bf16 v[2:5], v[204:207], v[236:239], v[2:5]
	v_mfma_f32_16x16x32_bf16 v[54:57], v[200:203], v[216:219], v[54:57]
	v_mfma_f32_16x16x32_bf16 v[50:53], v[208:211], v[216:219], v[50:53]
	v_mfma_f32_16x16x32_bf16 v[38:41], v[200:203], v[224:227], v[38:41]
	v_mfma_f32_16x16x32_bf16 v[34:37], v[208:211], v[224:227], v[34:37]
	v_mfma_f32_16x16x32_bf16 v[22:25], v[200:203], v[232:235], v[22:25]
	v_mfma_f32_16x16x32_bf16 v[18:21], v[208:211], v[232:235], v[18:21]
	v_mfma_f32_16x16x32_bf16 v[6:9], v[200:203], v[240:243], v[6:9]
	v_mfma_f32_16x16x32_bf16 v[2:5], v[208:211], v[240:243], v[2:5]
	s_setprio 0
	s_barrier
	s_add_u32 s0, s0, 0x100
	s_addc_u32 s1, s1, 0
	s_add_u32 s10, s10, 0x100
	s_addc_u32 s11, s11, 0
	s_cmp_ge_i32 s36, s79
	s_mov_b32 s8, s36
	s_cbranch_scc0 .LBB0_659
	s_movk_i32 s92, 0x2c00

; #define PG8_STAGE(bufoff, gbase, voff) do { _Pragma("unroll") for (int _i = 0; _i < 2; ++_i) \
;         __builtin_amdgcn_global_load_lds((const unsigned*)((const char*)(gbase) + (voff)[_i]), (PG8_LAS unsigned*)(lds + (bufoff) + ldsw + _i * 8192), 16, 0, 0); } while (0)
; #define PG8_LDA(dst, b, h) do { _Pragma("unroll") for (int m = 0; m < 4; ++m) _Pragma("unroll") for (int k = 0; k < 2; ++k) dst[m][k] = *(const PG8_LAS bf16x8*)(lds + PG8_SA(b, h) + aoff + m * 2048 + k * 1024); } while (0)
; #define PG8_LDB(dst, b, h) do { _Pragma("unroll") for (int n = 0; n < 2; ++n) _Pragma("unroll") for (int k = 0; k < 2; ++k) dst[n][k] = *(const PG8_LAS bf16x8*)(lds + PG8_SB(b, h) + boff + n * 2048 + k * 1024); } while (0)
; #define PG8_MMA(ai, bj, At, Bt) do { __builtin_amdgcn_s_setprio(1); _Pragma("unroll") for (int m = 0; m < 4; ++m) _Pragma("unroll") for (int n = 0; n < 2; ++n) _Pragma("unroll") for (int k = 0; k < 2; ++k) \
;         acc[ai][bj][m][n] = __builtin_amdgcn_mfma_f32_16x16x32_bf16(Bt[n][k], At[m][k], acc[ai][bj][m][n], 0, 0, 0); __builtin_amdgcn_s_setprio(0); } while (0)
; #define PG8_WAIT_V(n) asm volatile("s_waitcnt vmcnt(" #n ")" ::: "memory")
; #define PG8_WAIT_L(n) asm volatile("s_waitcnt lgkmcnt(" #n ")" ::: "memory")
; #define PG8_BAR __builtin_amdgcn_s_barrier()
; #define PG8_SCHED __builtin_amdgcn_sched_barrier(0)
; template <class Epi, class Sched, bool ALIGN_EPI = false, bool SP2 = false>
; __device__ __forceinline__ void gemm_phase(PG8_LAS unsigned char* lds, const Gemm g, const Sched& S, const Epi& E) {
;     ...
;             const bool last = (t == nt - 2);
;             const char* a1 = cA + (size_t)(t + 1) * kstep;
;             const char* a2 = last ? nA : cA + (size_t)(t + 2) * kstep; const char* b2 = last ? nB : cB + (size_t)(t + 2) * kstep;
;             const char* a3 = a2 + kstep; const char* b3 = b2 + kstep;
;             if (last && has_next) S.a_ready(nxt);
;             if constexpr (SP2) {
;             PG8_LDB(B0, 0, 0); PG8_LDB(B1, 0, 1); PG8_SCHED; PG8_LDA(At, 0, 0); PG8_STAGE(PG8_SA(1, 1), a1 + hstep, voffA);
;             PG8_WAIT_V(8); PG8_WAIT_L(0); PG8_BAR; PG8_MMA(0, 0, At, B0); PG8_MMA(0, 1, At, B1); PG8_BAR; PG8_SCHED;
;             PG8_LDA(At, 0, 1); PG8_STAGE(PG8_SB(0, 0), b2, voffB); PG8_STAGE(PG8_SB(0, 1), b2 + hstep, voffB); PG8_STAGE(PG8_SA(0, 0), a2, voffA);
.LBB0_865:
	s_add_i32 s11, s8, 2
	s_add_u32 s14, s0, 0x80
	s_addc_u32 s9, s1, 0
	s_add_i32 s56, 0, 0x10000
	s_cmp_eq_u32 s94, s8
	s_cselect_b32 s9, s35, s9
	s_cselect_b32 s8, s34, s14
	v_add_u32_e32 v146, s56, v150
	s_cselect_b32 s15, s37, s10
	s_cselect_b32 s14, s36, s5
	s_add_i32 s78, 0, 0x14000
	ds_read_b128 v[142:145], v146
	ds_read_b128 v[176:179], v146 offset:1024
	ds_read_b128 v[180:183], v146 offset:2048
	ds_read_b128 v[192:195], v146 offset:3072
	v_add_u32_e32 v146, s78, v150
	ds_read_b128 v[196:199], v146
	ds_read_b128 v[200:203], v146 offset:1024
	ds_read_b128 v[204:207], v146 offset:2048
	ds_read_b128 v[208:211], v146 offset:3072
	v_lshl_add_u64 v[146:147], s[0:1], 0, v[138:139]
	s_add_i32 m0, s80, 0xc000
	ds_read_b128 v[212:215], v175
	ds_read_b128 v[216:219], v175 offset:1024
	ds_read_b128 v[220:223], v175 offset:2048
	ds_read_b128 v[224:227], v175 offset:3072
	ds_read_b128 v[228:231], v175 offset:4096
	ds_read_b128 v[232:235], v175 offset:5120
	ds_read_b128 v[236:239], v175 offset:6144
	ds_read_b128 v[240:243], v175 offset:7168
	global_load_lds_dwordx4 v[146:147], off
	v_lshl_add_u64 v[146:147], s[0:1], 0, v[140:141]
	s_add_i32 m0, s80, 0xe000
	s_nop 0
	global_load_lds_dwordx4 v[146:147], off
	s_waitcnt vmcnt(8)
	s_waitcnt lgkmcnt(0)
	s_barrier
	s_setprio 1
	s_waitcnt lgkmcnt(0)
	v_mfma_f32_16x16x32_bf16 v[126:129], v[142:145], v[212:215], v[126:129]
	v_mfma_f32_16x16x32_bf16 v[122:125], v[180:183], v[212:215], v[122:125]
	v_mfma_f32_16x16x32_bf16 v[110:113], v[142:145], v[220:223], v[110:113]
	v_mfma_f32_16x16x32_bf16 v[106:109], v[180:183], v[220:223], v[106:109]
	v_mfma_f32_16x16x32_bf16 v[94:97], v[142:145], v[228:231], v[94:97]
	v_mfma_f32_16x16x32_bf16 v[90:93], v[180:183], v[228:231], v[90:93]
	v_mfma_f32_16x16x32_bf16 v[78:81], v[142:145], v[236:239], v[78:81]
	v_mfma_f32_16x16x32_bf16 v[74:77], v[180:183], v[236:239], v[74:77]
	v_mfma_f32_16x16x32_bf16 v[126:129], v[176:179], v[216:219], v[126:129]
	v_mfma_f32_16x16x32_bf16 v[122:125], v[192:195], v[216:219], v[122:125]
	v_mfma_f32_16x16x32_bf16 v[110:113], v[176:179], v[224:227], v[110:113]
	v_mfma_f32_16x16x32_bf16 v[106:109], v[192:195], v[224:227], v[106:109]
	v_mfma_f32_16x16x32_bf16 v[94:97], v[176:179], v[232:235], v[94:97]
	v_mfma_f32_16x16x32_bf16 v[90:93], v[192:195], v[232:235], v[90:93]
	v_mfma_f32_16x16x32_bf16 v[78:81], v[176:179], v[240:243], v[78:81]
	v_mfma_f32_16x16x32_bf16 v[74:77], v[192:195], v[240:243], v[74:77]
	s_setprio 0
	s_setprio 1
	v_mfma_f32_16x16x32_bf16 v[118:121], v[196:199], v[212:215], v[118:121]
	v_mfma_f32_16x16x32_bf16 v[114:117], v[204:207], v[212:215], v[114:117]
	v_mfma_f32_16x16x32_bf16 v[102:105], v[196:199], v[220:223], v[102:105]
	v_mfma_f32_16x16x32_bf16 v[98:101], v[204:207], v[220:223], v[98:101]
	v_mfma_f32_16x16x32_bf16 v[86:89], v[196:199], v[228:231], v[86:89]
	v_mfma_f32_16x16x32_bf16 v[82:85], v[204:207], v[228:231], v[82:85]
	v_mfma_f32_16x16x32_bf16 v[70:73], v[196:199], v[236:239], v[70:73]
	v_mfma_f32_16x16x32_bf16 v[66:69], v[204:207], v[236:239], v[66:69]
	v_mfma_f32_16x16x32_bf16 v[118:121], v[200:203], v[216:219], v[118:121]
	v_mfma_f32_16x16x32_bf16 v[114:117], v[208:211], v[216:219], v[114:117]
	v_mfma_f32_16x16x32_bf16 v[102:105], v[200:203], v[224:227], v[102:105]
	v_mfma_f32_16x16x32_bf16 v[98:101], v[208:211], v[224:227], v[98:101]
	v_mfma_f32_16x16x32_bf16 v[86:89], v[200:203], v[232:235], v[86:89]
	v_mfma_f32_16x16x32_bf16 v[82:85], v[208:211], v[232:235], v[82:85]
	v_mfma_f32_16x16x32_bf16 v[70:73], v[200:203], v[240:243], v[70:73]
	v_mfma_f32_16x16x32_bf16 v[66:69], v[208:211], v[240:243], v[66:69]
	s_setprio 0
	s_barrier
	s_add_i32 s56, s56, s59
	v_lshl_add_u64 v[146:147], s[14:15], 0, v[160:161]
	s_mov_b32 m0, s56
	ds_read_b128 v[212:215], v175 offset:16384
	ds_read_b128 v[216:219], v175 offset:17408
	ds_read_b128 v[220:223], v175 offset:18432
	ds_read_b128 v[224:227], v175 offset:19456
	ds_read_b128 v[228:231], v175 offset:20480
	ds_read_b128 v[232:235], v175 offset:21504
	ds_read_b128 v[236:239], v175 offset:22528
	ds_read_b128 v[240:243], v175 offset:23552
	global_load_lds_dwordx4 v[146:147], off
	s_add_i32 m0, s56, 0x2000
	v_lshl_add_u64 v[166:167], s[14:15], 0, v[134:135]
	s_add_u32 s14, s14, s20
	s_addc_u32 s15, s15, s21
	s_add_i32 s56, s78, s59
	global_load_lds_dwordx4 v[166:167], off
	v_lshl_add_u64 v[184:185], s[14:15], 0, v[160:161]
	s_mov_b32 m0, s56
	v_lshl_add_u64 v[244:245], s[14:15], 0, v[134:135]
	global_load_lds_dwordx4 v[184:185], off
	s_add_i32 m0, s56, 0x2000
	v_lshl_add_u64 v[246:247], s[8:9], 0, v[130:131]
	global_load_lds_dwordx4 v[244:245], off
	v_lshl_add_u64 v[248:249], s[8:9], 0, v[132:133]
	s_nop 0
	s_waitcnt vmcnt(6)
	s_waitcnt lgkmcnt(0)
	s_barrier
; #define PG8_STAGE(bufoff, gbase, voff) do { _Pragma("unroll") for (int _i = 0; _i < 2; ++_i) \
;         __builtin_amdgcn_global_load_lds((const unsigned*)((const char*)(gbase) + (voff)[_i]), (PG8_LAS unsigned*)(lds + (bufoff) + ldsw + _i * 8192), 16, 0, 0); } while (0)
; #define PG8_LDA(dst, b, h) do { _Pragma("unroll") for (int m = 0; m < 4; ++m) _Pragma("unroll") for (int k = 0; k < 2; ++k) dst[m][k] = *(const PG8_LAS bf16x8*)(lds + PG8_SA(b, h) + aoff + m * 2048 + k * 1024); } while (0)
; #define PG8_LDB(dst, b, h) do { _Pragma("unroll") for (int n = 0; n < 2; ++n) _Pragma("unroll") for (int k = 0; k < 2; ++k) dst[n][k] = *(const PG8_LAS bf16x8*)(lds + PG8_SB(b, h) + boff + n * 2048 + k * 1024); } while (0)
; #define PG8_MMA(ai, bj, At, Bt) do { __builtin_amdgcn_s_setprio(1); _Pragma("unroll") for (int m = 0; m < 4; ++m) _Pragma("unroll") for (int n = 0; n < 2; ++n) _Pragma("unroll") for (int k = 0; k < 2; ++k) \
;         acc[ai][bj][m][n] = __builtin_amdgcn_mfma_f32_16x16x32_bf16(Bt[n][k], At[m][k], acc[ai][bj][m][n], 0, 0, 0); __builtin_amdgcn_s_setprio(0); } while (0)
; #define PG8_WAIT_V(n) asm volatile("s_waitcnt vmcnt(" #n ")" ::: "memory")
; #define PG8_WAIT_L(n) asm volatile("s_waitcnt lgkmcnt(" #n ")" ::: "memory")
; #define PG8_BAR __builtin_amdgcn_s_barrier()
; #define PG8_SCHED __builtin_amdgcn_sched_barrier(0)
; template <class Epi, class Sched, bool ALIGN_EPI = false, bool SP2 = false>
; __device__ __forceinline__ void gemm_phase(PG8_LAS unsigned char* lds, const Gemm g, const Sched& S, const Epi& E) {
;     ...
;             PG8_WAIT_V(8); PG8_WAIT_L(0); PG8_BAR; PG8_MMA(1, 0, At, B0); PG8_MMA(1, 1, At, B1); PG8_BAR; PG8_SCHED;
;             PG8_LDB(B0, 1, 0); PG8_LDB(B1, 1, 1); PG8_SCHED; PG8_LDA(At, 1, 0); PG8_STAGE(PG8_SA(0, 1), a2 + hstep, voffA);
;             PG8_WAIT_V(8); PG8_WAIT_L(0); PG8_BAR; PG8_MMA(0, 0, At, B0); PG8_MMA(0, 1, At, B1); PG8_BAR; PG8_SCHED;
	s_setprio 1
	s_waitcnt lgkmcnt(0)
	v_mfma_f32_16x16x32_bf16 v[62:65], v[142:145], v[212:215], v[62:65]
	v_mfma_f32_16x16x32_bf16 v[58:61], v[180:183], v[212:215], v[58:61]
	v_mfma_f32_16x16x32_bf16 v[46:49], v[142:145], v[220:223], v[46:49]
	v_mfma_f32_16x16x32_bf16 v[42:45], v[180:183], v[220:223], v[42:45]
	v_mfma_f32_16x16x32_bf16 v[30:33], v[142:145], v[228:231], v[30:33]
	v_mfma_f32_16x16x32_bf16 v[26:29], v[180:183], v[228:231], v[26:29]
	v_mfma_f32_16x16x32_bf16 v[14:17], v[142:145], v[236:239], v[14:17]
	v_mfma_f32_16x16x32_bf16 v[10:13], v[180:183], v[236:239], v[10:13]
	v_mfma_f32_16x16x32_bf16 v[62:65], v[176:179], v[216:219], v[62:65]
	v_mfma_f32_16x16x32_bf16 v[58:61], v[192:195], v[216:219], v[58:61]
	v_mfma_f32_16x16x32_bf16 v[46:49], v[176:179], v[224:227], v[46:49]
	v_mfma_f32_16x16x32_bf16 v[42:45], v[192:195], v[224:227], v[42:45]
	v_mfma_f32_16x16x32_bf16 v[30:33], v[176:179], v[232:235], v[30:33]
	v_mfma_f32_16x16x32_bf16 v[26:29], v[192:195], v[232:235], v[26:29]
	v_mfma_f32_16x16x32_bf16 v[14:17], v[176:179], v[240:243], v[14:17]
	v_mfma_f32_16x16x32_bf16 v[10:13], v[192:195], v[240:243], v[10:13]
	s_setprio 0
	s_setprio 1
	v_mfma_f32_16x16x32_bf16 v[54:57], v[196:199], v[212:215], v[54:57]
	v_mfma_f32_16x16x32_bf16 v[50:53], v[204:207], v[212:215], v[50:53]
	v_mfma_f32_16x16x32_bf16 v[38:41], v[196:199], v[220:223], v[38:41]
	v_mfma_f32_16x16x32_bf16 v[34:37], v[204:207], v[220:223], v[34:37]
	v_mfma_f32_16x16x32_bf16 v[22:25], v[196:199], v[228:231], v[22:25]
	v_mfma_f32_16x16x32_bf16 v[18:21], v[204:207], v[228:231], v[18:21]
	v_mfma_f32_16x16x32_bf16 v[6:9], v[196:199], v[236:239], v[6:9]
	v_mfma_f32_16x16x32_bf16 v[2:5], v[204:207], v[236:239], v[2:5]
	v_mfma_f32_16x16x32_bf16 v[54:57], v[200:203], v[216:219], v[54:57]
	v_mfma_f32_16x16x32_bf16 v[50:53], v[208:211], v[216:219], v[50:53]
	v_mfma_f32_16x16x32_bf16 v[38:41], v[200:203], v[224:227], v[38:41]
	v_mfma_f32_16x16x32_bf16 v[34:37], v[208:211], v[224:227], v[34:37]
	v_mfma_f32_16x16x32_bf16 v[22:25], v[200:203], v[232:235], v[22:25]
	v_mfma_f32_16x16x32_bf16 v[18:21], v[208:211], v[232:235], v[18:21]
	v_mfma_f32_16x16x32_bf16 v[6:9], v[200:203], v[240:243], v[6:9]
	v_mfma_f32_16x16x32_bf16 v[2:5], v[208:211], v[240:243], v[2:5]
	s_setprio 0
	s_barrier
	s_add_i32 s14, 0, 0x18000
	v_add_u32_e32 v148, s14, v150
	s_add_i32 s15, 0, 0x1c000
	ds_read_b128 v[142:145], v148
	ds_read_b128 v[176:179], v148 offset:1024
	ds_read_b128 v[180:183], v148 offset:2048
	ds_read_b128 v[192:195], v148 offset:3072
	v_add_u32_e32 v148, s15, v150
	ds_read_b128 v[196:199], v148
	ds_read_b128 v[200:203], v148 offset:1024
	ds_read_b128 v[204:207], v148 offset:2048
	ds_read_b128 v[208:211], v148 offset:3072
	s_add_u32 s8, s8, s20
	s_addc_u32 s9, s9, s21
	s_mov_b32 m0, s80
	s_nop 0
	global_load_lds_dwordx4 v[246:247], off
	s_mov_b32 m0, s81
	s_nop 0
	global_load_lds_dwordx4 v[248:249], off
	s_mov_b32 m0, s82
	v_lshl_add_u64 v[250:251], s[8:9], 0, v[130:131]
	ds_read_b128 v[212:215], v175 offset:32768
	ds_read_b128 v[216:219], v175 offset:33792
	ds_read_b128 v[220:223], v175 offset:34816
	ds_read_b128 v[224:227], v175 offset:35840
	ds_read_b128 v[228:231], v175 offset:36864
	ds_read_b128 v[232:235], v175 offset:37888
	ds_read_b128 v[236:239], v175 offset:38912
	ds_read_b128 v[240:243], v175 offset:39936
	global_load_lds_dwordx4 v[250:251], off
	v_lshl_add_u64 v[250:251], s[8:9], 0, v[132:133]
	s_mov_b32 m0, s83
	s_nop 0
	global_load_lds_dwordx4 v[250:251], off
	s_waitcnt vmcnt(8)
	s_waitcnt lgkmcnt(0)
	s_barrier
	s_setprio 1
	s_waitcnt lgkmcnt(0)
	v_mfma_f32_16x16x32_bf16 v[126:129], v[142:145], v[212:215], v[126:129]
	v_mfma_f32_16x16x32_bf16 v[122:125], v[180:183], v[212:215], v[122:125]
	v_mfma_f32_16x16x32_bf16 v[110:113], v[142:145], v[220:223], v[110:113]
	v_mfma_f32_16x16x32_bf16 v[106:109], v[180:183], v[220:223], v[106:109]
	v_mfma_f32_16x16x32_bf16 v[94:97], v[142:145], v[228:231], v[94:97]
	v_mfma_f32_16x16x32_bf16 v[90:93], v[180:183], v[228:231], v[90:93]
	v_mfma_f32_16x16x32_bf16 v[78:81], v[142:145], v[236:239], v[78:81]
	v_mfma_f32_16x16x32_bf16 v[74:77], v[180:183], v[236:239], v[74:77]
	v_mfma_f32_16x16x32_bf16 v[126:129], v[176:179], v[216:219], v[126:129]
	v_mfma_f32_16x16x32_bf16 v[122:125], v[192:195], v[216:219], v[122:125]
	v_mfma_f32_16x16x32_bf16 v[110:113], v[176:179], v[224:227], v[110:113]
	v_mfma_f32_16x16x32_bf16 v[106:109], v[192:195], v[224:227], v[106:109]
	v_mfma_f32_16x16x32_bf16 v[94:97], v[176:179], v[232:235], v[94:97]
	v_mfma_f32_16x16x32_bf16 v[90:93], v[192:195], v[232:235], v[90:93]
	v_mfma_f32_16x16x32_bf16 v[78:81], v[176:179], v[240:243], v[78:81]
	v_mfma_f32_16x16x32_bf16 v[74:77], v[192:195], v[240:243], v[74:77]
	s_setprio 0
	s_setprio 1
	v_mfma_f32_16x16x32_bf16 v[118:121], v[196:199], v[212:215], v[118:121]
	v_mfma_f32_16x16x32_bf16 v[114:117], v[204:207], v[212:215], v[114:117]
	v_mfma_f32_16x16x32_bf16 v[102:105], v[196:199], v[220:223], v[102:105]
	v_mfma_f32_16x16x32_bf16 v[98:101], v[204:207], v[220:223], v[98:101]
	v_mfma_f32_16x16x32_bf16 v[86:89], v[196:199], v[228:231], v[86:89]
	v_mfma_f32_16x16x32_bf16 v[82:85], v[204:207], v[228:231], v[82:85]
	v_mfma_f32_16x16x32_bf16 v[70:73], v[196:199], v[236:239], v[70:73]
	v_mfma_f32_16x16x32_bf16 v[66:69], v[204:207], v[236:239], v[66:69]
	v_mfma_f32_16x16x32_bf16 v[118:121], v[200:203], v[216:219], v[118:121]
	v_mfma_f32_16x16x32_bf16 v[114:117], v[208:211], v[216:219], v[114:117]
	v_mfma_f32_16x16x32_bf16 v[102:105], v[200:203], v[224:227], v[102:105]
	v_mfma_f32_16x16x32_bf16 v[98:101], v[208:211], v[224:227], v[98:101]
	v_mfma_f32_16x16x32_bf16 v[86:89], v[200:203], v[232:235], v[86:89]
	v_mfma_f32_16x16x32_bf16 v[82:85], v[208:211], v[232:235], v[82:85]
	v_mfma_f32_16x16x32_bf16 v[70:73], v[200:203], v[240:243], v[70:73]
	v_mfma_f32_16x16x32_bf16 v[66:69], v[208:211], v[240:243], v[66:69]
	s_setprio 0
	s_barrier
; #define PG8_STAGE(bufoff, gbase, voff) do { _Pragma("unroll") for (int _i = 0; _i < 2; ++_i) \
;         __builtin_amdgcn_global_load_lds((const unsigned*)((const char*)(gbase) + (voff)[_i]), (PG8_LAS unsigned*)(lds + (bufoff) + ldsw + _i * 8192), 16, 0, 0); } while (0)
; #define PG8_LDA(dst, b, h) do { _Pragma("unroll") for (int m = 0; m < 4; ++m) _Pragma("unroll") for (int k = 0; k < 2; ++k) dst[m][k] = *(const PG8_LAS bf16x8*)(lds + PG8_SA(b, h) + aoff + m * 2048 + k * 1024); } while (0)
; #define PG8_MMA(ai, bj, At, Bt) do { __builtin_amdgcn_s_setprio(1); _Pragma("unroll") for (int m = 0; m < 4; ++m) _Pragma("unroll") for (int n = 0; n < 2; ++n) _Pragma("unroll") for (int k = 0; k < 2; ++k) \
;         acc[ai][bj][m][n] = __builtin_amdgcn_mfma_f32_16x16x32_bf16(Bt[n][k], At[m][k], acc[ai][bj][m][n], 0, 0, 0); __builtin_amdgcn_s_setprio(0); } while (0)
; #define PG8_WAIT_V(n) asm volatile("s_waitcnt vmcnt(" #n ")" ::: "memory")
; #define PG8_WAIT_L(n) asm volatile("s_waitcnt lgkmcnt(" #n ")" ::: "memory")
; #define PG8_BAR __builtin_amdgcn_s_barrier()
; #define PG8_SCHED __builtin_amdgcn_sched_barrier(0)
; template <class Epi, class Sched, bool ALIGN_EPI = false, bool SP2 = false>
; __device__ __forceinline__ void gemm_phase(PG8_LAS unsigned char* lds, const Gemm g, const Sched& S, const Epi& E) {
;     ...
;         for (int t = 0; t < nt; t += 2) {
;     ...
;             PG8_LDA(At, 1, 1); PG8_STAGE(PG8_SB(1, 0), b3, voffB); PG8_STAGE(PG8_SB(1, 1), b3 + hstep, voffB); PG8_STAGE(PG8_SA(1, 0), a3, voffA);
;             PG8_WAIT_V(8); PG8_WAIT_L(0); PG8_BAR; PG8_MMA(1, 0, At, B0); PG8_MMA(1, 1, At, B1); PG8_BAR; PG8_SCHED;
	s_add_i32 s8, s14, s59
	v_lshl_add_u64 v[146:147], v[146:147], 0, s[88:89]
	s_mov_b32 m0, s8
	ds_read_b128 v[212:215], v175 offset:49152
	ds_read_b128 v[216:219], v175 offset:50176
	ds_read_b128 v[220:223], v175 offset:51200
	ds_read_b128 v[224:227], v175 offset:52224
	ds_read_b128 v[228:231], v175 offset:53248
	ds_read_b128 v[232:235], v175 offset:54272
	ds_read_b128 v[236:239], v175 offset:55296
	ds_read_b128 v[240:243], v175 offset:56320
	global_load_lds_dwordx4 v[146:147], off
	v_lshl_add_u64 v[146:147], v[166:167], 0, s[88:89]
	s_add_i32 m0, s8, 0x2000
	s_add_i32 s8, s15, s59
	global_load_lds_dwordx4 v[146:147], off
	v_lshl_add_u64 v[146:147], v[184:185], 0, s[88:89]
	s_mov_b32 m0, s8
	s_nop 0
	global_load_lds_dwordx4 v[146:147], off
	v_lshl_add_u64 v[146:147], v[244:245], 0, s[88:89]
	s_add_i32 m0, s8, 0x2000
	s_nop 0
	global_load_lds_dwordx4 v[146:147], off
	v_lshl_add_u64 v[146:147], v[246:247], 0, s[88:89]
	s_mov_b32 m0, s86
	s_nop 0
	global_load_lds_dwordx4 v[146:147], off
	v_lshl_add_u64 v[146:147], v[248:249], 0, s[88:89]
	s_mov_b32 m0, s87
	s_nop 0
	global_load_lds_dwordx4 v[146:147], off
	s_waitcnt vmcnt(8)
	s_waitcnt lgkmcnt(0)
	s_barrier
	s_setprio 1
	s_waitcnt lgkmcnt(0)
	v_mfma_f32_16x16x32_bf16 v[62:65], v[142:145], v[212:215], v[62:65]
	v_mfma_f32_16x16x32_bf16 v[58:61], v[180:183], v[212:215], v[58:61]
	v_mfma_f32_16x16x32_bf16 v[46:49], v[142:145], v[220:223], v[46:49]
	v_mfma_f32_16x16x32_bf16 v[42:45], v[180:183], v[220:223], v[42:45]
	v_mfma_f32_16x16x32_bf16 v[30:33], v[142:145], v[228:231], v[30:33]
	v_mfma_f32_16x16x32_bf16 v[26:29], v[180:183], v[228:231], v[26:29]
	v_mfma_f32_16x16x32_bf16 v[14:17], v[142:145], v[236:239], v[14:17]
	v_mfma_f32_16x16x32_bf16 v[10:13], v[180:183], v[236:239], v[10:13]
	v_mfma_f32_16x16x32_bf16 v[62:65], v[176:179], v[216:219], v[62:65]
	v_mfma_f32_16x16x32_bf16 v[58:61], v[192:195], v[216:219], v[58:61]
	v_mfma_f32_16x16x32_bf16 v[46:49], v[176:179], v[224:227], v[46:49]
	v_mfma_f32_16x16x32_bf16 v[42:45], v[192:195], v[224:227], v[42:45]
	v_mfma_f32_16x16x32_bf16 v[30:33], v[176:179], v[232:235], v[30:33]
	v_mfma_f32_16x16x32_bf16 v[26:29], v[192:195], v[232:235], v[26:29]
	v_mfma_f32_16x16x32_bf16 v[14:17], v[176:179], v[240:243], v[14:17]
	v_mfma_f32_16x16x32_bf16 v[10:13], v[192:195], v[240:243], v[10:13]
	s_setprio 0
	s_setprio 1
	v_mfma_f32_16x16x32_bf16 v[54:57], v[196:199], v[212:215], v[54:57]
	v_mfma_f32_16x16x32_bf16 v[50:53], v[204:207], v[212:215], v[50:53]
	v_mfma_f32_16x16x32_bf16 v[38:41], v[196:199], v[220:223], v[38:41]
	v_mfma_f32_16x16x32_bf16 v[34:37], v[204:207], v[220:223], v[34:37]
	v_mfma_f32_16x16x32_bf16 v[22:25], v[196:199], v[228:231], v[22:25]
	v_mfma_f32_16x16x32_bf16 v[18:21], v[204:207], v[228:231], v[18:21]
	v_mfma_f32_16x16x32_bf16 v[6:9], v[196:199], v[236:239], v[6:9]
	v_mfma_f32_16x16x32_bf16 v[2:5], v[204:207], v[236:239], v[2:5]
	v_mfma_f32_16x16x32_bf16 v[54:57], v[200:203], v[216:219], v[54:57]
	v_mfma_f32_16x16x32_bf16 v[50:53], v[208:211], v[216:219], v[50:53]
	v_mfma_f32_16x16x32_bf16 v[38:41], v[200:203], v[224:227], v[38:41]
	v_mfma_f32_16x16x32_bf16 v[34:37], v[208:211], v[224:227], v[34:37]
	v_mfma_f32_16x16x32_bf16 v[22:25], v[200:203], v[232:235], v[22:25]
	v_mfma_f32_16x16x32_bf16 v[18:21], v[208:211], v[232:235], v[18:21]
	v_mfma_f32_16x16x32_bf16 v[6:9], v[200:203], v[240:243], v[6:9]
	v_mfma_f32_16x16x32_bf16 v[2:5], v[208:211], v[240:243], v[2:5]
	s_setprio 0
	s_barrier
	s_add_u32 s0, s0, 0x100
	s_addc_u32 s1, s1, 0
	s_add_u32 s5, s5, 0x100
	s_addc_u32 s10, s10, 0
	s_cmp_ge_i32 s11, s85
	s_mov_b32 s8, s11
	s_cbranch_scc0 .LBB0_865

; #define PG8_STAGE(bufoff, gbase, voff) do { _Pragma("unroll") for (int _i = 0; _i < 2; ++_i) \
;         __builtin_amdgcn_global_load_lds((const unsigned*)((const char*)(gbase) + (voff)[_i]), (PG8_LAS unsigned*)(lds + (bufoff) + ldsw + _i * 8192), 16, 0, 0); } while (0)
; #define PG8_LDA(dst, b, h) do { _Pragma("unroll") for (int m = 0; m < 4; ++m) _Pragma("unroll") for (int k = 0; k < 2; ++k) dst[m][k] = *(const PG8_LAS bf16x8*)(lds + PG8_SA(b, h) + aoff + m * 2048 + k * 1024); } while (0)
; #define PG8_LDB(dst, b, h) do { _Pragma("unroll") for (int n = 0; n < 2; ++n) _Pragma("unroll") for (int k = 0; k < 2; ++k) dst[n][k] = *(const PG8_LAS bf16x8*)(lds + PG8_SB(b, h) + boff + n * 2048 + k * 1024); } while (0)
; #define PG8_MMA(ai, bj, At, Bt) do { __builtin_amdgcn_s_setprio(1); _Pragma("unroll") for (int m = 0; m < 4; ++m) _Pragma("unroll") for (int n = 0; n < 2; ++n) _Pragma("unroll") for (int k = 0; k < 2; ++k) \
;         acc[ai][bj][m][n] = __builtin_amdgcn_mfma_f32_16x16x32_bf16(Bt[n][k], At[m][k], acc[ai][bj][m][n], 0, 0, 0); __builtin_amdgcn_s_setprio(0); } while (0)
; #define PG8_WAIT_V(n) asm volatile("s_waitcnt vmcnt(" #n ")" ::: "memory")
; #define PG8_WAIT_L(n) asm volatile("s_waitcnt lgkmcnt(" #n ")" ::: "memory")
; #define PG8_BAR __builtin_amdgcn_s_barrier()
; #define PG8_SCHED __builtin_amdgcn_sched_barrier(0)
; template <class Epi, class Sched, bool ALIGN_EPI = false, bool SP2 = false>
; __device__ __forceinline__ void gemm_phase(PG8_LAS unsigned char* lds, const Gemm g, const Sched& S, const Epi& E) {
;     ...
;             const bool last = (t == nt - 2);
;             const char* a1 = cA + (size_t)(t + 1) * kstep;
;             const char* a2 = last ? nA : cA + (size_t)(t + 2) * kstep; const char* b2 = last ? nB : cB + (size_t)(t + 2) * kstep;
;             const char* a3 = a2 + kstep; const char* b3 = b2 + kstep;
;             if (last && has_next) S.a_ready(nxt);
;             if constexpr (SP2) {
;             PG8_LDB(B0, 0, 0); PG8_LDB(B1, 0, 1); PG8_SCHED; PG8_LDA(At, 0, 0); PG8_STAGE(PG8_SA(1, 1), a1 + hstep, voffA);
;             PG8_WAIT_V(8); PG8_WAIT_L(0); PG8_BAR; PG8_MMA(0, 0, At, B0); PG8_MMA(0, 1, At, B1); PG8_BAR; PG8_SCHED;
;             PG8_LDA(At, 0, 1); PG8_STAGE(PG8_SB(0, 0), b2, voffB); PG8_STAGE(PG8_SB(0, 1), b2 + hstep, voffB); PG8_STAGE(PG8_SA(0, 0), a2, voffA);
.LBB0_1169:
	s_add_i32 s84, s10, 2
	s_add_u32 s85, s0, 0x80
	s_addc_u32 s11, s1, 0
	s_add_i32 s92, 0, 0x10000
	s_cmp_eq_u32 s74, s10
	s_cselect_b32 s11, s31, s11
	s_cselect_b32 s10, s30, s85
	v_add_u32_e32 v146, s92, v148
	s_cselect_b32 s87, s35, s37
	s_cselect_b32 s86, s34, s36
	s_add_i32 s85, 0, 0x14000
	ds_read_b128 v[142:145], v146
	ds_read_b128 v[174:177], v146 offset:1024
	ds_read_b128 v[178:181], v146 offset:2048
	ds_read_b128 v[182:185], v146 offset:3072
	v_add_u32_e32 v146, s85, v148
	ds_read_b128 v[192:195], v146
	ds_read_b128 v[196:199], v146 offset:1024
	ds_read_b128 v[200:203], v146 offset:2048
	ds_read_b128 v[204:207], v146 offset:3072
	v_lshl_add_u64 v[166:167], s[0:1], 0, v[138:139]
	s_add_i32 m0, s49, 0xc000
	ds_read_b128 v[208:211], v173
	ds_read_b128 v[212:215], v173 offset:1024
	ds_read_b128 v[216:219], v173 offset:2048
	ds_read_b128 v[220:223], v173 offset:3072
	ds_read_b128 v[224:227], v173 offset:4096
	ds_read_b128 v[228:231], v173 offset:5120
	ds_read_b128 v[232:235], v173 offset:6144
	ds_read_b128 v[236:239], v173 offset:7168
	global_load_lds_dwordx4 v[166:167], off
	v_lshl_add_u64 v[166:167], s[0:1], 0, v[140:141]
	s_add_i32 m0, s49, 0xe000
	s_nop 0
	global_load_lds_dwordx4 v[166:167], off
	s_waitcnt vmcnt(8)
	s_waitcnt lgkmcnt(0)
	s_barrier
	s_setprio 1
	s_waitcnt lgkmcnt(0)
	v_mfma_f32_16x16x32_bf16 v[126:129], v[142:145], v[208:211], v[126:129]
	v_mfma_f32_16x16x32_bf16 v[122:125], v[178:181], v[208:211], v[122:125]
	v_mfma_f32_16x16x32_bf16 v[110:113], v[142:145], v[216:219], v[110:113]
	v_mfma_f32_16x16x32_bf16 v[106:109], v[178:181], v[216:219], v[106:109]
	v_mfma_f32_16x16x32_bf16 v[94:97], v[142:145], v[224:227], v[94:97]
	v_mfma_f32_16x16x32_bf16 v[90:93], v[178:181], v[224:227], v[90:93]
	v_mfma_f32_16x16x32_bf16 v[78:81], v[142:145], v[232:235], v[78:81]
	v_mfma_f32_16x16x32_bf16 v[74:77], v[178:181], v[232:235], v[74:77]
	v_mfma_f32_16x16x32_bf16 v[126:129], v[174:177], v[212:215], v[126:129]
	v_mfma_f32_16x16x32_bf16 v[122:125], v[182:185], v[212:215], v[122:125]
	v_mfma_f32_16x16x32_bf16 v[110:113], v[174:177], v[220:223], v[110:113]
	v_mfma_f32_16x16x32_bf16 v[106:109], v[182:185], v[220:223], v[106:109]
	v_mfma_f32_16x16x32_bf16 v[94:97], v[174:177], v[228:231], v[94:97]
	v_mfma_f32_16x16x32_bf16 v[90:93], v[182:185], v[228:231], v[90:93]
	v_mfma_f32_16x16x32_bf16 v[78:81], v[174:177], v[236:239], v[78:81]
	v_mfma_f32_16x16x32_bf16 v[74:77], v[182:185], v[236:239], v[74:77]
	s_setprio 0
	s_setprio 1
	v_mfma_f32_16x16x32_bf16 v[118:121], v[192:195], v[208:211], v[118:121]
	v_mfma_f32_16x16x32_bf16 v[114:117], v[200:203], v[208:211], v[114:117]
	v_mfma_f32_16x16x32_bf16 v[102:105], v[192:195], v[216:219], v[102:105]
	v_mfma_f32_16x16x32_bf16 v[98:101], v[200:203], v[216:219], v[98:101]
	v_mfma_f32_16x16x32_bf16 v[86:89], v[192:195], v[224:227], v[86:89]
	v_mfma_f32_16x16x32_bf16 v[82:85], v[200:203], v[224:227], v[82:85]
	v_mfma_f32_16x16x32_bf16 v[70:73], v[192:195], v[232:235], v[70:73]
	v_mfma_f32_16x16x32_bf16 v[66:69], v[200:203], v[232:235], v[66:69]
	v_mfma_f32_16x16x32_bf16 v[118:121], v[196:199], v[212:215], v[118:121]
	v_mfma_f32_16x16x32_bf16 v[114:117], v[204:207], v[212:215], v[114:117]
	v_mfma_f32_16x16x32_bf16 v[102:105], v[196:199], v[220:223], v[102:105]
	v_mfma_f32_16x16x32_bf16 v[98:101], v[204:207], v[220:223], v[98:101]
	v_mfma_f32_16x16x32_bf16 v[86:89], v[196:199], v[228:231], v[86:89]
	v_mfma_f32_16x16x32_bf16 v[82:85], v[204:207], v[228:231], v[82:85]
	v_mfma_f32_16x16x32_bf16 v[70:73], v[196:199], v[236:239], v[70:73]
	v_mfma_f32_16x16x32_bf16 v[66:69], v[204:207], v[236:239], v[66:69]
	s_setprio 0
	s_barrier
	s_add_i32 s92, s92, s4
	v_lshl_add_u64 v[166:167], s[86:87], 0, v[160:161]
	s_mov_b32 m0, s92
	ds_read_b128 v[208:211], v173 offset:16384
	ds_read_b128 v[212:215], v173 offset:17408
	ds_read_b128 v[216:219], v173 offset:18432
	ds_read_b128 v[220:223], v173 offset:19456
	ds_read_b128 v[224:227], v173 offset:20480
	ds_read_b128 v[228:231], v173 offset:21504
	ds_read_b128 v[232:235], v173 offset:22528
	ds_read_b128 v[236:239], v173 offset:23552
	global_load_lds_dwordx4 v[166:167], off
	s_add_i32 m0, s92, 0x2000
	v_lshl_add_u64 v[240:241], s[86:87], 0, v[134:135]
	s_add_u32 s86, s86, s8
	s_addc_u32 s87, s87, s9
	s_add_i32 s85, s85, s4
	global_load_lds_dwordx4 v[240:241], off
	v_lshl_add_u64 v[242:243], s[86:87], 0, v[160:161]
	s_mov_b32 m0, s85
	v_lshl_add_u64 v[244:245], s[86:87], 0, v[134:135]
	global_load_lds_dwordx4 v[242:243], off
	s_add_i32 m0, s85, 0x2000
	v_lshl_add_u64 v[246:247], s[10:11], 0, v[130:131]
	global_load_lds_dwordx4 v[244:245], off
	v_lshl_add_u64 v[248:249], s[10:11], 0, v[132:133]
	s_nop 0
	s_waitcnt vmcnt(6)
	s_waitcnt lgkmcnt(0)
	s_barrier
; #define PG8_STAGE(bufoff, gbase, voff) do { _Pragma("unroll") for (int _i = 0; _i < 2; ++_i) \
;         __builtin_amdgcn_global_load_lds((const unsigned*)((const char*)(gbase) + (voff)[_i]), (PG8_LAS unsigned*)(lds + (bufoff) + ldsw + _i * 8192), 16, 0, 0); } while (0)
; #define PG8_LDA(dst, b, h) do { _Pragma("unroll") for (int m = 0; m < 4; ++m) _Pragma("unroll") for (int k = 0; k < 2; ++k) dst[m][k] = *(const PG8_LAS bf16x8*)(lds + PG8_SA(b, h) + aoff + m * 2048 + k * 1024); } while (0)
; #define PG8_LDB(dst, b, h) do { _Pragma("unroll") for (int n = 0; n < 2; ++n) _Pragma("unroll") for (int k = 0; k < 2; ++k) dst[n][k] = *(const PG8_LAS bf16x8*)(lds + PG8_SB(b, h) + boff + n * 2048 + k * 1024); } while (0)
; #define PG8_MMA(ai, bj, At, Bt) do { __builtin_amdgcn_s_setprio(1); _Pragma("unroll") for (int m = 0; m < 4; ++m) _Pragma("unroll") for (int n = 0; n < 2; ++n) _Pragma("unroll") for (int k = 0; k < 2; ++k) \
;         acc[ai][bj][m][n] = __builtin_amdgcn_mfma_f32_16x16x32_bf16(Bt[n][k], At[m][k], acc[ai][bj][m][n], 0, 0, 0); __builtin_amdgcn_s_setprio(0); } while (0)
; #define PG8_WAIT_V(n) asm volatile("s_waitcnt vmcnt(" #n ")" ::: "memory")
; #define PG8_WAIT_L(n) asm volatile("s_waitcnt lgkmcnt(" #n ")" ::: "memory")
; #define PG8_BAR __builtin_amdgcn_s_barrier()
; #define PG8_SCHED __builtin_amdgcn_sched_barrier(0)
; template <class Epi, class Sched, bool ALIGN_EPI = false, bool SP2 = false>
; __device__ __forceinline__ void gemm_phase(PG8_LAS unsigned char* lds, const Gemm g, const Sched& S, const Epi& E) {
;     ...
;             PG8_WAIT_V(8); PG8_WAIT_L(0); PG8_BAR; PG8_MMA(1, 0, At, B0); PG8_MMA(1, 1, At, B1); PG8_BAR; PG8_SCHED;
;             PG8_LDB(B0, 1, 0); PG8_LDB(B1, 1, 1); PG8_SCHED; PG8_LDA(At, 1, 0); PG8_STAGE(PG8_SA(0, 1), a2 + hstep, voffA);
;             PG8_WAIT_V(8); PG8_WAIT_L(0); PG8_BAR; PG8_MMA(0, 0, At, B0); PG8_MMA(0, 1, At, B1); PG8_BAR; PG8_SCHED;
	s_setprio 1
	s_waitcnt lgkmcnt(0)
	v_mfma_f32_16x16x32_bf16 v[62:65], v[142:145], v[208:211], v[62:65]
	v_mfma_f32_16x16x32_bf16 v[58:61], v[178:181], v[208:211], v[58:61]
	v_mfma_f32_16x16x32_bf16 v[46:49], v[142:145], v[216:219], v[46:49]
	v_mfma_f32_16x16x32_bf16 v[42:45], v[178:181], v[216:219], v[42:45]
	v_mfma_f32_16x16x32_bf16 v[30:33], v[142:145], v[224:227], v[30:33]
	v_mfma_f32_16x16x32_bf16 v[26:29], v[178:181], v[224:227], v[26:29]
	v_mfma_f32_16x16x32_bf16 v[14:17], v[142:145], v[232:235], v[14:17]
	v_mfma_f32_16x16x32_bf16 v[10:13], v[178:181], v[232:235], v[10:13]
	v_mfma_f32_16x16x32_bf16 v[62:65], v[174:177], v[212:215], v[62:65]
	v_mfma_f32_16x16x32_bf16 v[58:61], v[182:185], v[212:215], v[58:61]
	v_mfma_f32_16x16x32_bf16 v[46:49], v[174:177], v[220:223], v[46:49]
	v_mfma_f32_16x16x32_bf16 v[42:45], v[182:185], v[220:223], v[42:45]
	v_mfma_f32_16x16x32_bf16 v[30:33], v[174:177], v[228:231], v[30:33]
	v_mfma_f32_16x16x32_bf16 v[26:29], v[182:185], v[228:231], v[26:29]
	v_mfma_f32_16x16x32_bf16 v[14:17], v[174:177], v[236:239], v[14:17]
	v_mfma_f32_16x16x32_bf16 v[10:13], v[182:185], v[236:239], v[10:13]
	s_setprio 0
	s_setprio 1
	v_mfma_f32_16x16x32_bf16 v[54:57], v[192:195], v[208:211], v[54:57]
	v_mfma_f32_16x16x32_bf16 v[50:53], v[200:203], v[208:211], v[50:53]
	v_mfma_f32_16x16x32_bf16 v[38:41], v[192:195], v[216:219], v[38:41]
	v_mfma_f32_16x16x32_bf16 v[34:37], v[200:203], v[216:219], v[34:37]
	v_mfma_f32_16x16x32_bf16 v[22:25], v[192:195], v[224:227], v[22:25]
	v_mfma_f32_16x16x32_bf16 v[18:21], v[200:203], v[224:227], v[18:21]
	v_mfma_f32_16x16x32_bf16 v[6:9], v[192:195], v[232:235], v[6:9]
	v_mfma_f32_16x16x32_bf16 v[2:5], v[200:203], v[232:235], v[2:5]
	v_mfma_f32_16x16x32_bf16 v[54:57], v[196:199], v[212:215], v[54:57]
	v_mfma_f32_16x16x32_bf16 v[50:53], v[204:207], v[212:215], v[50:53]
	v_mfma_f32_16x16x32_bf16 v[38:41], v[196:199], v[220:223], v[38:41]
	v_mfma_f32_16x16x32_bf16 v[34:37], v[204:207], v[220:223], v[34:37]
	v_mfma_f32_16x16x32_bf16 v[22:25], v[196:199], v[228:231], v[22:25]
	v_mfma_f32_16x16x32_bf16 v[18:21], v[204:207], v[228:231], v[18:21]
	v_mfma_f32_16x16x32_bf16 v[6:9], v[196:199], v[236:239], v[6:9]
	v_mfma_f32_16x16x32_bf16 v[2:5], v[204:207], v[236:239], v[2:5]
	s_setprio 0
	s_barrier
	s_add_i32 s85, 0, 0x18000
	v_add_u32_e32 v146, s85, v148
	s_add_i32 s86, 0, 0x1c000
	ds_read_b128 v[142:145], v146
	ds_read_b128 v[174:177], v146 offset:1024
	ds_read_b128 v[178:181], v146 offset:2048
	ds_read_b128 v[182:185], v146 offset:3072
	v_add_u32_e32 v146, s86, v148
	ds_read_b128 v[192:195], v146
	ds_read_b128 v[196:199], v146 offset:1024
	ds_read_b128 v[200:203], v146 offset:2048
	ds_read_b128 v[204:207], v146 offset:3072
	s_add_u32 s10, s10, s8
	s_addc_u32 s11, s11, s9
	s_mov_b32 m0, s49
	s_nop 0
	global_load_lds_dwordx4 v[246:247], off
	s_mov_b32 m0, s50
	s_nop 0
	global_load_lds_dwordx4 v[248:249], off
	s_mov_b32 m0, s51
	v_lshl_add_u64 v[250:251], s[10:11], 0, v[130:131]
	ds_read_b128 v[208:211], v173 offset:32768
	ds_read_b128 v[212:215], v173 offset:33792
	ds_read_b128 v[216:219], v173 offset:34816
	ds_read_b128 v[220:223], v173 offset:35840
	ds_read_b128 v[224:227], v173 offset:36864
	ds_read_b128 v[228:231], v173 offset:37888
	ds_read_b128 v[232:235], v173 offset:38912
	ds_read_b128 v[236:239], v173 offset:39936
	global_load_lds_dwordx4 v[250:251], off
	v_lshl_add_u64 v[250:251], s[10:11], 0, v[132:133]
	s_mov_b32 m0, s52
	s_nop 0
	global_load_lds_dwordx4 v[250:251], off
	s_waitcnt vmcnt(8)
	s_waitcnt lgkmcnt(0)
	s_barrier
	s_setprio 1
	s_waitcnt lgkmcnt(0)
	v_mfma_f32_16x16x32_bf16 v[126:129], v[142:145], v[208:211], v[126:129]
	v_mfma_f32_16x16x32_bf16 v[122:125], v[178:181], v[208:211], v[122:125]
	v_mfma_f32_16x16x32_bf16 v[110:113], v[142:145], v[216:219], v[110:113]
	v_mfma_f32_16x16x32_bf16 v[106:109], v[178:181], v[216:219], v[106:109]
	v_mfma_f32_16x16x32_bf16 v[94:97], v[142:145], v[224:227], v[94:97]
	v_mfma_f32_16x16x32_bf16 v[90:93], v[178:181], v[224:227], v[90:93]
	v_mfma_f32_16x16x32_bf16 v[78:81], v[142:145], v[232:235], v[78:81]
	v_mfma_f32_16x16x32_bf16 v[74:77], v[178:181], v[232:235], v[74:77]
	v_mfma_f32_16x16x32_bf16 v[126:129], v[174:177], v[212:215], v[126:129]
	v_mfma_f32_16x16x32_bf16 v[122:125], v[182:185], v[212:215], v[122:125]
	v_mfma_f32_16x16x32_bf16 v[110:113], v[174:177], v[220:223], v[110:113]
	v_mfma_f32_16x16x32_bf16 v[106:109], v[182:185], v[220:223], v[106:109]
	v_mfma_f32_16x16x32_bf16 v[94:97], v[174:177], v[228:231], v[94:97]
	v_mfma_f32_16x16x32_bf16 v[90:93], v[182:185], v[228:231], v[90:93]
	v_mfma_f32_16x16x32_bf16 v[78:81], v[174:177], v[236:239], v[78:81]
	v_mfma_f32_16x16x32_bf16 v[74:77], v[182:185], v[236:239], v[74:77]
	s_setprio 0
	s_setprio 1
	v_mfma_f32_16x16x32_bf16 v[118:121], v[192:195], v[208:211], v[118:121]
	v_mfma_f32_16x16x32_bf16 v[114:117], v[200:203], v[208:211], v[114:117]
	v_mfma_f32_16x16x32_bf16 v[102:105], v[192:195], v[216:219], v[102:105]
	v_mfma_f32_16x16x32_bf16 v[98:101], v[200:203], v[216:219], v[98:101]
	v_mfma_f32_16x16x32_bf16 v[86:89], v[192:195], v[224:227], v[86:89]
	v_mfma_f32_16x16x32_bf16 v[82:85], v[200:203], v[224:227], v[82:85]
	v_mfma_f32_16x16x32_bf16 v[70:73], v[192:195], v[232:235], v[70:73]
	v_mfma_f32_16x16x32_bf16 v[66:69], v[200:203], v[232:235], v[66:69]
	v_mfma_f32_16x16x32_bf16 v[118:121], v[196:199], v[212:215], v[118:121]
	v_mfma_f32_16x16x32_bf16 v[114:117], v[204:207], v[212:215], v[114:117]
	v_mfma_f32_16x16x32_bf16 v[102:105], v[196:199], v[220:223], v[102:105]
	v_mfma_f32_16x16x32_bf16 v[98:101], v[204:207], v[220:223], v[98:101]
	v_mfma_f32_16x16x32_bf16 v[86:89], v[196:199], v[228:231], v[86:89]
	v_mfma_f32_16x16x32_bf16 v[82:85], v[204:207], v[228:231], v[82:85]
	v_mfma_f32_16x16x32_bf16 v[70:73], v[196:199], v[236:239], v[70:73]
	v_mfma_f32_16x16x32_bf16 v[66:69], v[204:207], v[236:239], v[66:69]
	s_setprio 0
	s_barrier
; #define PG8_STAGE(bufoff, gbase, voff) do { _Pragma("unroll") for (int _i = 0; _i < 2; ++_i) \
;         __builtin_amdgcn_global_load_lds((const unsigned*)((const char*)(gbase) + (voff)[_i]), (PG8_LAS unsigned*)(lds + (bufoff) + ldsw + _i * 8192), 16, 0, 0); } while (0)
; #define PG8_LDA(dst, b, h) do { _Pragma("unroll") for (int m = 0; m < 4; ++m) _Pragma("unroll") for (int k = 0; k < 2; ++k) dst[m][k] = *(const PG8_LAS bf16x8*)(lds + PG8_SA(b, h) + aoff + m * 2048 + k * 1024); } while (0)
; #define PG8_MMA(ai, bj, At, Bt) do { __builtin_amdgcn_s_setprio(1); _Pragma("unroll") for (int m = 0; m < 4; ++m) _Pragma("unroll") for (int n = 0; n < 2; ++n) _Pragma("unroll") for (int k = 0; k < 2; ++k) \
;         acc[ai][bj][m][n] = __builtin_amdgcn_mfma_f32_16x16x32_bf16(Bt[n][k], At[m][k], acc[ai][bj][m][n], 0, 0, 0); __builtin_amdgcn_s_setprio(0); } while (0)
; #define PG8_WAIT_V(n) asm volatile("s_waitcnt vmcnt(" #n ")" ::: "memory")
; #define PG8_WAIT_L(n) asm volatile("s_waitcnt lgkmcnt(" #n ")" ::: "memory")
; #define PG8_BAR __builtin_amdgcn_s_barrier()
; #define PG8_SCHED __builtin_amdgcn_sched_barrier(0)
; template <class Epi, class Sched, bool ALIGN_EPI = false, bool SP2 = false>
; __device__ __forceinline__ void gemm_phase(PG8_LAS unsigned char* lds, const Gemm g, const Sched& S, const Epi& E) {
;     ...
;         for (int t = 0; t < nt; t += 2) {
;     ...
;             PG8_LDA(At, 1, 1); PG8_STAGE(PG8_SB(1, 0), b3, voffB); PG8_STAGE(PG8_SB(1, 1), b3 + hstep, voffB); PG8_STAGE(PG8_SA(1, 0), a3, voffA);
;             PG8_WAIT_V(8); PG8_WAIT_L(0); PG8_BAR; PG8_MMA(1, 0, At, B0); PG8_MMA(1, 1, At, B1); PG8_BAR; PG8_SCHED;
	s_add_i32 s10, s85, s4
	v_lshl_add_u64 v[166:167], v[166:167], 0, s[88:89]
	s_mov_b32 m0, s10
	ds_read_b128 v[208:211], v173 offset:49152
	ds_read_b128 v[212:215], v173 offset:50176
	ds_read_b128 v[216:219], v173 offset:51200
	ds_read_b128 v[220:223], v173 offset:52224
	ds_read_b128 v[224:227], v173 offset:53248
	ds_read_b128 v[228:231], v173 offset:54272
	ds_read_b128 v[232:235], v173 offset:55296
	ds_read_b128 v[236:239], v173 offset:56320
	global_load_lds_dwordx4 v[166:167], off
	v_lshl_add_u64 v[166:167], v[240:241], 0, s[88:89]
	s_add_i32 m0, s10, 0x2000
	s_add_i32 s10, s86, s4
	global_load_lds_dwordx4 v[166:167], off
	v_lshl_add_u64 v[166:167], v[242:243], 0, s[88:89]
	s_mov_b32 m0, s10
	s_nop 0
	global_load_lds_dwordx4 v[166:167], off
	v_lshl_add_u64 v[166:167], v[244:245], 0, s[88:89]
	s_add_i32 m0, s10, 0x2000
	s_nop 0
	global_load_lds_dwordx4 v[166:167], off
	v_lshl_add_u64 v[166:167], v[246:247], 0, s[88:89]
	s_mov_b32 m0, s53
	s_nop 0
	global_load_lds_dwordx4 v[166:167], off
	v_lshl_add_u64 v[166:167], v[248:249], 0, s[88:89]
	s_mov_b32 m0, s56
	s_nop 0
	global_load_lds_dwordx4 v[166:167], off
	s_waitcnt vmcnt(8)
	s_waitcnt lgkmcnt(0)
	s_barrier
	s_setprio 1
	s_waitcnt lgkmcnt(0)
	v_mfma_f32_16x16x32_bf16 v[62:65], v[142:145], v[208:211], v[62:65]
	v_mfma_f32_16x16x32_bf16 v[58:61], v[178:181], v[208:211], v[58:61]
	v_mfma_f32_16x16x32_bf16 v[46:49], v[142:145], v[216:219], v[46:49]
	v_mfma_f32_16x16x32_bf16 v[42:45], v[178:181], v[216:219], v[42:45]
	v_mfma_f32_16x16x32_bf16 v[30:33], v[142:145], v[224:227], v[30:33]
	v_mfma_f32_16x16x32_bf16 v[26:29], v[178:181], v[224:227], v[26:29]
	v_mfma_f32_16x16x32_bf16 v[14:17], v[142:145], v[232:235], v[14:17]
	v_mfma_f32_16x16x32_bf16 v[10:13], v[178:181], v[232:235], v[10:13]
	v_mfma_f32_16x16x32_bf16 v[62:65], v[174:177], v[212:215], v[62:65]
	v_mfma_f32_16x16x32_bf16 v[58:61], v[182:185], v[212:215], v[58:61]
	v_mfma_f32_16x16x32_bf16 v[46:49], v[174:177], v[220:223], v[46:49]
	v_mfma_f32_16x16x32_bf16 v[42:45], v[182:185], v[220:223], v[42:45]
	v_mfma_f32_16x16x32_bf16 v[30:33], v[174:177], v[228:231], v[30:33]
	v_mfma_f32_16x16x32_bf16 v[26:29], v[182:185], v[228:231], v[26:29]
	v_mfma_f32_16x16x32_bf16 v[14:17], v[174:177], v[236:239], v[14:17]
	v_mfma_f32_16x16x32_bf16 v[10:13], v[182:185], v[236:239], v[10:13]
	s_setprio 0
	s_setprio 1
	v_mfma_f32_16x16x32_bf16 v[54:57], v[192:195], v[208:211], v[54:57]
	v_mfma_f32_16x16x32_bf16 v[50:53], v[200:203], v[208:211], v[50:53]
	v_mfma_f32_16x16x32_bf16 v[38:41], v[192:195], v[216:219], v[38:41]
	v_mfma_f32_16x16x32_bf16 v[34:37], v[200:203], v[216:219], v[34:37]
	v_mfma_f32_16x16x32_bf16 v[22:25], v[192:195], v[224:227], v[22:25]
	v_mfma_f32_16x16x32_bf16 v[18:21], v[200:203], v[224:227], v[18:21]
	v_mfma_f32_16x16x32_bf16 v[6:9], v[192:195], v[232:235], v[6:9]
	v_mfma_f32_16x16x32_bf16 v[2:5], v[200:203], v[232:235], v[2:5]
	v_mfma_f32_16x16x32_bf16 v[54:57], v[196:199], v[212:215], v[54:57]
	v_mfma_f32_16x16x32_bf16 v[50:53], v[204:207], v[212:215], v[50:53]
	v_mfma_f32_16x16x32_bf16 v[38:41], v[196:199], v[220:223], v[38:41]
	v_mfma_f32_16x16x32_bf16 v[34:37], v[204:207], v[220:223], v[34:37]
	v_mfma_f32_16x16x32_bf16 v[22:25], v[196:199], v[228:231], v[22:25]
	v_mfma_f32_16x16x32_bf16 v[18:21], v[204:207], v[228:231], v[18:21]
	v_mfma_f32_16x16x32_bf16 v[6:9], v[196:199], v[236:239], v[6:9]
	v_mfma_f32_16x16x32_bf16 v[2:5], v[204:207], v[236:239], v[2:5]
	s_setprio 0
	s_barrier
	s_add_u32 s0, s0, 0x100
	s_addc_u32 s1, s1, 0
	s_add_u32 s36, s36, 0x100
	s_addc_u32 s37, s37, 0
	s_cmp_ge_i32 s84, s59
	s_mov_b32 s10, s84
	s_cbranch_scc0 .LBB0_1169
	s_movk_i32 s92, 0x2c00
